# RWKV scaled-state scan: decay rescale group widened from 4 to 8 steps (decay is bounded in (0.545,1) so the 8-step product stays above 0.0078)
# speedup vs baseline: 1.0506x; 1.0012x over previous
; template <int CPL>
; DI void scan_block2(CP p, int layer, int s, int d, int hd, int rowhalf, char* smem) {
;     ...
; #pragma unroll 8
;       for (int jj = 0; jj < nst; ++jj) {
;         float4 na[CPL / 4], ny[CPL / 4], nw[CPL / 4], nb[CPL / 4], nk[CPL / 4];
;         float nvv;
;         {
;           const int jn = jj + 1;
;           const float* o = ob + jn * 392 + cg * CPL;
; #pragma unroll
;           for (int i = 0; i < CPL / 4; ++i) {
;             na[i] = *(const float4*)(o + 4 * i); ny[i] = *(const float4*)(o + 64 + 4 * i); nw[i] = *(const float4*)(o + 128 + 4 * i);
;             nb[i] = *(const float4*)(o + 192 + 4 * i); nk[i] = *(const float4*)(o + 256 + 4 * i);
;           }
;           nvv = ob[jn * 392 + 320 + row];
;         }
;         f2 A[NV], Y[NV], W[NV], B[NV], K[NV];
; #pragma unroll
;         for (int i = 0; i < CPL / 4; ++i) {
;           A[2 * i] = mk2(ca[i].x, ca[i].y); A[2 * i + 1] = mk2(ca[i].z, ca[i].w);
;           Y[2 * i] = mk2(cy[i].x, cy[i].y); Y[2 * i + 1] = mk2(cy[i].z, cy[i].w);
;           W[2 * i] = mk2(cw[i].x, cw[i].y); W[2 * i + 1] = mk2(cw[i].z, cw[i].w);
;           B[2 * i] = mk2(cb[i].x, cb[i].y); B[2 * i + 1] = mk2(cb[i].z, cb[i].w);
;           K[2 * i] = mk2(ck[i].x, ck[i].y); K[2 * i + 1] = mk2(ck[i].z, ck[i].w);
;         }
;         const float vv = cvv;
;         f2 pa0 = S[0] * A[0], pa1 = S[1] * A[1];
; #pragma unroll
;         for (int i = 2; i < NV; i += 2) { pa0 = S[i] * A[i] + pa0; pa1 = S[i + 1] * A[i + 1] + pa1; }
;         pa0 = pa0 + pa1;
;         float da = pa0.x + pa0.y;
;         const f2 vvv = mk2(vv, vv);
;         f2 SW[NV];
; #pragma unroll
;         for (int i = 0; i < NV; ++i) SW[i] = S[i] * W[i] + vvv * K[i];
;         da += __int_as_float(__builtin_amdgcn_update_dpp(0, __float_as_int(da), 0xB1, 0xf, 0xf, false));
;         da += __int_as_float(__builtin_amdgcn_update_dpp(0, __float_as_int(da), 0x4E, 0xf, 0xf, false));
;         if (CPL == 8) da += __int_as_float(__builtin_amdgcn_update_dpp(0, __float_as_int(da), 0x141, 0xf, 0xf, false));
;         const f2 dav = mk2(da, da);
; #pragma unroll
;         for (int i = 0; i < NV; ++i) S[i] = dav * B[i] + SW[i];
;         f2 py0 = S[0] * Y[0], py1 = S[1] * Y[1];
; #pragma unroll
;         for (int i = 2; i < NV; i += 2) { py0 = S[i] * Y[i] + py0; py1 = S[i + 1] * Y[i + 1] + py1; }
;         py0 = py0 + py1;
;         float yv = py0.x + py0.y;
.Lsc8_chunk:
	s_and_b32 s17, s10, 1
	s_mul_i32 s15, s17, 0xc400
	v_add_u32_e32 v199, s15, v202
	v_add_u32_e32 v200, s15, v205
	s_lshl_b32 s15, s17, 13
	v_add_u32_e32 v0, s15, v204
	v_cndmask_b32_e32 v201, v206, v0, vcc
	ds_read_b128 v[2:5], v199 offset:0
	ds_read_b128 v[6:9], v199 offset:16
	ds_read_b128 v[34:37], v199 offset:1024
	ds_read_b128 v[38:41], v199 offset:1040
	ds_read_b32 v42, v200 offset:0
	ds_read_b128 v[26:29], v199 offset:768
	ds_read_b128 v[30:33], v199 offset:784
	ds_read_b128 v[10:13], v199 offset:256
	ds_read_b128 v[14:17], v199 offset:272
	s_waitcnt lgkmcnt(0)
	v_pk_mul_f32 v[88:89], v[2:3], v[170:171]
	ds_read_b128 v[44:47], v199 offset:1568
	v_pk_fma_f32 v[88:89], v[4:5], v[172:173], v[88:89]
	ds_read_b128 v[48:51], v199 offset:1584
	v_pk_fma_f32 v[88:89], v[6:7], v[174:175], v[88:89]
	ds_read_b128 v[76:79], v199 offset:2592
	v_pk_fma_f32 v[88:89], v[8:9], v[176:177], v[88:89]
	ds_read_b128 v[80:83], v199 offset:2608
	v_add_f32_e32 v86, v88, v89
	ds_read_b32 v84, v200 offset:1568
	v_pk_fma_f32 v[162:163], v[34:35], v[42:43], v[170:171] op_sel_hi:[1,0,1]
	v_add_f32_dpp v86, v86, v86 quad_perm:[1,0,3,2] row_mask:0xf bank_mask:0xf bound_ctrl:1
	v_pk_fma_f32 v[164:165], v[36:37], v[42:43], v[172:173] op_sel_hi:[1,0,1]
	ds_read_b128 v[68:71], v199 offset:2336
	v_add_f32_dpp v86, v86, v86 quad_perm:[2,3,0,1] row_mask:0xf bank_mask:0xf bound_ctrl:1
	s_nop 0
	ds_read_b128 v[72:75], v199 offset:2352
	v_add_f32_dpp v86, v86, v86 row_half_mirror row_mask:0xf bank_mask:0xf bound_ctrl:1
	v_pk_fma_f32 v[166:167], v[38:39], v[42:43], v[174:175] op_sel_hi:[1,0,1]
	v_pk_fma_f32 v[168:169], v[40:41], v[42:43], v[176:177] op_sel_hi:[1,0,1]
	v_pk_fma_f32 v[94:95], v[26:27], v[86:87], v[162:163] op_sel_hi:[1,0,1]
	v_pk_fma_f32 v[96:97], v[28:29], v[86:87], v[164:165] op_sel_hi:[1,0,1]
	v_pk_fma_f32 v[98:99], v[30:31], v[86:87], v[166:167] op_sel_hi:[1,0,1]
	v_pk_fma_f32 v[100:101], v[32:33], v[86:87], v[168:169] op_sel_hi:[1,0,1]
	ds_read_b128 v[52:55], v199 offset:1824
	ds_read_b128 v[56:59], v199 offset:1840
	s_waitcnt lgkmcnt(4)
	v_pk_mul_f32 v[88:89], v[44:45], v[94:95]
	ds_read_b128 v[2:5], v199 offset:3136
	v_pk_fma_f32 v[88:89], v[46:47], v[96:97], v[88:89]
	ds_read_b128 v[6:9], v199 offset:3152
	v_pk_fma_f32 v[88:89], v[48:49], v[98:99], v[88:89]
	ds_read_b128 v[34:37], v199 offset:4160
	v_pk_fma_f32 v[88:89], v[50:51], v[100:101], v[88:89]
	ds_read_b128 v[38:41], v199 offset:4176
	v_add_f32_e32 v86, v88, v89
	ds_read_b32 v42, v200 offset:3136
	v_pk_fma_f32 v[162:163], v[76:77], v[84:85], v[94:95] op_sel_hi:[1,0,1]
	v_add_f32_dpp v86, v86, v86 quad_perm:[1,0,3,2] row_mask:0xf bank_mask:0xf bound_ctrl:1
	v_pk_fma_f32 v[164:165], v[78:79], v[84:85], v[96:97] op_sel_hi:[1,0,1]
	ds_read_b128 v[26:29], v199 offset:3904
	v_add_f32_dpp v86, v86, v86 quad_perm:[2,3,0,1] row_mask:0xf bank_mask:0xf bound_ctrl:1
	s_nop 0
	ds_read_b128 v[30:33], v199 offset:3920
	v_add_f32_dpp v86, v86, v86 row_half_mirror row_mask:0xf bank_mask:0xf bound_ctrl:1
	v_pk_fma_f32 v[166:167], v[80:81], v[84:85], v[98:99] op_sel_hi:[1,0,1]
	v_pk_fma_f32 v[168:169], v[82:83], v[84:85], v[100:101] op_sel_hi:[1,0,1]
	s_waitcnt lgkmcnt(9)
	v_pk_fma_f32 v[170:171], v[68:69], v[86:87], v[162:163] op_sel_hi:[1,0,1]
	v_pk_fma_f32 v[172:173], v[70:71], v[86:87], v[164:165] op_sel_hi:[1,0,1]
	v_pk_fma_f32 v[174:175], v[72:73], v[86:87], v[166:167] op_sel_hi:[1,0,1]
	v_pk_fma_f32 v[176:177], v[74:75], v[86:87], v[168:169] op_sel_hi:[1,0,1]
	v_pk_mul_f32 v[90:91], v[10:11], v[94:95]
	v_pk_fma_f32 v[90:91], v[12:13], v[96:97], v[90:91]
	v_pk_fma_f32 v[90:91], v[14:15], v[98:99], v[90:91]
	v_pk_fma_f32 v[90:91], v[16:17], v[100:101], v[90:91]
	ds_read_b128 v[10:13], v199 offset:3392
	v_add_f32_e32 v92, v90, v91
	ds_read_b128 v[14:17], v199 offset:3408
	s_waitcnt lgkmcnt(4)
	v_pk_mul_f32 v[88:89], v[2:3], v[170:171]
	ds_read_b128 v[44:47], v199 offset:4704
	v_pk_fma_f32 v[88:89], v[4:5], v[172:173], v[88:89]
	ds_read_b128 v[48:51], v199 offset:4720
	v_pk_fma_f32 v[88:89], v[6:7], v[174:175], v[88:89]
	ds_read_b128 v[76:79], v199 offset:5728
	v_pk_fma_f32 v[88:89], v[8:9], v[176:177], v[88:89]
	ds_read_b128 v[80:83], v199 offset:5744
	v_add_f32_e32 v86, v88, v89
	ds_read_b32 v84, v200 offset:4704
	v_pk_fma_f32 v[162:163], v[34:35], v[42:43], v[170:171] op_sel_hi:[1,0,1]
	v_add_f32_dpp v86, v86, v86 quad_perm:[1,0,3,2] row_mask:0xf bank_mask:0xf bound_ctrl:1
	v_add_f32_dpp v92, v92, v92 quad_perm:[1,0,3,2] row_mask:0xf bank_mask:0xf bound_ctrl:1
	ds_read_b128 v[68:71], v199 offset:5472
	v_add_f32_dpp v86, v86, v86 quad_perm:[2,3,0,1] row_mask:0xf bank_mask:0xf bound_ctrl:1
	v_add_f32_dpp v92, v92, v92 quad_perm:[2,3,0,1] row_mask:0xf bank_mask:0xf bound_ctrl:1
	ds_read_b128 v[72:75], v199 offset:5488
	v_add_f32_dpp v86, v86, v86 row_half_mirror row_mask:0xf bank_mask:0xf bound_ctrl:1
	v_add_f32_dpp v92, v92, v92 row_half_mirror row_mask:0xf bank_mask:0xf bound_ctrl:1
	v_pk_fma_f32 v[164:165], v[36:37], v[42:43], v[172:173] op_sel_hi:[1,0,1]
	v_pk_fma_f32 v[166:167], v[38:39], v[42:43], v[174:175] op_sel_hi:[1,0,1]
	v_pk_fma_f32 v[168:169], v[40:41], v[42:43], v[176:177] op_sel_hi:[1,0,1]
	s_waitcnt lgkmcnt(9)
	v_pk_fma_f32 v[94:95], v[26:27], v[86:87], v[162:163] op_sel_hi:[1,0,1]
	v_pk_fma_f32 v[96:97], v[28:29], v[86:87], v[164:165] op_sel_hi:[1,0,1]
	v_pk_fma_f32 v[98:99], v[30:31], v[86:87], v[166:167] op_sel_hi:[1,0,1]
	v_pk_fma_f32 v[100:101], v[32:33], v[86:87], v[168:169] op_sel_hi:[1,0,1]
	ds_write_b32 v201, v92 offset:0
	v_pk_mul_f32 v[90:91], v[52:53], v[170:171]
	v_pk_fma_f32 v[90:91], v[54:55], v[172:173], v[90:91]
	v_pk_fma_f32 v[90:91], v[56:57], v[174:175], v[90:91]
	v_pk_fma_f32 v[90:91], v[58:59], v[176:177], v[90:91]
	ds_read_b128 v[52:55], v199 offset:4960
	v_add_f32_e32 v93, v90, v91
	ds_read_b128 v[56:59], v199 offset:4976
	s_waitcnt lgkmcnt(5)
; template <int CPL>
; DI void scan_block2(CP p, int layer, int s, int d, int hd, int rowhalf, char* smem) {
;     ...
; #pragma unroll 8
;       for (int jj = 0; jj < nst; ++jj) {
;         float4 na[CPL / 4], ny[CPL / 4], nw[CPL / 4], nb[CPL / 4], nk[CPL / 4];
;         float nvv;
;         {
;           const int jn = jj + 1;
;           const float* o = ob + jn * 392 + cg * CPL;
; #pragma unroll
;           for (int i = 0; i < CPL / 4; ++i) {
;             na[i] = *(const float4*)(o + 4 * i); ny[i] = *(const float4*)(o + 64 + 4 * i); nw[i] = *(const float4*)(o + 128 + 4 * i);
;             nb[i] = *(const float4*)(o + 192 + 4 * i); nk[i] = *(const float4*)(o + 256 + 4 * i);
;           }
;           nvv = ob[jn * 392 + 320 + row];
;         }
;         f2 A[NV], Y[NV], W[NV], B[NV], K[NV];
; #pragma unroll
;         for (int i = 0; i < CPL / 4; ++i) {
;           A[2 * i] = mk2(ca[i].x, ca[i].y); A[2 * i + 1] = mk2(ca[i].z, ca[i].w);
;           Y[2 * i] = mk2(cy[i].x, cy[i].y); Y[2 * i + 1] = mk2(cy[i].z, cy[i].w);
;           W[2 * i] = mk2(cw[i].x, cw[i].y); W[2 * i + 1] = mk2(cw[i].z, cw[i].w);
;           B[2 * i] = mk2(cb[i].x, cb[i].y); B[2 * i + 1] = mk2(cb[i].z, cb[i].w);
;           K[2 * i] = mk2(ck[i].x, ck[i].y); K[2 * i + 1] = mk2(ck[i].z, ck[i].w);
;         }
;         const float vv = cvv;
;         f2 pa0 = S[0] * A[0], pa1 = S[1] * A[1];
; #pragma unroll
;         for (int i = 2; i < NV; i += 2) { pa0 = S[i] * A[i] + pa0; pa1 = S[i + 1] * A[i + 1] + pa1; }
;         pa0 = pa0 + pa1;
;         float da = pa0.x + pa0.y;
;         const f2 vvv = mk2(vv, vv);
;         f2 SW[NV];
; #pragma unroll
;         for (int i = 0; i < NV; ++i) SW[i] = S[i] * W[i] + vvv * K[i];
;         da += __int_as_float(__builtin_amdgcn_update_dpp(0, __float_as_int(da), 0xB1, 0xf, 0xf, false));
;         da += __int_as_float(__builtin_amdgcn_update_dpp(0, __float_as_int(da), 0x4E, 0xf, 0xf, false));
;         if (CPL == 8) da += __int_as_float(__builtin_amdgcn_update_dpp(0, __float_as_int(da), 0x141, 0xf, 0xf, false));
;         const f2 dav = mk2(da, da);
; #pragma unroll
;         for (int i = 0; i < NV; ++i) S[i] = dav * B[i] + SW[i];
;         f2 py0 = S[0] * Y[0], py1 = S[1] * Y[1];
; #pragma unroll
;         for (int i = 2; i < NV; i += 2) { py0 = S[i] * Y[i] + py0; py1 = S[i + 1] * Y[i + 1] + py1; }
;         py0 = py0 + py1;
;         float yv = py0.x + py0.y;
	v_pk_mul_f32 v[88:89], v[44:45], v[94:95]
	ds_read_b128 v[2:5], v199 offset:6272
	v_pk_fma_f32 v[88:89], v[46:47], v[96:97], v[88:89]
	ds_read_b128 v[6:9], v199 offset:6288
	v_pk_fma_f32 v[88:89], v[48:49], v[98:99], v[88:89]
	ds_read_b128 v[34:37], v199 offset:7296
	v_pk_fma_f32 v[88:89], v[50:51], v[100:101], v[88:89]
	ds_read_b128 v[38:41], v199 offset:7312
	v_add_f32_e32 v86, v88, v89
	ds_read_b32 v42, v200 offset:6272
	v_pk_fma_f32 v[162:163], v[76:77], v[84:85], v[94:95] op_sel_hi:[1,0,1]
	v_add_f32_dpp v86, v86, v86 quad_perm:[1,0,3,2] row_mask:0xf bank_mask:0xf bound_ctrl:1
	v_add_f32_dpp v93, v93, v93 quad_perm:[1,0,3,2] row_mask:0xf bank_mask:0xf bound_ctrl:1
	ds_read_b128 v[26:29], v199 offset:7040
	v_add_f32_dpp v86, v86, v86 quad_perm:[2,3,0,1] row_mask:0xf bank_mask:0xf bound_ctrl:1
	v_add_f32_dpp v93, v93, v93 quad_perm:[2,3,0,1] row_mask:0xf bank_mask:0xf bound_ctrl:1
	ds_read_b128 v[30:33], v199 offset:7056
	v_add_f32_dpp v86, v86, v86 row_half_mirror row_mask:0xf bank_mask:0xf bound_ctrl:1
	v_add_f32_dpp v93, v93, v93 row_half_mirror row_mask:0xf bank_mask:0xf bound_ctrl:1
	v_pk_fma_f32 v[164:165], v[78:79], v[84:85], v[96:97] op_sel_hi:[1,0,1]
	v_pk_fma_f32 v[166:167], v[80:81], v[84:85], v[98:99] op_sel_hi:[1,0,1]
	v_pk_fma_f32 v[168:169], v[82:83], v[84:85], v[100:101] op_sel_hi:[1,0,1]
	s_waitcnt lgkmcnt(10)
	v_pk_fma_f32 v[170:171], v[68:69], v[86:87], v[162:163] op_sel_hi:[1,0,1]
	v_pk_fma_f32 v[172:173], v[70:71], v[86:87], v[164:165] op_sel_hi:[1,0,1]
	v_pk_fma_f32 v[174:175], v[72:73], v[86:87], v[166:167] op_sel_hi:[1,0,1]
	v_pk_fma_f32 v[176:177], v[74:75], v[86:87], v[168:169] op_sel_hi:[1,0,1]
	ds_write_b32 v201, v93 offset:256
	v_pk_mul_f32 v[90:91], v[10:11], v[94:95]
	v_pk_fma_f32 v[90:91], v[12:13], v[96:97], v[90:91]
	v_pk_fma_f32 v[90:91], v[14:15], v[98:99], v[90:91]
	v_pk_fma_f32 v[90:91], v[16:17], v[100:101], v[90:91]
	ds_read_b128 v[10:13], v199 offset:6528
	v_add_f32_e32 v92, v90, v91
	ds_read_b128 v[14:17], v199 offset:6544
	s_waitcnt lgkmcnt(5)
	v_pk_mul_f32 v[88:89], v[2:3], v[170:171]
	ds_read_b128 v[44:47], v199 offset:7840
	v_pk_fma_f32 v[88:89], v[4:5], v[172:173], v[88:89]
	ds_read_b128 v[48:51], v199 offset:7856
	v_pk_fma_f32 v[88:89], v[6:7], v[174:175], v[88:89]
	ds_read_b128 v[76:79], v199 offset:8864
	v_pk_fma_f32 v[88:89], v[8:9], v[176:177], v[88:89]
	ds_read_b128 v[80:83], v199 offset:8880
	v_add_f32_e32 v86, v88, v89
	ds_read_b32 v84, v200 offset:7840
	v_pk_fma_f32 v[162:163], v[34:35], v[42:43], v[170:171] op_sel_hi:[1,0,1]
	v_add_f32_dpp v86, v86, v86 quad_perm:[1,0,3,2] row_mask:0xf bank_mask:0xf bound_ctrl:1
	v_add_f32_dpp v92, v92, v92 quad_perm:[1,0,3,2] row_mask:0xf bank_mask:0xf bound_ctrl:1
	ds_read_b128 v[68:71], v199 offset:8608
	v_add_f32_dpp v86, v86, v86 quad_perm:[2,3,0,1] row_mask:0xf bank_mask:0xf bound_ctrl:1
	v_add_f32_dpp v92, v92, v92 quad_perm:[2,3,0,1] row_mask:0xf bank_mask:0xf bound_ctrl:1
	ds_read_b128 v[72:75], v199 offset:8624
	v_add_f32_dpp v86, v86, v86 row_half_mirror row_mask:0xf bank_mask:0xf bound_ctrl:1
	v_add_f32_dpp v92, v92, v92 row_half_mirror row_mask:0xf bank_mask:0xf bound_ctrl:1
	v_pk_fma_f32 v[164:165], v[36:37], v[42:43], v[172:173] op_sel_hi:[1,0,1]
	v_pk_fma_f32 v[166:167], v[38:39], v[42:43], v[174:175] op_sel_hi:[1,0,1]
	v_pk_fma_f32 v[168:169], v[40:41], v[42:43], v[176:177] op_sel_hi:[1,0,1]
	s_waitcnt lgkmcnt(10)
	v_pk_fma_f32 v[94:95], v[26:27], v[86:87], v[162:163] op_sel_hi:[1,0,1]
	v_pk_fma_f32 v[96:97], v[28:29], v[86:87], v[164:165] op_sel_hi:[1,0,1]
	v_pk_fma_f32 v[98:99], v[30:31], v[86:87], v[166:167] op_sel_hi:[1,0,1]
	v_pk_fma_f32 v[100:101], v[32:33], v[86:87], v[168:169] op_sel_hi:[1,0,1]
	ds_write_b32 v201, v92 offset:512
	v_pk_mul_f32 v[90:91], v[52:53], v[170:171]
	v_pk_fma_f32 v[90:91], v[54:55], v[172:173], v[90:91]
	v_pk_fma_f32 v[90:91], v[56:57], v[174:175], v[90:91]
	v_pk_fma_f32 v[90:91], v[58:59], v[176:177], v[90:91]
	ds_read_b128 v[52:55], v199 offset:8096
	v_add_f32_e32 v93, v90, v91
	ds_read_b128 v[56:59], v199 offset:8112
	s_waitcnt lgkmcnt(5)
	v_pk_mul_f32 v[88:89], v[44:45], v[94:95]
	ds_read_b128 v[2:5], v199 offset:9408
	v_pk_fma_f32 v[88:89], v[46:47], v[96:97], v[88:89]
	ds_read_b128 v[6:9], v199 offset:9424
	v_pk_fma_f32 v[88:89], v[48:49], v[98:99], v[88:89]
	ds_read_b128 v[34:37], v199 offset:10432
	v_pk_fma_f32 v[88:89], v[50:51], v[100:101], v[88:89]
	ds_read_b128 v[38:41], v199 offset:10448
	v_add_f32_e32 v86, v88, v89
	ds_read_b32 v42, v200 offset:9408
	v_pk_fma_f32 v[162:163], v[76:77], v[84:85], v[94:95] op_sel_hi:[1,0,1]
	v_add_f32_dpp v86, v86, v86 quad_perm:[1,0,3,2] row_mask:0xf bank_mask:0xf bound_ctrl:1
	v_add_f32_dpp v93, v93, v93 quad_perm:[1,0,3,2] row_mask:0xf bank_mask:0xf bound_ctrl:1
	ds_read_b128 v[26:29], v199 offset:10176
	v_add_f32_dpp v86, v86, v86 quad_perm:[2,3,0,1] row_mask:0xf bank_mask:0xf bound_ctrl:1
	v_add_f32_dpp v93, v93, v93 quad_perm:[2,3,0,1] row_mask:0xf bank_mask:0xf bound_ctrl:1
	ds_read_b128 v[30:33], v199 offset:10192
	v_add_f32_dpp v86, v86, v86 row_half_mirror row_mask:0xf bank_mask:0xf bound_ctrl:1
	v_add_f32_dpp v93, v93, v93 row_half_mirror row_mask:0xf bank_mask:0xf bound_ctrl:1
	v_pk_fma_f32 v[164:165], v[78:79], v[84:85], v[96:97] op_sel_hi:[1,0,1]
	v_pk_fma_f32 v[166:167], v[80:81], v[84:85], v[98:99] op_sel_hi:[1,0,1]
	v_pk_fma_f32 v[168:169], v[82:83], v[84:85], v[100:101] op_sel_hi:[1,0,1]
	s_waitcnt lgkmcnt(10)
; template <int CPL>
; DI void scan_block2(CP p, int layer, int s, int d, int hd, int rowhalf, char* smem) {
;     ...
; #pragma unroll 8
;       for (int jj = 0; jj < nst; ++jj) {
;         float4 na[CPL / 4], ny[CPL / 4], nw[CPL / 4], nb[CPL / 4], nk[CPL / 4];
;         float nvv;
;         {
;           const int jn = jj + 1;
;           const float* o = ob + jn * 392 + cg * CPL;
; #pragma unroll
;           for (int i = 0; i < CPL / 4; ++i) {
;             na[i] = *(const float4*)(o + 4 * i); ny[i] = *(const float4*)(o + 64 + 4 * i); nw[i] = *(const float4*)(o + 128 + 4 * i);
;             nb[i] = *(const float4*)(o + 192 + 4 * i); nk[i] = *(const float4*)(o + 256 + 4 * i);
;           }
;           nvv = ob[jn * 392 + 320 + row];
;         }
;         f2 A[NV], Y[NV], W[NV], B[NV], K[NV];
; #pragma unroll
;         for (int i = 0; i < CPL / 4; ++i) {
;           A[2 * i] = mk2(ca[i].x, ca[i].y); A[2 * i + 1] = mk2(ca[i].z, ca[i].w);
;           Y[2 * i] = mk2(cy[i].x, cy[i].y); Y[2 * i + 1] = mk2(cy[i].z, cy[i].w);
;           W[2 * i] = mk2(cw[i].x, cw[i].y); W[2 * i + 1] = mk2(cw[i].z, cw[i].w);
;           B[2 * i] = mk2(cb[i].x, cb[i].y); B[2 * i + 1] = mk2(cb[i].z, cb[i].w);
;           K[2 * i] = mk2(ck[i].x, ck[i].y); K[2 * i + 1] = mk2(ck[i].z, ck[i].w);
;         }
;         const float vv = cvv;
;         f2 pa0 = S[0] * A[0], pa1 = S[1] * A[1];
; #pragma unroll
;         for (int i = 2; i < NV; i += 2) { pa0 = S[i] * A[i] + pa0; pa1 = S[i + 1] * A[i + 1] + pa1; }
;         pa0 = pa0 + pa1;
;         float da = pa0.x + pa0.y;
;         const f2 vvv = mk2(vv, vv);
;         f2 SW[NV];
; #pragma unroll
;         for (int i = 0; i < NV; ++i) SW[i] = S[i] * W[i] + vvv * K[i];
;         da += __int_as_float(__builtin_amdgcn_update_dpp(0, __float_as_int(da), 0xB1, 0xf, 0xf, false));
;         da += __int_as_float(__builtin_amdgcn_update_dpp(0, __float_as_int(da), 0x4E, 0xf, 0xf, false));
;         if (CPL == 8) da += __int_as_float(__builtin_amdgcn_update_dpp(0, __float_as_int(da), 0x141, 0xf, 0xf, false));
;         const f2 dav = mk2(da, da);
; #pragma unroll
;         for (int i = 0; i < NV; ++i) S[i] = dav * B[i] + SW[i];
;         f2 py0 = S[0] * Y[0], py1 = S[1] * Y[1];
; #pragma unroll
;         for (int i = 2; i < NV; i += 2) { py0 = S[i] * Y[i] + py0; py1 = S[i + 1] * Y[i + 1] + py1; }
;         py0 = py0 + py1;
;         float yv = py0.x + py0.y;
	v_pk_fma_f32 v[170:171], v[68:69], v[86:87], v[162:163] op_sel_hi:[1,0,1]
	v_pk_fma_f32 v[172:173], v[70:71], v[86:87], v[164:165] op_sel_hi:[1,0,1]
	v_pk_fma_f32 v[174:175], v[72:73], v[86:87], v[166:167] op_sel_hi:[1,0,1]
	v_pk_fma_f32 v[176:177], v[74:75], v[86:87], v[168:169] op_sel_hi:[1,0,1]
	ds_write_b32 v201, v93 offset:768
	v_pk_mul_f32 v[90:91], v[10:11], v[94:95]
	v_pk_fma_f32 v[90:91], v[12:13], v[96:97], v[90:91]
	v_pk_fma_f32 v[90:91], v[14:15], v[98:99], v[90:91]
	v_pk_fma_f32 v[90:91], v[16:17], v[100:101], v[90:91]
	ds_read_b128 v[10:13], v199 offset:9664
	v_add_f32_e32 v92, v90, v91
	ds_read_b128 v[14:17], v199 offset:9680
	s_waitcnt lgkmcnt(5)
	v_pk_mul_f32 v[88:89], v[2:3], v[170:171]
	ds_read_b128 v[44:47], v199 offset:10976
	v_pk_fma_f32 v[88:89], v[4:5], v[172:173], v[88:89]
	ds_read_b128 v[48:51], v199 offset:10992
	v_pk_fma_f32 v[88:89], v[6:7], v[174:175], v[88:89]
	ds_read_b128 v[76:79], v199 offset:12000
	v_pk_fma_f32 v[88:89], v[8:9], v[176:177], v[88:89]
	ds_read_b128 v[80:83], v199 offset:12016
	v_add_f32_e32 v86, v88, v89
	ds_read_b32 v84, v200 offset:10976
	v_pk_fma_f32 v[162:163], v[34:35], v[42:43], v[170:171] op_sel_hi:[1,0,1]
	v_add_f32_dpp v86, v86, v86 quad_perm:[1,0,3,2] row_mask:0xf bank_mask:0xf bound_ctrl:1
	v_add_f32_dpp v92, v92, v92 quad_perm:[1,0,3,2] row_mask:0xf bank_mask:0xf bound_ctrl:1
	ds_read_b128 v[68:71], v199 offset:11744
	v_add_f32_dpp v86, v86, v86 quad_perm:[2,3,0,1] row_mask:0xf bank_mask:0xf bound_ctrl:1
	v_add_f32_dpp v92, v92, v92 quad_perm:[2,3,0,1] row_mask:0xf bank_mask:0xf bound_ctrl:1
	ds_read_b128 v[72:75], v199 offset:11760
	v_add_f32_dpp v86, v86, v86 row_half_mirror row_mask:0xf bank_mask:0xf bound_ctrl:1
	v_add_f32_dpp v92, v92, v92 row_half_mirror row_mask:0xf bank_mask:0xf bound_ctrl:1
	v_pk_fma_f32 v[164:165], v[36:37], v[42:43], v[172:173] op_sel_hi:[1,0,1]
	v_pk_fma_f32 v[166:167], v[38:39], v[42:43], v[174:175] op_sel_hi:[1,0,1]
	v_pk_fma_f32 v[168:169], v[40:41], v[42:43], v[176:177] op_sel_hi:[1,0,1]
	s_waitcnt lgkmcnt(10)
	v_pk_fma_f32 v[94:95], v[26:27], v[86:87], v[162:163] op_sel_hi:[1,0,1]
	v_pk_fma_f32 v[96:97], v[28:29], v[86:87], v[164:165] op_sel_hi:[1,0,1]
	v_pk_fma_f32 v[98:99], v[30:31], v[86:87], v[166:167] op_sel_hi:[1,0,1]
	v_pk_fma_f32 v[100:101], v[32:33], v[86:87], v[168:169] op_sel_hi:[1,0,1]
	ds_write_b32 v201, v92 offset:1024
	v_pk_mul_f32 v[90:91], v[52:53], v[170:171]
	v_pk_fma_f32 v[90:91], v[54:55], v[172:173], v[90:91]
	v_pk_fma_f32 v[90:91], v[56:57], v[174:175], v[90:91]
	v_pk_fma_f32 v[90:91], v[58:59], v[176:177], v[90:91]
	ds_read_b128 v[52:55], v199 offset:11232
	v_add_f32_e32 v93, v90, v91
	ds_read_b128 v[56:59], v199 offset:11248
	s_waitcnt lgkmcnt(5)
	v_pk_mul_f32 v[88:89], v[44:45], v[94:95]
	ds_read_b128 v[2:5], v199 offset:12544
	v_pk_fma_f32 v[88:89], v[46:47], v[96:97], v[88:89]
	ds_read_b128 v[6:9], v199 offset:12560
	v_pk_fma_f32 v[88:89], v[48:49], v[98:99], v[88:89]
	ds_read_b128 v[34:37], v199 offset:13568
	v_pk_fma_f32 v[88:89], v[50:51], v[100:101], v[88:89]
	ds_read_b128 v[38:41], v199 offset:13584
	v_add_f32_e32 v86, v88, v89
	ds_read_b32 v42, v200 offset:12544
	ds_read_b128 v[18:21], v199 offset:11488
	ds_read_b128 v[22:25], v199 offset:11504
	v_add_f32_dpp v86, v86, v86 quad_perm:[1,0,3,2] row_mask:0xf bank_mask:0xf bound_ctrl:1
	v_add_f32_dpp v93, v93, v93 quad_perm:[1,0,3,2] row_mask:0xf bank_mask:0xf bound_ctrl:1
	ds_read_b128 v[26:29], v199 offset:13312
	v_add_f32_dpp v86, v86, v86 quad_perm:[2,3,0,1] row_mask:0xf bank_mask:0xf bound_ctrl:1
	v_add_f32_dpp v93, v93, v93 quad_perm:[2,3,0,1] row_mask:0xf bank_mask:0xf bound_ctrl:1
	ds_read_b128 v[30:33], v199 offset:13328
	v_add_f32_dpp v86, v86, v86 row_half_mirror row_mask:0xf bank_mask:0xf bound_ctrl:1
	v_add_f32_dpp v93, v93, v93 row_half_mirror row_mask:0xf bank_mask:0xf bound_ctrl:1
	v_pk_fma_f32 v[162:163], v[76:77], v[84:85], v[94:95] op_sel_hi:[1,0,1]
	v_pk_fma_f32 v[164:165], v[78:79], v[84:85], v[96:97] op_sel_hi:[1,0,1]
	v_pk_fma_f32 v[166:167], v[80:81], v[84:85], v[98:99] op_sel_hi:[1,0,1]
	v_pk_fma_f32 v[168:169], v[82:83], v[84:85], v[100:101] op_sel_hi:[1,0,1]
	s_waitcnt lgkmcnt(12)
	v_pk_fma_f32 v[170:171], v[68:69], v[86:87], v[162:163] op_sel_hi:[1,0,1]
	v_pk_fma_f32 v[172:173], v[70:71], v[86:87], v[164:165] op_sel_hi:[1,0,1]
	v_pk_fma_f32 v[174:175], v[72:73], v[86:87], v[166:167] op_sel_hi:[1,0,1]
	v_pk_fma_f32 v[176:177], v[74:75], v[86:87], v[168:169] op_sel_hi:[1,0,1]
	s_waitcnt lgkmcnt(2)
	v_pk_mul_f32 v[170:171], v[170:171], v[18:19]
	v_pk_mul_f32 v[172:173], v[172:173], v[20:21]
	v_pk_mul_f32 v[174:175], v[174:175], v[22:23]
	v_pk_mul_f32 v[176:177], v[176:177], v[24:25]
	ds_write_b32 v201, v93 offset:1280
	v_pk_mul_f32 v[90:91], v[10:11], v[94:95]
	v_pk_fma_f32 v[90:91], v[12:13], v[96:97], v[90:91]
	v_pk_fma_f32 v[90:91], v[14:15], v[98:99], v[90:91]
	v_pk_fma_f32 v[90:91], v[16:17], v[100:101], v[90:91]
	ds_read_b128 v[10:13], v199 offset:12800
	v_add_f32_e32 v92, v90, v91
	ds_read_b128 v[14:17], v199 offset:12816
	s_waitcnt lgkmcnt(7)
; template <int CPL>
; DI void scan_block2(CP p, int layer, int s, int d, int hd, int rowhalf, char* smem) {
;     ...
; #pragma unroll 8
;       for (int jj = 0; jj < nst; ++jj) {
;         float4 na[CPL / 4], ny[CPL / 4], nw[CPL / 4], nb[CPL / 4], nk[CPL / 4];
;         float nvv;
;         {
;           const int jn = jj + 1;
;           const float* o = ob + jn * 392 + cg * CPL;
; #pragma unroll
;           for (int i = 0; i < CPL / 4; ++i) {
;             na[i] = *(const float4*)(o + 4 * i); ny[i] = *(const float4*)(o + 64 + 4 * i); nw[i] = *(const float4*)(o + 128 + 4 * i);
;             nb[i] = *(const float4*)(o + 192 + 4 * i); nk[i] = *(const float4*)(o + 256 + 4 * i);
;           }
;           nvv = ob[jn * 392 + 320 + row];
;         }
;         f2 A[NV], Y[NV], W[NV], B[NV], K[NV];
; #pragma unroll
;         for (int i = 0; i < CPL / 4; ++i) {
;           A[2 * i] = mk2(ca[i].x, ca[i].y); A[2 * i + 1] = mk2(ca[i].z, ca[i].w);
;           Y[2 * i] = mk2(cy[i].x, cy[i].y); Y[2 * i + 1] = mk2(cy[i].z, cy[i].w);
;           W[2 * i] = mk2(cw[i].x, cw[i].y); W[2 * i + 1] = mk2(cw[i].z, cw[i].w);
;           B[2 * i] = mk2(cb[i].x, cb[i].y); B[2 * i + 1] = mk2(cb[i].z, cb[i].w);
;           K[2 * i] = mk2(ck[i].x, ck[i].y); K[2 * i + 1] = mk2(ck[i].z, ck[i].w);
;         }
;         const float vv = cvv;
;         f2 pa0 = S[0] * A[0], pa1 = S[1] * A[1];
; #pragma unroll
;         for (int i = 2; i < NV; i += 2) { pa0 = S[i] * A[i] + pa0; pa1 = S[i + 1] * A[i + 1] + pa1; }
;         pa0 = pa0 + pa1;
;         float da = pa0.x + pa0.y;
;         const f2 vvv = mk2(vv, vv);
;         f2 SW[NV];
; #pragma unroll
;         for (int i = 0; i < NV; ++i) SW[i] = S[i] * W[i] + vvv * K[i];
;         da += __int_as_float(__builtin_amdgcn_update_dpp(0, __float_as_int(da), 0xB1, 0xf, 0xf, false));
;         da += __int_as_float(__builtin_amdgcn_update_dpp(0, __float_as_int(da), 0x4E, 0xf, 0xf, false));
;         if (CPL == 8) da += __int_as_float(__builtin_amdgcn_update_dpp(0, __float_as_int(da), 0x141, 0xf, 0xf, false));
;         const f2 dav = mk2(da, da);
; #pragma unroll
;         for (int i = 0; i < NV; ++i) S[i] = dav * B[i] + SW[i];
;         f2 py0 = S[0] * Y[0], py1 = S[1] * Y[1];
; #pragma unroll
;         for (int i = 2; i < NV; i += 2) { py0 = S[i] * Y[i] + py0; py1 = S[i + 1] * Y[i + 1] + py1; }
;         py0 = py0 + py1;
;         float yv = py0.x + py0.y;
	v_pk_mul_f32 v[88:89], v[2:3], v[170:171]
	ds_read_b128 v[44:47], v199 offset:14112
	v_pk_fma_f32 v[88:89], v[4:5], v[172:173], v[88:89]
	ds_read_b128 v[48:51], v199 offset:14128
	v_pk_fma_f32 v[88:89], v[6:7], v[174:175], v[88:89]
	ds_read_b128 v[76:79], v199 offset:15136
	v_pk_fma_f32 v[88:89], v[8:9], v[176:177], v[88:89]
	ds_read_b128 v[80:83], v199 offset:15152
	v_add_f32_e32 v86, v88, v89
	ds_read_b32 v84, v200 offset:14112
	v_pk_fma_f32 v[162:163], v[34:35], v[42:43], v[170:171] op_sel_hi:[1,0,1]
	v_add_f32_dpp v86, v86, v86 quad_perm:[1,0,3,2] row_mask:0xf bank_mask:0xf bound_ctrl:1
	v_add_f32_dpp v92, v92, v92 quad_perm:[1,0,3,2] row_mask:0xf bank_mask:0xf bound_ctrl:1
	ds_read_b128 v[68:71], v199 offset:14880
	v_add_f32_dpp v86, v86, v86 quad_perm:[2,3,0,1] row_mask:0xf bank_mask:0xf bound_ctrl:1
	v_add_f32_dpp v92, v92, v92 quad_perm:[2,3,0,1] row_mask:0xf bank_mask:0xf bound_ctrl:1
	ds_read_b128 v[72:75], v199 offset:14896
	v_add_f32_dpp v86, v86, v86 row_half_mirror row_mask:0xf bank_mask:0xf bound_ctrl:1
	v_add_f32_dpp v92, v92, v92 row_half_mirror row_mask:0xf bank_mask:0xf bound_ctrl:1
	v_pk_fma_f32 v[164:165], v[36:37], v[42:43], v[172:173] op_sel_hi:[1,0,1]
	v_pk_fma_f32 v[166:167], v[38:39], v[42:43], v[174:175] op_sel_hi:[1,0,1]
	v_pk_fma_f32 v[168:169], v[40:41], v[42:43], v[176:177] op_sel_hi:[1,0,1]
	s_waitcnt lgkmcnt(10)
	v_pk_fma_f32 v[94:95], v[26:27], v[86:87], v[162:163] op_sel_hi:[1,0,1]
	v_pk_fma_f32 v[96:97], v[28:29], v[86:87], v[164:165] op_sel_hi:[1,0,1]
	v_pk_fma_f32 v[98:99], v[30:31], v[86:87], v[166:167] op_sel_hi:[1,0,1]
	v_pk_fma_f32 v[100:101], v[32:33], v[86:87], v[168:169] op_sel_hi:[1,0,1]
	ds_write_b32 v201, v92 offset:1536
	v_pk_mul_f32 v[90:91], v[52:53], v[170:171]
	v_pk_fma_f32 v[90:91], v[54:55], v[172:173], v[90:91]
	v_pk_fma_f32 v[90:91], v[56:57], v[174:175], v[90:91]
	v_pk_fma_f32 v[90:91], v[58:59], v[176:177], v[90:91]
	ds_read_b128 v[52:55], v199 offset:14368
	v_add_f32_e32 v93, v90, v91
	ds_read_b128 v[56:59], v199 offset:14384
	s_waitcnt lgkmcnt(5)
	v_pk_mul_f32 v[88:89], v[44:45], v[94:95]
	ds_read_b128 v[2:5], v199 offset:15680
	v_pk_fma_f32 v[88:89], v[46:47], v[96:97], v[88:89]
	ds_read_b128 v[6:9], v199 offset:15696
	v_pk_fma_f32 v[88:89], v[48:49], v[98:99], v[88:89]
	ds_read_b128 v[34:37], v199 offset:16704
	v_pk_fma_f32 v[88:89], v[50:51], v[100:101], v[88:89]
	ds_read_b128 v[38:41], v199 offset:16720
	v_add_f32_e32 v86, v88, v89
	ds_read_b32 v42, v200 offset:15680
	v_pk_fma_f32 v[162:163], v[76:77], v[84:85], v[94:95] op_sel_hi:[1,0,1]
	v_add_f32_dpp v86, v86, v86 quad_perm:[1,0,3,2] row_mask:0xf bank_mask:0xf bound_ctrl:1
	v_add_f32_dpp v93, v93, v93 quad_perm:[1,0,3,2] row_mask:0xf bank_mask:0xf bound_ctrl:1
	ds_read_b128 v[26:29], v199 offset:16448
	v_add_f32_dpp v86, v86, v86 quad_perm:[2,3,0,1] row_mask:0xf bank_mask:0xf bound_ctrl:1
	v_add_f32_dpp v93, v93, v93 quad_perm:[2,3,0,1] row_mask:0xf bank_mask:0xf bound_ctrl:1
	ds_read_b128 v[30:33], v199 offset:16464
	v_add_f32_dpp v86, v86, v86 row_half_mirror row_mask:0xf bank_mask:0xf bound_ctrl:1
	v_add_f32_dpp v93, v93, v93 row_half_mirror row_mask:0xf bank_mask:0xf bound_ctrl:1
	v_pk_fma_f32 v[164:165], v[78:79], v[84:85], v[96:97] op_sel_hi:[1,0,1]
	v_pk_fma_f32 v[166:167], v[80:81], v[84:85], v[98:99] op_sel_hi:[1,0,1]
	v_pk_fma_f32 v[168:169], v[82:83], v[84:85], v[100:101] op_sel_hi:[1,0,1]
	s_waitcnt lgkmcnt(10)
	v_pk_fma_f32 v[170:171], v[68:69], v[86:87], v[162:163] op_sel_hi:[1,0,1]
	v_pk_fma_f32 v[172:173], v[70:71], v[86:87], v[164:165] op_sel_hi:[1,0,1]
	v_pk_fma_f32 v[174:175], v[72:73], v[86:87], v[166:167] op_sel_hi:[1,0,1]
	v_pk_fma_f32 v[176:177], v[74:75], v[86:87], v[168:169] op_sel_hi:[1,0,1]
	ds_write_b32 v201, v93 offset:1792
	v_pk_mul_f32 v[90:91], v[10:11], v[94:95]
	v_pk_fma_f32 v[90:91], v[12:13], v[96:97], v[90:91]
	v_pk_fma_f32 v[90:91], v[14:15], v[98:99], v[90:91]
	v_pk_fma_f32 v[90:91], v[16:17], v[100:101], v[90:91]
	ds_read_b128 v[10:13], v199 offset:15936
	v_add_f32_e32 v92, v90, v91
	ds_read_b128 v[14:17], v199 offset:15952
	s_waitcnt lgkmcnt(5)
	v_pk_mul_f32 v[88:89], v[2:3], v[170:171]
	ds_read_b128 v[44:47], v199 offset:17248
	v_pk_fma_f32 v[88:89], v[4:5], v[172:173], v[88:89]
	ds_read_b128 v[48:51], v199 offset:17264
	v_pk_fma_f32 v[88:89], v[6:7], v[174:175], v[88:89]
	ds_read_b128 v[76:79], v199 offset:18272
	v_pk_fma_f32 v[88:89], v[8:9], v[176:177], v[88:89]
	ds_read_b128 v[80:83], v199 offset:18288
	v_add_f32_e32 v86, v88, v89
	ds_read_b32 v84, v200 offset:17248
	v_pk_fma_f32 v[162:163], v[34:35], v[42:43], v[170:171] op_sel_hi:[1,0,1]
	v_add_f32_dpp v86, v86, v86 quad_perm:[1,0,3,2] row_mask:0xf bank_mask:0xf bound_ctrl:1
	v_add_f32_dpp v92, v92, v92 quad_perm:[1,0,3,2] row_mask:0xf bank_mask:0xf bound_ctrl:1
	ds_read_b128 v[68:71], v199 offset:18016
	v_add_f32_dpp v86, v86, v86 quad_perm:[2,3,0,1] row_mask:0xf bank_mask:0xf bound_ctrl:1
	v_add_f32_dpp v92, v92, v92 quad_perm:[2,3,0,1] row_mask:0xf bank_mask:0xf bound_ctrl:1
	ds_read_b128 v[72:75], v199 offset:18032
	v_add_f32_dpp v86, v86, v86 row_half_mirror row_mask:0xf bank_mask:0xf bound_ctrl:1
	v_add_f32_dpp v92, v92, v92 row_half_mirror row_mask:0xf bank_mask:0xf bound_ctrl:1
	v_pk_fma_f32 v[164:165], v[36:37], v[42:43], v[172:173] op_sel_hi:[1,0,1]
	v_pk_fma_f32 v[166:167], v[38:39], v[42:43], v[174:175] op_sel_hi:[1,0,1]
	v_pk_fma_f32 v[168:169], v[40:41], v[42:43], v[176:177] op_sel_hi:[1,0,1]
	s_waitcnt lgkmcnt(10)
; template <int CPL>
; DI void scan_block2(CP p, int layer, int s, int d, int hd, int rowhalf, char* smem) {
;     ...
; #pragma unroll 8
;       for (int jj = 0; jj < nst; ++jj) {
;         float4 na[CPL / 4], ny[CPL / 4], nw[CPL / 4], nb[CPL / 4], nk[CPL / 4];
;         float nvv;
;         {
;           const int jn = jj + 1;
;           const float* o = ob + jn * 392 + cg * CPL;
; #pragma unroll
;           for (int i = 0; i < CPL / 4; ++i) {
;             na[i] = *(const float4*)(o + 4 * i); ny[i] = *(const float4*)(o + 64 + 4 * i); nw[i] = *(const float4*)(o + 128 + 4 * i);
;             nb[i] = *(const float4*)(o + 192 + 4 * i); nk[i] = *(const float4*)(o + 256 + 4 * i);
;           }
;           nvv = ob[jn * 392 + 320 + row];
;         }
;         f2 A[NV], Y[NV], W[NV], B[NV], K[NV];
; #pragma unroll
;         for (int i = 0; i < CPL / 4; ++i) {
;           A[2 * i] = mk2(ca[i].x, ca[i].y); A[2 * i + 1] = mk2(ca[i].z, ca[i].w);
;           Y[2 * i] = mk2(cy[i].x, cy[i].y); Y[2 * i + 1] = mk2(cy[i].z, cy[i].w);
;           W[2 * i] = mk2(cw[i].x, cw[i].y); W[2 * i + 1] = mk2(cw[i].z, cw[i].w);
;           B[2 * i] = mk2(cb[i].x, cb[i].y); B[2 * i + 1] = mk2(cb[i].z, cb[i].w);
;           K[2 * i] = mk2(ck[i].x, ck[i].y); K[2 * i + 1] = mk2(ck[i].z, ck[i].w);
;         }
;         const float vv = cvv;
;         f2 pa0 = S[0] * A[0], pa1 = S[1] * A[1];
; #pragma unroll
;         for (int i = 2; i < NV; i += 2) { pa0 = S[i] * A[i] + pa0; pa1 = S[i + 1] * A[i + 1] + pa1; }
;         pa0 = pa0 + pa1;
;         float da = pa0.x + pa0.y;
;         const f2 vvv = mk2(vv, vv);
;         f2 SW[NV];
; #pragma unroll
;         for (int i = 0; i < NV; ++i) SW[i] = S[i] * W[i] + vvv * K[i];
;         da += __int_as_float(__builtin_amdgcn_update_dpp(0, __float_as_int(da), 0xB1, 0xf, 0xf, false));
;         da += __int_as_float(__builtin_amdgcn_update_dpp(0, __float_as_int(da), 0x4E, 0xf, 0xf, false));
;         if (CPL == 8) da += __int_as_float(__builtin_amdgcn_update_dpp(0, __float_as_int(da), 0x141, 0xf, 0xf, false));
;         const f2 dav = mk2(da, da);
; #pragma unroll
;         for (int i = 0; i < NV; ++i) S[i] = dav * B[i] + SW[i];
;         f2 py0 = S[0] * Y[0], py1 = S[1] * Y[1];
; #pragma unroll
;         for (int i = 2; i < NV; i += 2) { py0 = S[i] * Y[i] + py0; py1 = S[i + 1] * Y[i + 1] + py1; }
;         py0 = py0 + py1;
;         float yv = py0.x + py0.y;
	v_pk_fma_f32 v[94:95], v[26:27], v[86:87], v[162:163] op_sel_hi:[1,0,1]
	v_pk_fma_f32 v[96:97], v[28:29], v[86:87], v[164:165] op_sel_hi:[1,0,1]
	v_pk_fma_f32 v[98:99], v[30:31], v[86:87], v[166:167] op_sel_hi:[1,0,1]
	v_pk_fma_f32 v[100:101], v[32:33], v[86:87], v[168:169] op_sel_hi:[1,0,1]
	ds_write_b32 v201, v92 offset:2048
	v_pk_mul_f32 v[90:91], v[52:53], v[170:171]
	v_pk_fma_f32 v[90:91], v[54:55], v[172:173], v[90:91]
	v_pk_fma_f32 v[90:91], v[56:57], v[174:175], v[90:91]
	v_pk_fma_f32 v[90:91], v[58:59], v[176:177], v[90:91]
	ds_read_b128 v[52:55], v199 offset:17504
	v_add_f32_e32 v93, v90, v91
	ds_read_b128 v[56:59], v199 offset:17520
	s_waitcnt lgkmcnt(5)
	v_pk_mul_f32 v[88:89], v[44:45], v[94:95]
	ds_read_b128 v[2:5], v199 offset:18816
	v_pk_fma_f32 v[88:89], v[46:47], v[96:97], v[88:89]
	ds_read_b128 v[6:9], v199 offset:18832
	v_pk_fma_f32 v[88:89], v[48:49], v[98:99], v[88:89]
	ds_read_b128 v[34:37], v199 offset:19840
	v_pk_fma_f32 v[88:89], v[50:51], v[100:101], v[88:89]
	ds_read_b128 v[38:41], v199 offset:19856
	v_add_f32_e32 v86, v88, v89
	ds_read_b32 v42, v200 offset:18816
	v_pk_fma_f32 v[162:163], v[76:77], v[84:85], v[94:95] op_sel_hi:[1,0,1]
	v_add_f32_dpp v86, v86, v86 quad_perm:[1,0,3,2] row_mask:0xf bank_mask:0xf bound_ctrl:1
	v_add_f32_dpp v93, v93, v93 quad_perm:[1,0,3,2] row_mask:0xf bank_mask:0xf bound_ctrl:1
	ds_read_b128 v[26:29], v199 offset:19584
	v_add_f32_dpp v86, v86, v86 quad_perm:[2,3,0,1] row_mask:0xf bank_mask:0xf bound_ctrl:1
	v_add_f32_dpp v93, v93, v93 quad_perm:[2,3,0,1] row_mask:0xf bank_mask:0xf bound_ctrl:1
	ds_read_b128 v[30:33], v199 offset:19600
	v_add_f32_dpp v86, v86, v86 row_half_mirror row_mask:0xf bank_mask:0xf bound_ctrl:1
	v_add_f32_dpp v93, v93, v93 row_half_mirror row_mask:0xf bank_mask:0xf bound_ctrl:1
	v_pk_fma_f32 v[164:165], v[78:79], v[84:85], v[96:97] op_sel_hi:[1,0,1]
	v_pk_fma_f32 v[166:167], v[80:81], v[84:85], v[98:99] op_sel_hi:[1,0,1]
	v_pk_fma_f32 v[168:169], v[82:83], v[84:85], v[100:101] op_sel_hi:[1,0,1]
	s_waitcnt lgkmcnt(10)
	v_pk_fma_f32 v[170:171], v[68:69], v[86:87], v[162:163] op_sel_hi:[1,0,1]
	v_pk_fma_f32 v[172:173], v[70:71], v[86:87], v[164:165] op_sel_hi:[1,0,1]
	v_pk_fma_f32 v[174:175], v[72:73], v[86:87], v[166:167] op_sel_hi:[1,0,1]
	v_pk_fma_f32 v[176:177], v[74:75], v[86:87], v[168:169] op_sel_hi:[1,0,1]
	ds_write_b32 v201, v93 offset:2304
	v_pk_mul_f32 v[90:91], v[10:11], v[94:95]
	v_pk_fma_f32 v[90:91], v[12:13], v[96:97], v[90:91]
	v_pk_fma_f32 v[90:91], v[14:15], v[98:99], v[90:91]
	v_pk_fma_f32 v[90:91], v[16:17], v[100:101], v[90:91]
	ds_read_b128 v[10:13], v199 offset:19072
	v_add_f32_e32 v92, v90, v91
	ds_read_b128 v[14:17], v199 offset:19088
	s_waitcnt lgkmcnt(5)
	v_pk_mul_f32 v[88:89], v[2:3], v[170:171]
	ds_read_b128 v[44:47], v199 offset:20384
	v_pk_fma_f32 v[88:89], v[4:5], v[172:173], v[88:89]
	ds_read_b128 v[48:51], v199 offset:20400
	v_pk_fma_f32 v[88:89], v[6:7], v[174:175], v[88:89]
	ds_read_b128 v[76:79], v199 offset:21408
	v_pk_fma_f32 v[88:89], v[8:9], v[176:177], v[88:89]
	ds_read_b128 v[80:83], v199 offset:21424
	v_add_f32_e32 v86, v88, v89
	ds_read_b32 v84, v200 offset:20384
	v_pk_fma_f32 v[162:163], v[34:35], v[42:43], v[170:171] op_sel_hi:[1,0,1]
	v_add_f32_dpp v86, v86, v86 quad_perm:[1,0,3,2] row_mask:0xf bank_mask:0xf bound_ctrl:1
	v_add_f32_dpp v92, v92, v92 quad_perm:[1,0,3,2] row_mask:0xf bank_mask:0xf bound_ctrl:1
	ds_read_b128 v[68:71], v199 offset:21152
	v_add_f32_dpp v86, v86, v86 quad_perm:[2,3,0,1] row_mask:0xf bank_mask:0xf bound_ctrl:1
	v_add_f32_dpp v92, v92, v92 quad_perm:[2,3,0,1] row_mask:0xf bank_mask:0xf bound_ctrl:1
	ds_read_b128 v[72:75], v199 offset:21168
	v_add_f32_dpp v86, v86, v86 row_half_mirror row_mask:0xf bank_mask:0xf bound_ctrl:1
	v_add_f32_dpp v92, v92, v92 row_half_mirror row_mask:0xf bank_mask:0xf bound_ctrl:1
	v_pk_fma_f32 v[164:165], v[36:37], v[42:43], v[172:173] op_sel_hi:[1,0,1]
	v_pk_fma_f32 v[166:167], v[38:39], v[42:43], v[174:175] op_sel_hi:[1,0,1]
	v_pk_fma_f32 v[168:169], v[40:41], v[42:43], v[176:177] op_sel_hi:[1,0,1]
	s_waitcnt lgkmcnt(10)
	v_pk_fma_f32 v[94:95], v[26:27], v[86:87], v[162:163] op_sel_hi:[1,0,1]
	v_pk_fma_f32 v[96:97], v[28:29], v[86:87], v[164:165] op_sel_hi:[1,0,1]
	v_pk_fma_f32 v[98:99], v[30:31], v[86:87], v[166:167] op_sel_hi:[1,0,1]
	v_pk_fma_f32 v[100:101], v[32:33], v[86:87], v[168:169] op_sel_hi:[1,0,1]
	ds_write_b32 v201, v92 offset:2560
	v_pk_mul_f32 v[90:91], v[52:53], v[170:171]
	v_pk_fma_f32 v[90:91], v[54:55], v[172:173], v[90:91]
	v_pk_fma_f32 v[90:91], v[56:57], v[174:175], v[90:91]
	v_pk_fma_f32 v[90:91], v[58:59], v[176:177], v[90:91]
	ds_read_b128 v[52:55], v199 offset:20640
	v_add_f32_e32 v93, v90, v91
	ds_read_b128 v[56:59], v199 offset:20656
	s_waitcnt lgkmcnt(5)
	v_pk_mul_f32 v[88:89], v[44:45], v[94:95]
	ds_read_b128 v[2:5], v199 offset:21952
	v_pk_fma_f32 v[88:89], v[46:47], v[96:97], v[88:89]
	ds_read_b128 v[6:9], v199 offset:21968
	v_pk_fma_f32 v[88:89], v[48:49], v[98:99], v[88:89]
	ds_read_b128 v[34:37], v199 offset:22976
	v_pk_fma_f32 v[88:89], v[50:51], v[100:101], v[88:89]
	ds_read_b128 v[38:41], v199 offset:22992
	v_add_f32_e32 v86, v88, v89
	ds_read_b32 v42, v200 offset:21952
	v_pk_fma_f32 v[162:163], v[76:77], v[84:85], v[94:95] op_sel_hi:[1,0,1]
	v_add_f32_dpp v86, v86, v86 quad_perm:[1,0,3,2] row_mask:0xf bank_mask:0xf bound_ctrl:1
	v_add_f32_dpp v93, v93, v93 quad_perm:[1,0,3,2] row_mask:0xf bank_mask:0xf bound_ctrl:1
	ds_read_b128 v[26:29], v199 offset:22720
	v_add_f32_dpp v86, v86, v86 quad_perm:[2,3,0,1] row_mask:0xf bank_mask:0xf bound_ctrl:1
	v_add_f32_dpp v93, v93, v93 quad_perm:[2,3,0,1] row_mask:0xf bank_mask:0xf bound_ctrl:1
	ds_read_b128 v[30:33], v199 offset:22736
	v_add_f32_dpp v86, v86, v86 row_half_mirror row_mask:0xf bank_mask:0xf bound_ctrl:1
	v_add_f32_dpp v93, v93, v93 row_half_mirror row_mask:0xf bank_mask:0xf bound_ctrl:1
	v_pk_fma_f32 v[164:165], v[78:79], v[84:85], v[96:97] op_sel_hi:[1,0,1]
	v_pk_fma_f32 v[166:167], v[80:81], v[84:85], v[98:99] op_sel_hi:[1,0,1]
	v_pk_fma_f32 v[168:169], v[82:83], v[84:85], v[100:101] op_sel_hi:[1,0,1]
	s_waitcnt lgkmcnt(10)
; template <int CPL>
; DI void scan_block2(CP p, int layer, int s, int d, int hd, int rowhalf, char* smem) {
;     ...
; #pragma unroll 8
;       for (int jj = 0; jj < nst; ++jj) {
;         float4 na[CPL / 4], ny[CPL / 4], nw[CPL / 4], nb[CPL / 4], nk[CPL / 4];
;         float nvv;
;         {
;           const int jn = jj + 1;
;           const float* o = ob + jn * 392 + cg * CPL;
; #pragma unroll
;           for (int i = 0; i < CPL / 4; ++i) {
;             na[i] = *(const float4*)(o + 4 * i); ny[i] = *(const float4*)(o + 64 + 4 * i); nw[i] = *(const float4*)(o + 128 + 4 * i);
;             nb[i] = *(const float4*)(o + 192 + 4 * i); nk[i] = *(const float4*)(o + 256 + 4 * i);
;           }
;           nvv = ob[jn * 392 + 320 + row];
;         }
;         f2 A[NV], Y[NV], W[NV], B[NV], K[NV];
; #pragma unroll
;         for (int i = 0; i < CPL / 4; ++i) {
;           A[2 * i] = mk2(ca[i].x, ca[i].y); A[2 * i + 1] = mk2(ca[i].z, ca[i].w);
;           Y[2 * i] = mk2(cy[i].x, cy[i].y); Y[2 * i + 1] = mk2(cy[i].z, cy[i].w);
;           W[2 * i] = mk2(cw[i].x, cw[i].y); W[2 * i + 1] = mk2(cw[i].z, cw[i].w);
;           B[2 * i] = mk2(cb[i].x, cb[i].y); B[2 * i + 1] = mk2(cb[i].z, cb[i].w);
;           K[2 * i] = mk2(ck[i].x, ck[i].y); K[2 * i + 1] = mk2(ck[i].z, ck[i].w);
;         }
;         const float vv = cvv;
;         f2 pa0 = S[0] * A[0], pa1 = S[1] * A[1];
; #pragma unroll
;         for (int i = 2; i < NV; i += 2) { pa0 = S[i] * A[i] + pa0; pa1 = S[i + 1] * A[i + 1] + pa1; }
;         pa0 = pa0 + pa1;
;         float da = pa0.x + pa0.y;
;         const f2 vvv = mk2(vv, vv);
;         f2 SW[NV];
; #pragma unroll
;         for (int i = 0; i < NV; ++i) SW[i] = S[i] * W[i] + vvv * K[i];
;         da += __int_as_float(__builtin_amdgcn_update_dpp(0, __float_as_int(da), 0xB1, 0xf, 0xf, false));
;         da += __int_as_float(__builtin_amdgcn_update_dpp(0, __float_as_int(da), 0x4E, 0xf, 0xf, false));
;         if (CPL == 8) da += __int_as_float(__builtin_amdgcn_update_dpp(0, __float_as_int(da), 0x141, 0xf, 0xf, false));
;         const f2 dav = mk2(da, da);
; #pragma unroll
;         for (int i = 0; i < NV; ++i) S[i] = dav * B[i] + SW[i];
;         f2 py0 = S[0] * Y[0], py1 = S[1] * Y[1];
; #pragma unroll
;         for (int i = 2; i < NV; i += 2) { py0 = S[i] * Y[i] + py0; py1 = S[i + 1] * Y[i + 1] + py1; }
;         py0 = py0 + py1;
;         float yv = py0.x + py0.y;
	v_pk_fma_f32 v[170:171], v[68:69], v[86:87], v[162:163] op_sel_hi:[1,0,1]
	v_pk_fma_f32 v[172:173], v[70:71], v[86:87], v[164:165] op_sel_hi:[1,0,1]
	v_pk_fma_f32 v[174:175], v[72:73], v[86:87], v[166:167] op_sel_hi:[1,0,1]
	v_pk_fma_f32 v[176:177], v[74:75], v[86:87], v[168:169] op_sel_hi:[1,0,1]
	ds_write_b32 v201, v93 offset:2816
	v_pk_mul_f32 v[90:91], v[10:11], v[94:95]
	v_pk_fma_f32 v[90:91], v[12:13], v[96:97], v[90:91]
	v_pk_fma_f32 v[90:91], v[14:15], v[98:99], v[90:91]
	v_pk_fma_f32 v[90:91], v[16:17], v[100:101], v[90:91]
	ds_read_b128 v[10:13], v199 offset:22208
	v_add_f32_e32 v92, v90, v91
	ds_read_b128 v[14:17], v199 offset:22224
	s_waitcnt lgkmcnt(5)
	v_pk_mul_f32 v[88:89], v[2:3], v[170:171]
	ds_read_b128 v[44:47], v199 offset:23520
	v_pk_fma_f32 v[88:89], v[4:5], v[172:173], v[88:89]
	ds_read_b128 v[48:51], v199 offset:23536
	v_pk_fma_f32 v[88:89], v[6:7], v[174:175], v[88:89]
	ds_read_b128 v[76:79], v199 offset:24544
	v_pk_fma_f32 v[88:89], v[8:9], v[176:177], v[88:89]
	ds_read_b128 v[80:83], v199 offset:24560
	v_add_f32_e32 v86, v88, v89
	ds_read_b32 v84, v200 offset:23520
	v_pk_fma_f32 v[162:163], v[34:35], v[42:43], v[170:171] op_sel_hi:[1,0,1]
	v_add_f32_dpp v86, v86, v86 quad_perm:[1,0,3,2] row_mask:0xf bank_mask:0xf bound_ctrl:1
	v_add_f32_dpp v92, v92, v92 quad_perm:[1,0,3,2] row_mask:0xf bank_mask:0xf bound_ctrl:1
	ds_read_b128 v[68:71], v199 offset:24288
	v_add_f32_dpp v86, v86, v86 quad_perm:[2,3,0,1] row_mask:0xf bank_mask:0xf bound_ctrl:1
	v_add_f32_dpp v92, v92, v92 quad_perm:[2,3,0,1] row_mask:0xf bank_mask:0xf bound_ctrl:1
	ds_read_b128 v[72:75], v199 offset:24304
	v_add_f32_dpp v86, v86, v86 row_half_mirror row_mask:0xf bank_mask:0xf bound_ctrl:1
	v_add_f32_dpp v92, v92, v92 row_half_mirror row_mask:0xf bank_mask:0xf bound_ctrl:1
	v_pk_fma_f32 v[164:165], v[36:37], v[42:43], v[172:173] op_sel_hi:[1,0,1]
	v_pk_fma_f32 v[166:167], v[38:39], v[42:43], v[174:175] op_sel_hi:[1,0,1]
	v_pk_fma_f32 v[168:169], v[40:41], v[42:43], v[176:177] op_sel_hi:[1,0,1]
	s_waitcnt lgkmcnt(10)
	v_pk_fma_f32 v[94:95], v[26:27], v[86:87], v[162:163] op_sel_hi:[1,0,1]
	v_pk_fma_f32 v[96:97], v[28:29], v[86:87], v[164:165] op_sel_hi:[1,0,1]
	v_pk_fma_f32 v[98:99], v[30:31], v[86:87], v[166:167] op_sel_hi:[1,0,1]
	v_pk_fma_f32 v[100:101], v[32:33], v[86:87], v[168:169] op_sel_hi:[1,0,1]
	ds_write_b32 v201, v92 offset:3072
	v_pk_mul_f32 v[90:91], v[52:53], v[170:171]
	v_pk_fma_f32 v[90:91], v[54:55], v[172:173], v[90:91]
	v_pk_fma_f32 v[90:91], v[56:57], v[174:175], v[90:91]
	v_pk_fma_f32 v[90:91], v[58:59], v[176:177], v[90:91]
	ds_read_b128 v[52:55], v199 offset:23776
	v_add_f32_e32 v93, v90, v91
	ds_read_b128 v[56:59], v199 offset:23792
	s_waitcnt lgkmcnt(5)
	v_pk_mul_f32 v[88:89], v[44:45], v[94:95]
	ds_read_b128 v[2:5], v199 offset:25088
	v_pk_fma_f32 v[88:89], v[46:47], v[96:97], v[88:89]
	ds_read_b128 v[6:9], v199 offset:25104
	v_pk_fma_f32 v[88:89], v[48:49], v[98:99], v[88:89]
	ds_read_b128 v[34:37], v199 offset:26112
	v_pk_fma_f32 v[88:89], v[50:51], v[100:101], v[88:89]
	ds_read_b128 v[38:41], v199 offset:26128
	v_add_f32_e32 v86, v88, v89
	ds_read_b32 v42, v200 offset:25088
	ds_read_b128 v[18:21], v199 offset:24032
	ds_read_b128 v[22:25], v199 offset:24048
	v_add_f32_dpp v86, v86, v86 quad_perm:[1,0,3,2] row_mask:0xf bank_mask:0xf bound_ctrl:1
	v_add_f32_dpp v93, v93, v93 quad_perm:[1,0,3,2] row_mask:0xf bank_mask:0xf bound_ctrl:1
	ds_read_b128 v[26:29], v199 offset:25856
	v_add_f32_dpp v86, v86, v86 quad_perm:[2,3,0,1] row_mask:0xf bank_mask:0xf bound_ctrl:1
	v_add_f32_dpp v93, v93, v93 quad_perm:[2,3,0,1] row_mask:0xf bank_mask:0xf bound_ctrl:1
	ds_read_b128 v[30:33], v199 offset:25872
	v_add_f32_dpp v86, v86, v86 row_half_mirror row_mask:0xf bank_mask:0xf bound_ctrl:1
	v_add_f32_dpp v93, v93, v93 row_half_mirror row_mask:0xf bank_mask:0xf bound_ctrl:1
	v_pk_fma_f32 v[162:163], v[76:77], v[84:85], v[94:95] op_sel_hi:[1,0,1]
	v_pk_fma_f32 v[164:165], v[78:79], v[84:85], v[96:97] op_sel_hi:[1,0,1]
	v_pk_fma_f32 v[166:167], v[80:81], v[84:85], v[98:99] op_sel_hi:[1,0,1]
	v_pk_fma_f32 v[168:169], v[82:83], v[84:85], v[100:101] op_sel_hi:[1,0,1]
	s_waitcnt lgkmcnt(12)
	v_pk_fma_f32 v[170:171], v[68:69], v[86:87], v[162:163] op_sel_hi:[1,0,1]
	v_pk_fma_f32 v[172:173], v[70:71], v[86:87], v[164:165] op_sel_hi:[1,0,1]
	v_pk_fma_f32 v[174:175], v[72:73], v[86:87], v[166:167] op_sel_hi:[1,0,1]
	v_pk_fma_f32 v[176:177], v[74:75], v[86:87], v[168:169] op_sel_hi:[1,0,1]
	s_waitcnt lgkmcnt(2)
	v_pk_mul_f32 v[170:171], v[170:171], v[18:19]
	v_pk_mul_f32 v[172:173], v[172:173], v[20:21]
	v_pk_mul_f32 v[174:175], v[174:175], v[22:23]
	v_pk_mul_f32 v[176:177], v[176:177], v[24:25]
	ds_write_b32 v201, v93 offset:3328
	v_pk_mul_f32 v[90:91], v[10:11], v[94:95]
	v_pk_fma_f32 v[90:91], v[12:13], v[96:97], v[90:91]
	v_pk_fma_f32 v[90:91], v[14:15], v[98:99], v[90:91]
	v_pk_fma_f32 v[90:91], v[16:17], v[100:101], v[90:91]
	ds_read_b128 v[10:13], v199 offset:25344
	v_add_f32_e32 v92, v90, v91
	ds_read_b128 v[14:17], v199 offset:25360
	s_cmp_eq_u32 s10, 0x100
	s_cbranch_scc1 .Lsc8_drain16
; template <int CPL>
; DI void scan_block2(CP p, int layer, int s, int d, int hd, int rowhalf, char* smem) {
;     ...
; #pragma unroll 8
;       for (int jj = 0; jj < nst; ++jj) {
;         float4 na[CPL / 4], ny[CPL / 4], nw[CPL / 4], nb[CPL / 4], nk[CPL / 4];
;         float nvv;
;         {
;           const int jn = jj + 1;
;           const float* o = ob + jn * 392 + cg * CPL;
; #pragma unroll
;           for (int i = 0; i < CPL / 4; ++i) {
;             na[i] = *(const float4*)(o + 4 * i); ny[i] = *(const float4*)(o + 64 + 4 * i); nw[i] = *(const float4*)(o + 128 + 4 * i);
;             nb[i] = *(const float4*)(o + 192 + 4 * i); nk[i] = *(const float4*)(o + 256 + 4 * i);
;           }
;           nvv = ob[jn * 392 + 320 + row];
;         }
;         f2 A[NV], Y[NV], W[NV], B[NV], K[NV];
; #pragma unroll
;         for (int i = 0; i < CPL / 4; ++i) {
;           A[2 * i] = mk2(ca[i].x, ca[i].y); A[2 * i + 1] = mk2(ca[i].z, ca[i].w);
;           Y[2 * i] = mk2(cy[i].x, cy[i].y); Y[2 * i + 1] = mk2(cy[i].z, cy[i].w);
;           W[2 * i] = mk2(cw[i].x, cw[i].y); W[2 * i + 1] = mk2(cw[i].z, cw[i].w);
;           B[2 * i] = mk2(cb[i].x, cb[i].y); B[2 * i + 1] = mk2(cb[i].z, cb[i].w);
;           K[2 * i] = mk2(ck[i].x, ck[i].y); K[2 * i + 1] = mk2(ck[i].z, ck[i].w);
;         }
;         const float vv = cvv;
;         f2 pa0 = S[0] * A[0], pa1 = S[1] * A[1];
; #pragma unroll
;         for (int i = 2; i < NV; i += 2) { pa0 = S[i] * A[i] + pa0; pa1 = S[i + 1] * A[i + 1] + pa1; }
;         pa0 = pa0 + pa1;
;         float da = pa0.x + pa0.y;
;         const f2 vvv = mk2(vv, vv);
;         f2 SW[NV];
; #pragma unroll
;         for (int i = 0; i < NV; ++i) SW[i] = S[i] * W[i] + vvv * K[i];
;         da += __int_as_float(__builtin_amdgcn_update_dpp(0, __float_as_int(da), 0xB1, 0xf, 0xf, false));
;         da += __int_as_float(__builtin_amdgcn_update_dpp(0, __float_as_int(da), 0x4E, 0xf, 0xf, false));
;         if (CPL == 8) da += __int_as_float(__builtin_amdgcn_update_dpp(0, __float_as_int(da), 0x141, 0xf, 0xf, false));
;         const f2 dav = mk2(da, da);
; #pragma unroll
;         for (int i = 0; i < NV; ++i) S[i] = dav * B[i] + SW[i];
;         f2 py0 = S[0] * Y[0], py1 = S[1] * Y[1];
; #pragma unroll
;         for (int i = 2; i < NV; i += 2) { py0 = S[i] * Y[i] + py0; py1 = S[i + 1] * Y[i + 1] + py1; }
;         py0 = py0 + py1;
;         float yv = py0.x + py0.y;
	s_waitcnt lgkmcnt(7)
	v_pk_mul_f32 v[88:89], v[2:3], v[170:171]
	ds_read_b128 v[44:47], v199 offset:26656
	v_pk_fma_f32 v[88:89], v[4:5], v[172:173], v[88:89]
	ds_read_b128 v[48:51], v199 offset:26672
	v_pk_fma_f32 v[88:89], v[6:7], v[174:175], v[88:89]
	ds_read_b128 v[76:79], v199 offset:27680
	v_pk_fma_f32 v[88:89], v[8:9], v[176:177], v[88:89]
	ds_read_b128 v[80:83], v199 offset:27696
	v_add_f32_e32 v86, v88, v89
	ds_read_b32 v84, v200 offset:26656
	v_pk_fma_f32 v[162:163], v[34:35], v[42:43], v[170:171] op_sel_hi:[1,0,1]
	v_add_f32_dpp v86, v86, v86 quad_perm:[1,0,3,2] row_mask:0xf bank_mask:0xf bound_ctrl:1
	v_add_f32_dpp v92, v92, v92 quad_perm:[1,0,3,2] row_mask:0xf bank_mask:0xf bound_ctrl:1
	ds_read_b128 v[68:71], v199 offset:27424
	v_add_f32_dpp v86, v86, v86 quad_perm:[2,3,0,1] row_mask:0xf bank_mask:0xf bound_ctrl:1
	v_add_f32_dpp v92, v92, v92 quad_perm:[2,3,0,1] row_mask:0xf bank_mask:0xf bound_ctrl:1
	ds_read_b128 v[72:75], v199 offset:27440
	v_add_f32_dpp v86, v86, v86 row_half_mirror row_mask:0xf bank_mask:0xf bound_ctrl:1
	v_add_f32_dpp v92, v92, v92 row_half_mirror row_mask:0xf bank_mask:0xf bound_ctrl:1
	v_pk_fma_f32 v[164:165], v[36:37], v[42:43], v[172:173] op_sel_hi:[1,0,1]
	v_pk_fma_f32 v[166:167], v[38:39], v[42:43], v[174:175] op_sel_hi:[1,0,1]
	v_pk_fma_f32 v[168:169], v[40:41], v[42:43], v[176:177] op_sel_hi:[1,0,1]
	s_waitcnt lgkmcnt(10)
	v_pk_fma_f32 v[94:95], v[26:27], v[86:87], v[162:163] op_sel_hi:[1,0,1]
	v_pk_fma_f32 v[96:97], v[28:29], v[86:87], v[164:165] op_sel_hi:[1,0,1]
	v_pk_fma_f32 v[98:99], v[30:31], v[86:87], v[166:167] op_sel_hi:[1,0,1]
	v_pk_fma_f32 v[100:101], v[32:33], v[86:87], v[168:169] op_sel_hi:[1,0,1]
	ds_write_b32 v201, v92 offset:3584
	v_pk_mul_f32 v[90:91], v[52:53], v[170:171]
	v_pk_fma_f32 v[90:91], v[54:55], v[172:173], v[90:91]
	v_pk_fma_f32 v[90:91], v[56:57], v[174:175], v[90:91]
	v_pk_fma_f32 v[90:91], v[58:59], v[176:177], v[90:91]
	ds_read_b128 v[52:55], v199 offset:26912
	v_add_f32_e32 v93, v90, v91
	ds_read_b128 v[56:59], v199 offset:26928
	s_waitcnt lgkmcnt(5)
	v_pk_mul_f32 v[88:89], v[44:45], v[94:95]
	ds_read_b128 v[2:5], v199 offset:28224
	v_pk_fma_f32 v[88:89], v[46:47], v[96:97], v[88:89]
	ds_read_b128 v[6:9], v199 offset:28240
	v_pk_fma_f32 v[88:89], v[48:49], v[98:99], v[88:89]
	ds_read_b128 v[34:37], v199 offset:29248
	v_pk_fma_f32 v[88:89], v[50:51], v[100:101], v[88:89]
	ds_read_b128 v[38:41], v199 offset:29264
	v_add_f32_e32 v86, v88, v89
	ds_read_b32 v42, v200 offset:28224
	v_pk_fma_f32 v[162:163], v[76:77], v[84:85], v[94:95] op_sel_hi:[1,0,1]
	v_add_f32_dpp v86, v86, v86 quad_perm:[1,0,3,2] row_mask:0xf bank_mask:0xf bound_ctrl:1
	v_add_f32_dpp v93, v93, v93 quad_perm:[1,0,3,2] row_mask:0xf bank_mask:0xf bound_ctrl:1
	ds_read_b128 v[26:29], v199 offset:28992
	v_add_f32_dpp v86, v86, v86 quad_perm:[2,3,0,1] row_mask:0xf bank_mask:0xf bound_ctrl:1
	v_add_f32_dpp v93, v93, v93 quad_perm:[2,3,0,1] row_mask:0xf bank_mask:0xf bound_ctrl:1
	ds_read_b128 v[30:33], v199 offset:29008
	v_add_f32_dpp v86, v86, v86 row_half_mirror row_mask:0xf bank_mask:0xf bound_ctrl:1
	v_add_f32_dpp v93, v93, v93 row_half_mirror row_mask:0xf bank_mask:0xf bound_ctrl:1
	v_pk_fma_f32 v[164:165], v[78:79], v[84:85], v[96:97] op_sel_hi:[1,0,1]
	v_pk_fma_f32 v[166:167], v[80:81], v[84:85], v[98:99] op_sel_hi:[1,0,1]
	v_pk_fma_f32 v[168:169], v[82:83], v[84:85], v[100:101] op_sel_hi:[1,0,1]
	s_waitcnt lgkmcnt(10)
	v_pk_fma_f32 v[170:171], v[68:69], v[86:87], v[162:163] op_sel_hi:[1,0,1]
	v_pk_fma_f32 v[172:173], v[70:71], v[86:87], v[164:165] op_sel_hi:[1,0,1]
	v_pk_fma_f32 v[174:175], v[72:73], v[86:87], v[166:167] op_sel_hi:[1,0,1]
	v_pk_fma_f32 v[176:177], v[74:75], v[86:87], v[168:169] op_sel_hi:[1,0,1]
	ds_write_b32 v201, v93 offset:3840
	v_pk_mul_f32 v[90:91], v[10:11], v[94:95]
	v_pk_fma_f32 v[90:91], v[12:13], v[96:97], v[90:91]
	v_pk_fma_f32 v[90:91], v[14:15], v[98:99], v[90:91]
	v_pk_fma_f32 v[90:91], v[16:17], v[100:101], v[90:91]
	ds_read_b128 v[10:13], v199 offset:28480
	v_add_f32_e32 v92, v90, v91
	ds_read_b128 v[14:17], v199 offset:28496
	s_waitcnt lgkmcnt(5)
	v_pk_mul_f32 v[88:89], v[2:3], v[170:171]
	ds_read_b128 v[44:47], v199 offset:29792
	v_pk_fma_f32 v[88:89], v[4:5], v[172:173], v[88:89]
	ds_read_b128 v[48:51], v199 offset:29808
	v_pk_fma_f32 v[88:89], v[6:7], v[174:175], v[88:89]
	ds_read_b128 v[76:79], v199 offset:30816
	v_pk_fma_f32 v[88:89], v[8:9], v[176:177], v[88:89]
	ds_read_b128 v[80:83], v199 offset:30832
	v_add_f32_e32 v86, v88, v89
	ds_read_b32 v84, v200 offset:29792
	v_pk_fma_f32 v[162:163], v[34:35], v[42:43], v[170:171] op_sel_hi:[1,0,1]
	v_add_f32_dpp v86, v86, v86 quad_perm:[1,0,3,2] row_mask:0xf bank_mask:0xf bound_ctrl:1
	v_add_f32_dpp v92, v92, v92 quad_perm:[1,0,3,2] row_mask:0xf bank_mask:0xf bound_ctrl:1
	ds_read_b128 v[68:71], v199 offset:30560
	v_add_f32_dpp v86, v86, v86 quad_perm:[2,3,0,1] row_mask:0xf bank_mask:0xf bound_ctrl:1
	v_add_f32_dpp v92, v92, v92 quad_perm:[2,3,0,1] row_mask:0xf bank_mask:0xf bound_ctrl:1
	ds_read_b128 v[72:75], v199 offset:30576
	v_add_f32_dpp v86, v86, v86 row_half_mirror row_mask:0xf bank_mask:0xf bound_ctrl:1
	v_add_f32_dpp v92, v92, v92 row_half_mirror row_mask:0xf bank_mask:0xf bound_ctrl:1
	v_pk_fma_f32 v[164:165], v[36:37], v[42:43], v[172:173] op_sel_hi:[1,0,1]
	v_pk_fma_f32 v[166:167], v[38:39], v[42:43], v[174:175] op_sel_hi:[1,0,1]
	v_pk_fma_f32 v[168:169], v[40:41], v[42:43], v[176:177] op_sel_hi:[1,0,1]
	s_waitcnt lgkmcnt(10)
; template <int CPL>
; DI void scan_block2(CP p, int layer, int s, int d, int hd, int rowhalf, char* smem) {
;     ...
; #pragma unroll 8
;       for (int jj = 0; jj < nst; ++jj) {
;         float4 na[CPL / 4], ny[CPL / 4], nw[CPL / 4], nb[CPL / 4], nk[CPL / 4];
;         float nvv;
;         {
;           const int jn = jj + 1;
;           const float* o = ob + jn * 392 + cg * CPL;
; #pragma unroll
;           for (int i = 0; i < CPL / 4; ++i) {
;             na[i] = *(const float4*)(o + 4 * i); ny[i] = *(const float4*)(o + 64 + 4 * i); nw[i] = *(const float4*)(o + 128 + 4 * i);
;             nb[i] = *(const float4*)(o + 192 + 4 * i); nk[i] = *(const float4*)(o + 256 + 4 * i);
;           }
;           nvv = ob[jn * 392 + 320 + row];
;         }
;         f2 A[NV], Y[NV], W[NV], B[NV], K[NV];
; #pragma unroll
;         for (int i = 0; i < CPL / 4; ++i) {
;           A[2 * i] = mk2(ca[i].x, ca[i].y); A[2 * i + 1] = mk2(ca[i].z, ca[i].w);
;           Y[2 * i] = mk2(cy[i].x, cy[i].y); Y[2 * i + 1] = mk2(cy[i].z, cy[i].w);
;           W[2 * i] = mk2(cw[i].x, cw[i].y); W[2 * i + 1] = mk2(cw[i].z, cw[i].w);
;           B[2 * i] = mk2(cb[i].x, cb[i].y); B[2 * i + 1] = mk2(cb[i].z, cb[i].w);
;           K[2 * i] = mk2(ck[i].x, ck[i].y); K[2 * i + 1] = mk2(ck[i].z, ck[i].w);
;         }
;         const float vv = cvv;
;         f2 pa0 = S[0] * A[0], pa1 = S[1] * A[1];
; #pragma unroll
;         for (int i = 2; i < NV; i += 2) { pa0 = S[i] * A[i] + pa0; pa1 = S[i + 1] * A[i + 1] + pa1; }
;         pa0 = pa0 + pa1;
;         float da = pa0.x + pa0.y;
;         const f2 vvv = mk2(vv, vv);
;         f2 SW[NV];
; #pragma unroll
;         for (int i = 0; i < NV; ++i) SW[i] = S[i] * W[i] + vvv * K[i];
;         da += __int_as_float(__builtin_amdgcn_update_dpp(0, __float_as_int(da), 0xB1, 0xf, 0xf, false));
;         da += __int_as_float(__builtin_amdgcn_update_dpp(0, __float_as_int(da), 0x4E, 0xf, 0xf, false));
;         if (CPL == 8) da += __int_as_float(__builtin_amdgcn_update_dpp(0, __float_as_int(da), 0x141, 0xf, 0xf, false));
;         const f2 dav = mk2(da, da);
; #pragma unroll
;         for (int i = 0; i < NV; ++i) S[i] = dav * B[i] + SW[i];
;         f2 py0 = S[0] * Y[0], py1 = S[1] * Y[1];
; #pragma unroll
;         for (int i = 2; i < NV; i += 2) { py0 = S[i] * Y[i] + py0; py1 = S[i + 1] * Y[i + 1] + py1; }
;         py0 = py0 + py1;
;         float yv = py0.x + py0.y;
	v_pk_fma_f32 v[94:95], v[26:27], v[86:87], v[162:163] op_sel_hi:[1,0,1]
	v_pk_fma_f32 v[96:97], v[28:29], v[86:87], v[164:165] op_sel_hi:[1,0,1]
	v_pk_fma_f32 v[98:99], v[30:31], v[86:87], v[166:167] op_sel_hi:[1,0,1]
	v_pk_fma_f32 v[100:101], v[32:33], v[86:87], v[168:169] op_sel_hi:[1,0,1]
	ds_write_b32 v201, v92 offset:4096
	v_pk_mul_f32 v[90:91], v[52:53], v[170:171]
	v_pk_fma_f32 v[90:91], v[54:55], v[172:173], v[90:91]
	v_pk_fma_f32 v[90:91], v[56:57], v[174:175], v[90:91]
	v_pk_fma_f32 v[90:91], v[58:59], v[176:177], v[90:91]
	ds_read_b128 v[52:55], v199 offset:30048
	v_add_f32_e32 v93, v90, v91
	ds_read_b128 v[56:59], v199 offset:30064
	s_waitcnt lgkmcnt(5)
	v_pk_mul_f32 v[88:89], v[44:45], v[94:95]
	ds_read_b128 v[2:5], v199 offset:31360
	v_pk_fma_f32 v[88:89], v[46:47], v[96:97], v[88:89]
	ds_read_b128 v[6:9], v199 offset:31376
	v_pk_fma_f32 v[88:89], v[48:49], v[98:99], v[88:89]
	ds_read_b128 v[34:37], v199 offset:32384
	v_pk_fma_f32 v[88:89], v[50:51], v[100:101], v[88:89]
	ds_read_b128 v[38:41], v199 offset:32400
	v_add_f32_e32 v86, v88, v89
	ds_read_b32 v42, v200 offset:31360
	v_pk_fma_f32 v[162:163], v[76:77], v[84:85], v[94:95] op_sel_hi:[1,0,1]
	v_add_f32_dpp v86, v86, v86 quad_perm:[1,0,3,2] row_mask:0xf bank_mask:0xf bound_ctrl:1
	v_add_f32_dpp v93, v93, v93 quad_perm:[1,0,3,2] row_mask:0xf bank_mask:0xf bound_ctrl:1
	ds_read_b128 v[26:29], v199 offset:32128
	v_add_f32_dpp v86, v86, v86 quad_perm:[2,3,0,1] row_mask:0xf bank_mask:0xf bound_ctrl:1
	v_add_f32_dpp v93, v93, v93 quad_perm:[2,3,0,1] row_mask:0xf bank_mask:0xf bound_ctrl:1
	ds_read_b128 v[30:33], v199 offset:32144
	v_add_f32_dpp v86, v86, v86 row_half_mirror row_mask:0xf bank_mask:0xf bound_ctrl:1
	v_add_f32_dpp v93, v93, v93 row_half_mirror row_mask:0xf bank_mask:0xf bound_ctrl:1
	v_pk_fma_f32 v[164:165], v[78:79], v[84:85], v[96:97] op_sel_hi:[1,0,1]
	v_pk_fma_f32 v[166:167], v[80:81], v[84:85], v[98:99] op_sel_hi:[1,0,1]
	v_pk_fma_f32 v[168:169], v[82:83], v[84:85], v[100:101] op_sel_hi:[1,0,1]
	s_waitcnt lgkmcnt(10)
	v_pk_fma_f32 v[170:171], v[68:69], v[86:87], v[162:163] op_sel_hi:[1,0,1]
	v_pk_fma_f32 v[172:173], v[70:71], v[86:87], v[164:165] op_sel_hi:[1,0,1]
	v_pk_fma_f32 v[174:175], v[72:73], v[86:87], v[166:167] op_sel_hi:[1,0,1]
	v_pk_fma_f32 v[176:177], v[74:75], v[86:87], v[168:169] op_sel_hi:[1,0,1]
	ds_write_b32 v201, v93 offset:4352
	v_pk_mul_f32 v[90:91], v[10:11], v[94:95]
	v_pk_fma_f32 v[90:91], v[12:13], v[96:97], v[90:91]
	v_pk_fma_f32 v[90:91], v[14:15], v[98:99], v[90:91]
	v_pk_fma_f32 v[90:91], v[16:17], v[100:101], v[90:91]
	ds_read_b128 v[10:13], v199 offset:31616
	v_add_f32_e32 v92, v90, v91
	ds_read_b128 v[14:17], v199 offset:31632
	s_waitcnt lgkmcnt(5)
	v_pk_mul_f32 v[88:89], v[2:3], v[170:171]
	ds_read_b128 v[44:47], v199 offset:32928
	v_pk_fma_f32 v[88:89], v[4:5], v[172:173], v[88:89]
	ds_read_b128 v[48:51], v199 offset:32944
	v_pk_fma_f32 v[88:89], v[6:7], v[174:175], v[88:89]
	ds_read_b128 v[76:79], v199 offset:33952
	v_pk_fma_f32 v[88:89], v[8:9], v[176:177], v[88:89]
	ds_read_b128 v[80:83], v199 offset:33968
	v_add_f32_e32 v86, v88, v89
	ds_read_b32 v84, v200 offset:32928
	v_pk_fma_f32 v[162:163], v[34:35], v[42:43], v[170:171] op_sel_hi:[1,0,1]
	v_add_f32_dpp v86, v86, v86 quad_perm:[1,0,3,2] row_mask:0xf bank_mask:0xf bound_ctrl:1
	v_add_f32_dpp v92, v92, v92 quad_perm:[1,0,3,2] row_mask:0xf bank_mask:0xf bound_ctrl:1
	ds_read_b128 v[68:71], v199 offset:33696
	v_add_f32_dpp v86, v86, v86 quad_perm:[2,3,0,1] row_mask:0xf bank_mask:0xf bound_ctrl:1
	v_add_f32_dpp v92, v92, v92 quad_perm:[2,3,0,1] row_mask:0xf bank_mask:0xf bound_ctrl:1
	ds_read_b128 v[72:75], v199 offset:33712
	v_add_f32_dpp v86, v86, v86 row_half_mirror row_mask:0xf bank_mask:0xf bound_ctrl:1
	v_add_f32_dpp v92, v92, v92 row_half_mirror row_mask:0xf bank_mask:0xf bound_ctrl:1
	v_pk_fma_f32 v[164:165], v[36:37], v[42:43], v[172:173] op_sel_hi:[1,0,1]
	v_pk_fma_f32 v[166:167], v[38:39], v[42:43], v[174:175] op_sel_hi:[1,0,1]
	v_pk_fma_f32 v[168:169], v[40:41], v[42:43], v[176:177] op_sel_hi:[1,0,1]
	s_waitcnt lgkmcnt(10)
	v_pk_fma_f32 v[94:95], v[26:27], v[86:87], v[162:163] op_sel_hi:[1,0,1]
	v_pk_fma_f32 v[96:97], v[28:29], v[86:87], v[164:165] op_sel_hi:[1,0,1]
	v_pk_fma_f32 v[98:99], v[30:31], v[86:87], v[166:167] op_sel_hi:[1,0,1]
	v_pk_fma_f32 v[100:101], v[32:33], v[86:87], v[168:169] op_sel_hi:[1,0,1]
	ds_write_b32 v201, v92 offset:4608
	v_pk_mul_f32 v[90:91], v[52:53], v[170:171]
	v_pk_fma_f32 v[90:91], v[54:55], v[172:173], v[90:91]
	v_pk_fma_f32 v[90:91], v[56:57], v[174:175], v[90:91]
	v_pk_fma_f32 v[90:91], v[58:59], v[176:177], v[90:91]
	ds_read_b128 v[52:55], v199 offset:33184
	v_add_f32_e32 v93, v90, v91
	ds_read_b128 v[56:59], v199 offset:33200
	s_waitcnt lgkmcnt(5)
	v_pk_mul_f32 v[88:89], v[44:45], v[94:95]
	ds_read_b128 v[2:5], v199 offset:34496
	v_pk_fma_f32 v[88:89], v[46:47], v[96:97], v[88:89]
	ds_read_b128 v[6:9], v199 offset:34512
	v_pk_fma_f32 v[88:89], v[48:49], v[98:99], v[88:89]
	ds_read_b128 v[34:37], v199 offset:35520
	v_pk_fma_f32 v[88:89], v[50:51], v[100:101], v[88:89]
	ds_read_b128 v[38:41], v199 offset:35536
	v_add_f32_e32 v86, v88, v89
	ds_read_b32 v42, v200 offset:34496
	v_pk_fma_f32 v[162:163], v[76:77], v[84:85], v[94:95] op_sel_hi:[1,0,1]
	v_add_f32_dpp v86, v86, v86 quad_perm:[1,0,3,2] row_mask:0xf bank_mask:0xf bound_ctrl:1
	v_add_f32_dpp v93, v93, v93 quad_perm:[1,0,3,2] row_mask:0xf bank_mask:0xf bound_ctrl:1
	ds_read_b128 v[26:29], v199 offset:35264
	v_add_f32_dpp v86, v86, v86 quad_perm:[2,3,0,1] row_mask:0xf bank_mask:0xf bound_ctrl:1
	v_add_f32_dpp v93, v93, v93 quad_perm:[2,3,0,1] row_mask:0xf bank_mask:0xf bound_ctrl:1
	ds_read_b128 v[30:33], v199 offset:35280
	v_add_f32_dpp v86, v86, v86 row_half_mirror row_mask:0xf bank_mask:0xf bound_ctrl:1
	v_add_f32_dpp v93, v93, v93 row_half_mirror row_mask:0xf bank_mask:0xf bound_ctrl:1
	v_pk_fma_f32 v[164:165], v[78:79], v[84:85], v[96:97] op_sel_hi:[1,0,1]
	v_pk_fma_f32 v[166:167], v[80:81], v[84:85], v[98:99] op_sel_hi:[1,0,1]
	v_pk_fma_f32 v[168:169], v[82:83], v[84:85], v[100:101] op_sel_hi:[1,0,1]
	s_waitcnt lgkmcnt(10)
; template <int CPL>
; DI void scan_block2(CP p, int layer, int s, int d, int hd, int rowhalf, char* smem) {
;     ...
; #pragma unroll 8
;       for (int jj = 0; jj < nst; ++jj) {
;         float4 na[CPL / 4], ny[CPL / 4], nw[CPL / 4], nb[CPL / 4], nk[CPL / 4];
;         float nvv;
;         {
;           const int jn = jj + 1;
;           const float* o = ob + jn * 392 + cg * CPL;
; #pragma unroll
;           for (int i = 0; i < CPL / 4; ++i) {
;             na[i] = *(const float4*)(o + 4 * i); ny[i] = *(const float4*)(o + 64 + 4 * i); nw[i] = *(const float4*)(o + 128 + 4 * i);
;             nb[i] = *(const float4*)(o + 192 + 4 * i); nk[i] = *(const float4*)(o + 256 + 4 * i);
;           }
;           nvv = ob[jn * 392 + 320 + row];
;         }
;         f2 A[NV], Y[NV], W[NV], B[NV], K[NV];
; #pragma unroll
;         for (int i = 0; i < CPL / 4; ++i) {
;           A[2 * i] = mk2(ca[i].x, ca[i].y); A[2 * i + 1] = mk2(ca[i].z, ca[i].w);
;           Y[2 * i] = mk2(cy[i].x, cy[i].y); Y[2 * i + 1] = mk2(cy[i].z, cy[i].w);
;           W[2 * i] = mk2(cw[i].x, cw[i].y); W[2 * i + 1] = mk2(cw[i].z, cw[i].w);
;           B[2 * i] = mk2(cb[i].x, cb[i].y); B[2 * i + 1] = mk2(cb[i].z, cb[i].w);
;           K[2 * i] = mk2(ck[i].x, ck[i].y); K[2 * i + 1] = mk2(ck[i].z, ck[i].w);
;         }
;         const float vv = cvv;
;         f2 pa0 = S[0] * A[0], pa1 = S[1] * A[1];
; #pragma unroll
;         for (int i = 2; i < NV; i += 2) { pa0 = S[i] * A[i] + pa0; pa1 = S[i + 1] * A[i + 1] + pa1; }
;         pa0 = pa0 + pa1;
;         float da = pa0.x + pa0.y;
;         const f2 vvv = mk2(vv, vv);
;         f2 SW[NV];
; #pragma unroll
;         for (int i = 0; i < NV; ++i) SW[i] = S[i] * W[i] + vvv * K[i];
;         da += __int_as_float(__builtin_amdgcn_update_dpp(0, __float_as_int(da), 0xB1, 0xf, 0xf, false));
;         da += __int_as_float(__builtin_amdgcn_update_dpp(0, __float_as_int(da), 0x4E, 0xf, 0xf, false));
;         if (CPL == 8) da += __int_as_float(__builtin_amdgcn_update_dpp(0, __float_as_int(da), 0x141, 0xf, 0xf, false));
;         const f2 dav = mk2(da, da);
; #pragma unroll
;         for (int i = 0; i < NV; ++i) S[i] = dav * B[i] + SW[i];
;         f2 py0 = S[0] * Y[0], py1 = S[1] * Y[1];
; #pragma unroll
;         for (int i = 2; i < NV; i += 2) { py0 = S[i] * Y[i] + py0; py1 = S[i + 1] * Y[i + 1] + py1; }
;         py0 = py0 + py1;
;         float yv = py0.x + py0.y;
	v_pk_fma_f32 v[170:171], v[68:69], v[86:87], v[162:163] op_sel_hi:[1,0,1]
	v_pk_fma_f32 v[172:173], v[70:71], v[86:87], v[164:165] op_sel_hi:[1,0,1]
	v_pk_fma_f32 v[174:175], v[72:73], v[86:87], v[166:167] op_sel_hi:[1,0,1]
	v_pk_fma_f32 v[176:177], v[74:75], v[86:87], v[168:169] op_sel_hi:[1,0,1]
	ds_write_b32 v201, v93 offset:4864
	v_pk_mul_f32 v[90:91], v[10:11], v[94:95]
	v_pk_fma_f32 v[90:91], v[12:13], v[96:97], v[90:91]
	v_pk_fma_f32 v[90:91], v[14:15], v[98:99], v[90:91]
	v_pk_fma_f32 v[90:91], v[16:17], v[100:101], v[90:91]
	ds_read_b128 v[10:13], v199 offset:34752
	v_add_f32_e32 v92, v90, v91
	ds_read_b128 v[14:17], v199 offset:34768
	s_waitcnt lgkmcnt(5)
	v_pk_mul_f32 v[88:89], v[2:3], v[170:171]
	ds_read_b128 v[44:47], v199 offset:36064
	v_pk_fma_f32 v[88:89], v[4:5], v[172:173], v[88:89]
	ds_read_b128 v[48:51], v199 offset:36080
	v_pk_fma_f32 v[88:89], v[6:7], v[174:175], v[88:89]
	ds_read_b128 v[76:79], v199 offset:37088
	v_pk_fma_f32 v[88:89], v[8:9], v[176:177], v[88:89]
	ds_read_b128 v[80:83], v199 offset:37104
	v_add_f32_e32 v86, v88, v89
	ds_read_b32 v84, v200 offset:36064
	v_pk_fma_f32 v[162:163], v[34:35], v[42:43], v[170:171] op_sel_hi:[1,0,1]
	v_add_f32_dpp v86, v86, v86 quad_perm:[1,0,3,2] row_mask:0xf bank_mask:0xf bound_ctrl:1
	v_add_f32_dpp v92, v92, v92 quad_perm:[1,0,3,2] row_mask:0xf bank_mask:0xf bound_ctrl:1
	ds_read_b128 v[68:71], v199 offset:36832
	v_add_f32_dpp v86, v86, v86 quad_perm:[2,3,0,1] row_mask:0xf bank_mask:0xf bound_ctrl:1
	v_add_f32_dpp v92, v92, v92 quad_perm:[2,3,0,1] row_mask:0xf bank_mask:0xf bound_ctrl:1
	ds_read_b128 v[72:75], v199 offset:36848
	v_add_f32_dpp v86, v86, v86 row_half_mirror row_mask:0xf bank_mask:0xf bound_ctrl:1
	v_add_f32_dpp v92, v92, v92 row_half_mirror row_mask:0xf bank_mask:0xf bound_ctrl:1
	v_pk_fma_f32 v[164:165], v[36:37], v[42:43], v[172:173] op_sel_hi:[1,0,1]
	v_pk_fma_f32 v[166:167], v[38:39], v[42:43], v[174:175] op_sel_hi:[1,0,1]
	v_pk_fma_f32 v[168:169], v[40:41], v[42:43], v[176:177] op_sel_hi:[1,0,1]
	s_waitcnt lgkmcnt(10)
	v_pk_fma_f32 v[94:95], v[26:27], v[86:87], v[162:163] op_sel_hi:[1,0,1]
	v_pk_fma_f32 v[96:97], v[28:29], v[86:87], v[164:165] op_sel_hi:[1,0,1]
	v_pk_fma_f32 v[98:99], v[30:31], v[86:87], v[166:167] op_sel_hi:[1,0,1]
	v_pk_fma_f32 v[100:101], v[32:33], v[86:87], v[168:169] op_sel_hi:[1,0,1]
	ds_write_b32 v201, v92 offset:5120
	v_pk_mul_f32 v[90:91], v[52:53], v[170:171]
	v_pk_fma_f32 v[90:91], v[54:55], v[172:173], v[90:91]
	v_pk_fma_f32 v[90:91], v[56:57], v[174:175], v[90:91]
	v_pk_fma_f32 v[90:91], v[58:59], v[176:177], v[90:91]
	ds_read_b128 v[52:55], v199 offset:36320
	v_add_f32_e32 v93, v90, v91
	ds_read_b128 v[56:59], v199 offset:36336
	s_waitcnt lgkmcnt(5)
	v_pk_mul_f32 v[88:89], v[44:45], v[94:95]
	ds_read_b128 v[2:5], v199 offset:37632
	v_pk_fma_f32 v[88:89], v[46:47], v[96:97], v[88:89]
	ds_read_b128 v[6:9], v199 offset:37648
	v_pk_fma_f32 v[88:89], v[48:49], v[98:99], v[88:89]
	ds_read_b128 v[34:37], v199 offset:38656
	v_pk_fma_f32 v[88:89], v[50:51], v[100:101], v[88:89]
	ds_read_b128 v[38:41], v199 offset:38672
	v_add_f32_e32 v86, v88, v89
	ds_read_b32 v42, v200 offset:37632
	ds_read_b128 v[18:21], v199 offset:36576
	ds_read_b128 v[22:25], v199 offset:36592
	v_add_f32_dpp v86, v86, v86 quad_perm:[1,0,3,2] row_mask:0xf bank_mask:0xf bound_ctrl:1
	v_add_f32_dpp v93, v93, v93 quad_perm:[1,0,3,2] row_mask:0xf bank_mask:0xf bound_ctrl:1
	ds_read_b128 v[26:29], v199 offset:38400
	v_add_f32_dpp v86, v86, v86 quad_perm:[2,3,0,1] row_mask:0xf bank_mask:0xf bound_ctrl:1
	v_add_f32_dpp v93, v93, v93 quad_perm:[2,3,0,1] row_mask:0xf bank_mask:0xf bound_ctrl:1
	ds_read_b128 v[30:33], v199 offset:38416
	v_add_f32_dpp v86, v86, v86 row_half_mirror row_mask:0xf bank_mask:0xf bound_ctrl:1
	v_add_f32_dpp v93, v93, v93 row_half_mirror row_mask:0xf bank_mask:0xf bound_ctrl:1
	v_pk_fma_f32 v[162:163], v[76:77], v[84:85], v[94:95] op_sel_hi:[1,0,1]
	v_pk_fma_f32 v[164:165], v[78:79], v[84:85], v[96:97] op_sel_hi:[1,0,1]
	v_pk_fma_f32 v[166:167], v[80:81], v[84:85], v[98:99] op_sel_hi:[1,0,1]
	v_pk_fma_f32 v[168:169], v[82:83], v[84:85], v[100:101] op_sel_hi:[1,0,1]
	s_waitcnt lgkmcnt(12)
	v_pk_fma_f32 v[170:171], v[68:69], v[86:87], v[162:163] op_sel_hi:[1,0,1]
	v_pk_fma_f32 v[172:173], v[70:71], v[86:87], v[164:165] op_sel_hi:[1,0,1]
	v_pk_fma_f32 v[174:175], v[72:73], v[86:87], v[166:167] op_sel_hi:[1,0,1]
	v_pk_fma_f32 v[176:177], v[74:75], v[86:87], v[168:169] op_sel_hi:[1,0,1]
	s_waitcnt lgkmcnt(2)
	v_pk_mul_f32 v[170:171], v[170:171], v[18:19]
	v_pk_mul_f32 v[172:173], v[172:173], v[20:21]
	v_pk_mul_f32 v[174:175], v[174:175], v[22:23]
	v_pk_mul_f32 v[176:177], v[176:177], v[24:25]
	ds_write_b32 v201, v93 offset:5376
	v_pk_mul_f32 v[90:91], v[10:11], v[94:95]
	v_pk_fma_f32 v[90:91], v[12:13], v[96:97], v[90:91]
	v_pk_fma_f32 v[90:91], v[14:15], v[98:99], v[90:91]
	v_pk_fma_f32 v[90:91], v[16:17], v[100:101], v[90:91]
	ds_read_b128 v[10:13], v199 offset:37888
	v_add_f32_e32 v92, v90, v91
	ds_read_b128 v[14:17], v199 offset:37904
	s_waitcnt lgkmcnt(7)
; template <int CPL>
; DI void scan_block2(CP p, int layer, int s, int d, int hd, int rowhalf, char* smem) {
;     ...
; #pragma unroll 8
;       for (int jj = 0; jj < nst; ++jj) {
;         float4 na[CPL / 4], ny[CPL / 4], nw[CPL / 4], nb[CPL / 4], nk[CPL / 4];
;         float nvv;
;         {
;           const int jn = jj + 1;
;           const float* o = ob + jn * 392 + cg * CPL;
; #pragma unroll
;           for (int i = 0; i < CPL / 4; ++i) {
;             na[i] = *(const float4*)(o + 4 * i); ny[i] = *(const float4*)(o + 64 + 4 * i); nw[i] = *(const float4*)(o + 128 + 4 * i);
;             nb[i] = *(const float4*)(o + 192 + 4 * i); nk[i] = *(const float4*)(o + 256 + 4 * i);
;           }
;           nvv = ob[jn * 392 + 320 + row];
;         }
;         f2 A[NV], Y[NV], W[NV], B[NV], K[NV];
; #pragma unroll
;         for (int i = 0; i < CPL / 4; ++i) {
;           A[2 * i] = mk2(ca[i].x, ca[i].y); A[2 * i + 1] = mk2(ca[i].z, ca[i].w);
;           Y[2 * i] = mk2(cy[i].x, cy[i].y); Y[2 * i + 1] = mk2(cy[i].z, cy[i].w);
;           W[2 * i] = mk2(cw[i].x, cw[i].y); W[2 * i + 1] = mk2(cw[i].z, cw[i].w);
;           B[2 * i] = mk2(cb[i].x, cb[i].y); B[2 * i + 1] = mk2(cb[i].z, cb[i].w);
;           K[2 * i] = mk2(ck[i].x, ck[i].y); K[2 * i + 1] = mk2(ck[i].z, ck[i].w);
;         }
;         const float vv = cvv;
;         f2 pa0 = S[0] * A[0], pa1 = S[1] * A[1];
; #pragma unroll
;         for (int i = 2; i < NV; i += 2) { pa0 = S[i] * A[i] + pa0; pa1 = S[i + 1] * A[i + 1] + pa1; }
;         pa0 = pa0 + pa1;
;         float da = pa0.x + pa0.y;
;         const f2 vvv = mk2(vv, vv);
;         f2 SW[NV];
; #pragma unroll
;         for (int i = 0; i < NV; ++i) SW[i] = S[i] * W[i] + vvv * K[i];
;         da += __int_as_float(__builtin_amdgcn_update_dpp(0, __float_as_int(da), 0xB1, 0xf, 0xf, false));
;         da += __int_as_float(__builtin_amdgcn_update_dpp(0, __float_as_int(da), 0x4E, 0xf, 0xf, false));
;         if (CPL == 8) da += __int_as_float(__builtin_amdgcn_update_dpp(0, __float_as_int(da), 0x141, 0xf, 0xf, false));
;         const f2 dav = mk2(da, da);
; #pragma unroll
;         for (int i = 0; i < NV; ++i) S[i] = dav * B[i] + SW[i];
;         f2 py0 = S[0] * Y[0], py1 = S[1] * Y[1];
; #pragma unroll
;         for (int i = 2; i < NV; i += 2) { py0 = S[i] * Y[i] + py0; py1 = S[i + 1] * Y[i + 1] + py1; }
;         py0 = py0 + py1;
;         float yv = py0.x + py0.y;
	v_pk_mul_f32 v[88:89], v[2:3], v[170:171]
	ds_read_b128 v[44:47], v199 offset:39200
	v_pk_fma_f32 v[88:89], v[4:5], v[172:173], v[88:89]
	ds_read_b128 v[48:51], v199 offset:39216
	v_pk_fma_f32 v[88:89], v[6:7], v[174:175], v[88:89]
	ds_read_b128 v[76:79], v199 offset:40224
	v_pk_fma_f32 v[88:89], v[8:9], v[176:177], v[88:89]
	ds_read_b128 v[80:83], v199 offset:40240
	v_add_f32_e32 v86, v88, v89
	ds_read_b32 v84, v200 offset:39200
	v_pk_fma_f32 v[162:163], v[34:35], v[42:43], v[170:171] op_sel_hi:[1,0,1]
	v_add_f32_dpp v86, v86, v86 quad_perm:[1,0,3,2] row_mask:0xf bank_mask:0xf bound_ctrl:1
	v_add_f32_dpp v92, v92, v92 quad_perm:[1,0,3,2] row_mask:0xf bank_mask:0xf bound_ctrl:1
	ds_read_b128 v[68:71], v199 offset:39968
	v_add_f32_dpp v86, v86, v86 quad_perm:[2,3,0,1] row_mask:0xf bank_mask:0xf bound_ctrl:1
	v_add_f32_dpp v92, v92, v92 quad_perm:[2,3,0,1] row_mask:0xf bank_mask:0xf bound_ctrl:1
	ds_read_b128 v[72:75], v199 offset:39984
	v_add_f32_dpp v86, v86, v86 row_half_mirror row_mask:0xf bank_mask:0xf bound_ctrl:1
	v_add_f32_dpp v92, v92, v92 row_half_mirror row_mask:0xf bank_mask:0xf bound_ctrl:1
	v_pk_fma_f32 v[164:165], v[36:37], v[42:43], v[172:173] op_sel_hi:[1,0,1]
	v_pk_fma_f32 v[166:167], v[38:39], v[42:43], v[174:175] op_sel_hi:[1,0,1]
	v_pk_fma_f32 v[168:169], v[40:41], v[42:43], v[176:177] op_sel_hi:[1,0,1]
	s_waitcnt lgkmcnt(10)
	v_pk_fma_f32 v[94:95], v[26:27], v[86:87], v[162:163] op_sel_hi:[1,0,1]
	v_pk_fma_f32 v[96:97], v[28:29], v[86:87], v[164:165] op_sel_hi:[1,0,1]
	v_pk_fma_f32 v[98:99], v[30:31], v[86:87], v[166:167] op_sel_hi:[1,0,1]
	v_pk_fma_f32 v[100:101], v[32:33], v[86:87], v[168:169] op_sel_hi:[1,0,1]
	ds_write_b32 v201, v92 offset:5632
	v_pk_mul_f32 v[90:91], v[52:53], v[170:171]
	v_pk_fma_f32 v[90:91], v[54:55], v[172:173], v[90:91]
	v_pk_fma_f32 v[90:91], v[56:57], v[174:175], v[90:91]
	v_pk_fma_f32 v[90:91], v[58:59], v[176:177], v[90:91]
	ds_read_b128 v[52:55], v199 offset:39456
	v_add_f32_e32 v93, v90, v91
	ds_read_b128 v[56:59], v199 offset:39472
	s_waitcnt lgkmcnt(5)
	v_pk_mul_f32 v[88:89], v[44:45], v[94:95]
	ds_read_b128 v[2:5], v199 offset:40768
	v_pk_fma_f32 v[88:89], v[46:47], v[96:97], v[88:89]
	ds_read_b128 v[6:9], v199 offset:40784
	v_pk_fma_f32 v[88:89], v[48:49], v[98:99], v[88:89]
	ds_read_b128 v[34:37], v199 offset:41792
	v_pk_fma_f32 v[88:89], v[50:51], v[100:101], v[88:89]
	ds_read_b128 v[38:41], v199 offset:41808
	v_add_f32_e32 v86, v88, v89
	ds_read_b32 v42, v200 offset:40768
	v_pk_fma_f32 v[162:163], v[76:77], v[84:85], v[94:95] op_sel_hi:[1,0,1]
	v_add_f32_dpp v86, v86, v86 quad_perm:[1,0,3,2] row_mask:0xf bank_mask:0xf bound_ctrl:1
	v_add_f32_dpp v93, v93, v93 quad_perm:[1,0,3,2] row_mask:0xf bank_mask:0xf bound_ctrl:1
	ds_read_b128 v[26:29], v199 offset:41536
	v_add_f32_dpp v86, v86, v86 quad_perm:[2,3,0,1] row_mask:0xf bank_mask:0xf bound_ctrl:1
	v_add_f32_dpp v93, v93, v93 quad_perm:[2,3,0,1] row_mask:0xf bank_mask:0xf bound_ctrl:1
	ds_read_b128 v[30:33], v199 offset:41552
	v_add_f32_dpp v86, v86, v86 row_half_mirror row_mask:0xf bank_mask:0xf bound_ctrl:1
	v_add_f32_dpp v93, v93, v93 row_half_mirror row_mask:0xf bank_mask:0xf bound_ctrl:1
	v_pk_fma_f32 v[164:165], v[78:79], v[84:85], v[96:97] op_sel_hi:[1,0,1]
	v_pk_fma_f32 v[166:167], v[80:81], v[84:85], v[98:99] op_sel_hi:[1,0,1]
	v_pk_fma_f32 v[168:169], v[82:83], v[84:85], v[100:101] op_sel_hi:[1,0,1]
	s_waitcnt lgkmcnt(10)
	v_pk_fma_f32 v[170:171], v[68:69], v[86:87], v[162:163] op_sel_hi:[1,0,1]
	v_pk_fma_f32 v[172:173], v[70:71], v[86:87], v[164:165] op_sel_hi:[1,0,1]
	v_pk_fma_f32 v[174:175], v[72:73], v[86:87], v[166:167] op_sel_hi:[1,0,1]
	v_pk_fma_f32 v[176:177], v[74:75], v[86:87], v[168:169] op_sel_hi:[1,0,1]
	ds_write_b32 v201, v93 offset:5888
	v_pk_mul_f32 v[90:91], v[10:11], v[94:95]
	v_pk_fma_f32 v[90:91], v[12:13], v[96:97], v[90:91]
	v_pk_fma_f32 v[90:91], v[14:15], v[98:99], v[90:91]
	v_pk_fma_f32 v[90:91], v[16:17], v[100:101], v[90:91]
	ds_read_b128 v[10:13], v199 offset:41024
	v_add_f32_e32 v92, v90, v91
	ds_read_b128 v[14:17], v199 offset:41040
	s_waitcnt lgkmcnt(5)
	v_pk_mul_f32 v[88:89], v[2:3], v[170:171]
	ds_read_b128 v[44:47], v199 offset:42336
	v_pk_fma_f32 v[88:89], v[4:5], v[172:173], v[88:89]
	ds_read_b128 v[48:51], v199 offset:42352
	v_pk_fma_f32 v[88:89], v[6:7], v[174:175], v[88:89]
	ds_read_b128 v[76:79], v199 offset:43360
	v_pk_fma_f32 v[88:89], v[8:9], v[176:177], v[88:89]
	ds_read_b128 v[80:83], v199 offset:43376
	v_add_f32_e32 v86, v88, v89
	ds_read_b32 v84, v200 offset:42336
	v_pk_fma_f32 v[162:163], v[34:35], v[42:43], v[170:171] op_sel_hi:[1,0,1]
	v_add_f32_dpp v86, v86, v86 quad_perm:[1,0,3,2] row_mask:0xf bank_mask:0xf bound_ctrl:1
	v_add_f32_dpp v92, v92, v92 quad_perm:[1,0,3,2] row_mask:0xf bank_mask:0xf bound_ctrl:1
	ds_read_b128 v[68:71], v199 offset:43104
	v_add_f32_dpp v86, v86, v86 quad_perm:[2,3,0,1] row_mask:0xf bank_mask:0xf bound_ctrl:1
	v_add_f32_dpp v92, v92, v92 quad_perm:[2,3,0,1] row_mask:0xf bank_mask:0xf bound_ctrl:1
	ds_read_b128 v[72:75], v199 offset:43120
	v_add_f32_dpp v86, v86, v86 row_half_mirror row_mask:0xf bank_mask:0xf bound_ctrl:1
	v_add_f32_dpp v92, v92, v92 row_half_mirror row_mask:0xf bank_mask:0xf bound_ctrl:1
	v_pk_fma_f32 v[164:165], v[36:37], v[42:43], v[172:173] op_sel_hi:[1,0,1]
	v_pk_fma_f32 v[166:167], v[38:39], v[42:43], v[174:175] op_sel_hi:[1,0,1]
	v_pk_fma_f32 v[168:169], v[40:41], v[42:43], v[176:177] op_sel_hi:[1,0,1]
	s_waitcnt lgkmcnt(10)
; template <int CPL>
; DI void scan_block2(CP p, int layer, int s, int d, int hd, int rowhalf, char* smem) {
;     ...
; #pragma unroll 8
;       for (int jj = 0; jj < nst; ++jj) {
;         float4 na[CPL / 4], ny[CPL / 4], nw[CPL / 4], nb[CPL / 4], nk[CPL / 4];
;         float nvv;
;         {
;           const int jn = jj + 1;
;           const float* o = ob + jn * 392 + cg * CPL;
; #pragma unroll
;           for (int i = 0; i < CPL / 4; ++i) {
;             na[i] = *(const float4*)(o + 4 * i); ny[i] = *(const float4*)(o + 64 + 4 * i); nw[i] = *(const float4*)(o + 128 + 4 * i);
;             nb[i] = *(const float4*)(o + 192 + 4 * i); nk[i] = *(const float4*)(o + 256 + 4 * i);
;           }
;           nvv = ob[jn * 392 + 320 + row];
;         }
;         f2 A[NV], Y[NV], W[NV], B[NV], K[NV];
; #pragma unroll
;         for (int i = 0; i < CPL / 4; ++i) {
;           A[2 * i] = mk2(ca[i].x, ca[i].y); A[2 * i + 1] = mk2(ca[i].z, ca[i].w);
;           Y[2 * i] = mk2(cy[i].x, cy[i].y); Y[2 * i + 1] = mk2(cy[i].z, cy[i].w);
;           W[2 * i] = mk2(cw[i].x, cw[i].y); W[2 * i + 1] = mk2(cw[i].z, cw[i].w);
;           B[2 * i] = mk2(cb[i].x, cb[i].y); B[2 * i + 1] = mk2(cb[i].z, cb[i].w);
;           K[2 * i] = mk2(ck[i].x, ck[i].y); K[2 * i + 1] = mk2(ck[i].z, ck[i].w);
;         }
;         const float vv = cvv;
;         f2 pa0 = S[0] * A[0], pa1 = S[1] * A[1];
; #pragma unroll
;         for (int i = 2; i < NV; i += 2) { pa0 = S[i] * A[i] + pa0; pa1 = S[i + 1] * A[i + 1] + pa1; }
;         pa0 = pa0 + pa1;
;         float da = pa0.x + pa0.y;
;         const f2 vvv = mk2(vv, vv);
;         f2 SW[NV];
; #pragma unroll
;         for (int i = 0; i < NV; ++i) SW[i] = S[i] * W[i] + vvv * K[i];
;         da += __int_as_float(__builtin_amdgcn_update_dpp(0, __float_as_int(da), 0xB1, 0xf, 0xf, false));
;         da += __int_as_float(__builtin_amdgcn_update_dpp(0, __float_as_int(da), 0x4E, 0xf, 0xf, false));
;         if (CPL == 8) da += __int_as_float(__builtin_amdgcn_update_dpp(0, __float_as_int(da), 0x141, 0xf, 0xf, false));
;         const f2 dav = mk2(da, da);
; #pragma unroll
;         for (int i = 0; i < NV; ++i) S[i] = dav * B[i] + SW[i];
;         f2 py0 = S[0] * Y[0], py1 = S[1] * Y[1];
; #pragma unroll
;         for (int i = 2; i < NV; i += 2) { py0 = S[i] * Y[i] + py0; py1 = S[i + 1] * Y[i + 1] + py1; }
;         py0 = py0 + py1;
;         float yv = py0.x + py0.y;
	v_pk_fma_f32 v[94:95], v[26:27], v[86:87], v[162:163] op_sel_hi:[1,0,1]
	v_pk_fma_f32 v[96:97], v[28:29], v[86:87], v[164:165] op_sel_hi:[1,0,1]
	v_pk_fma_f32 v[98:99], v[30:31], v[86:87], v[166:167] op_sel_hi:[1,0,1]
	v_pk_fma_f32 v[100:101], v[32:33], v[86:87], v[168:169] op_sel_hi:[1,0,1]
	ds_write_b32 v201, v92 offset:6144
	v_pk_mul_f32 v[90:91], v[52:53], v[170:171]
	v_pk_fma_f32 v[90:91], v[54:55], v[172:173], v[90:91]
	v_pk_fma_f32 v[90:91], v[56:57], v[174:175], v[90:91]
	v_pk_fma_f32 v[90:91], v[58:59], v[176:177], v[90:91]
	ds_read_b128 v[52:55], v199 offset:42592
	v_add_f32_e32 v93, v90, v91
	ds_read_b128 v[56:59], v199 offset:42608
	s_waitcnt lgkmcnt(5)
	v_pk_mul_f32 v[88:89], v[44:45], v[94:95]
	ds_read_b128 v[2:5], v199 offset:43904
	v_pk_fma_f32 v[88:89], v[46:47], v[96:97], v[88:89]
	ds_read_b128 v[6:9], v199 offset:43920
	v_pk_fma_f32 v[88:89], v[48:49], v[98:99], v[88:89]
	ds_read_b128 v[34:37], v199 offset:44928
	v_pk_fma_f32 v[88:89], v[50:51], v[100:101], v[88:89]
	ds_read_b128 v[38:41], v199 offset:44944
	v_add_f32_e32 v86, v88, v89
	ds_read_b32 v42, v200 offset:43904
	v_pk_fma_f32 v[162:163], v[76:77], v[84:85], v[94:95] op_sel_hi:[1,0,1]
	v_add_f32_dpp v86, v86, v86 quad_perm:[1,0,3,2] row_mask:0xf bank_mask:0xf bound_ctrl:1
	v_add_f32_dpp v93, v93, v93 quad_perm:[1,0,3,2] row_mask:0xf bank_mask:0xf bound_ctrl:1
	ds_read_b128 v[26:29], v199 offset:44672
	v_add_f32_dpp v86, v86, v86 quad_perm:[2,3,0,1] row_mask:0xf bank_mask:0xf bound_ctrl:1
	v_add_f32_dpp v93, v93, v93 quad_perm:[2,3,0,1] row_mask:0xf bank_mask:0xf bound_ctrl:1
	ds_read_b128 v[30:33], v199 offset:44688
	v_add_f32_dpp v86, v86, v86 row_half_mirror row_mask:0xf bank_mask:0xf bound_ctrl:1
	v_add_f32_dpp v93, v93, v93 row_half_mirror row_mask:0xf bank_mask:0xf bound_ctrl:1
	v_pk_fma_f32 v[164:165], v[78:79], v[84:85], v[96:97] op_sel_hi:[1,0,1]
	v_pk_fma_f32 v[166:167], v[80:81], v[84:85], v[98:99] op_sel_hi:[1,0,1]
	v_pk_fma_f32 v[168:169], v[82:83], v[84:85], v[100:101] op_sel_hi:[1,0,1]
	s_waitcnt lgkmcnt(10)
	v_pk_fma_f32 v[170:171], v[68:69], v[86:87], v[162:163] op_sel_hi:[1,0,1]
	v_pk_fma_f32 v[172:173], v[70:71], v[86:87], v[164:165] op_sel_hi:[1,0,1]
	v_pk_fma_f32 v[174:175], v[72:73], v[86:87], v[166:167] op_sel_hi:[1,0,1]
	v_pk_fma_f32 v[176:177], v[74:75], v[86:87], v[168:169] op_sel_hi:[1,0,1]
	ds_write_b32 v201, v93 offset:6400
	v_pk_mul_f32 v[90:91], v[10:11], v[94:95]
	v_pk_fma_f32 v[90:91], v[12:13], v[96:97], v[90:91]
	v_pk_fma_f32 v[90:91], v[14:15], v[98:99], v[90:91]
	v_pk_fma_f32 v[90:91], v[16:17], v[100:101], v[90:91]
	ds_read_b128 v[10:13], v199 offset:44160
	v_add_f32_e32 v92, v90, v91
	ds_read_b128 v[14:17], v199 offset:44176
	s_waitcnt lgkmcnt(5)
	v_pk_mul_f32 v[88:89], v[2:3], v[170:171]
	ds_read_b128 v[44:47], v199 offset:45472
	v_pk_fma_f32 v[88:89], v[4:5], v[172:173], v[88:89]
	ds_read_b128 v[48:51], v199 offset:45488
	v_pk_fma_f32 v[88:89], v[6:7], v[174:175], v[88:89]
	ds_read_b128 v[76:79], v199 offset:46496
	v_pk_fma_f32 v[88:89], v[8:9], v[176:177], v[88:89]
	ds_read_b128 v[80:83], v199 offset:46512
	v_add_f32_e32 v86, v88, v89
	ds_read_b32 v84, v200 offset:45472
	v_pk_fma_f32 v[162:163], v[34:35], v[42:43], v[170:171] op_sel_hi:[1,0,1]
	v_add_f32_dpp v86, v86, v86 quad_perm:[1,0,3,2] row_mask:0xf bank_mask:0xf bound_ctrl:1
	v_add_f32_dpp v92, v92, v92 quad_perm:[1,0,3,2] row_mask:0xf bank_mask:0xf bound_ctrl:1
	ds_read_b128 v[68:71], v199 offset:46240
	v_add_f32_dpp v86, v86, v86 quad_perm:[2,3,0,1] row_mask:0xf bank_mask:0xf bound_ctrl:1
	v_add_f32_dpp v92, v92, v92 quad_perm:[2,3,0,1] row_mask:0xf bank_mask:0xf bound_ctrl:1
	ds_read_b128 v[72:75], v199 offset:46256
	v_add_f32_dpp v86, v86, v86 row_half_mirror row_mask:0xf bank_mask:0xf bound_ctrl:1
	v_add_f32_dpp v92, v92, v92 row_half_mirror row_mask:0xf bank_mask:0xf bound_ctrl:1
	v_pk_fma_f32 v[164:165], v[36:37], v[42:43], v[172:173] op_sel_hi:[1,0,1]
	v_pk_fma_f32 v[166:167], v[38:39], v[42:43], v[174:175] op_sel_hi:[1,0,1]
	v_pk_fma_f32 v[168:169], v[40:41], v[42:43], v[176:177] op_sel_hi:[1,0,1]
	s_waitcnt lgkmcnt(10)
	v_pk_fma_f32 v[94:95], v[26:27], v[86:87], v[162:163] op_sel_hi:[1,0,1]
	v_pk_fma_f32 v[96:97], v[28:29], v[86:87], v[164:165] op_sel_hi:[1,0,1]
	v_pk_fma_f32 v[98:99], v[30:31], v[86:87], v[166:167] op_sel_hi:[1,0,1]
	v_pk_fma_f32 v[100:101], v[32:33], v[86:87], v[168:169] op_sel_hi:[1,0,1]
	ds_write_b32 v201, v92 offset:6656
	v_pk_mul_f32 v[90:91], v[52:53], v[170:171]
	v_pk_fma_f32 v[90:91], v[54:55], v[172:173], v[90:91]
	v_pk_fma_f32 v[90:91], v[56:57], v[174:175], v[90:91]
	v_pk_fma_f32 v[90:91], v[58:59], v[176:177], v[90:91]
	ds_read_b128 v[52:55], v199 offset:45728
	v_add_f32_e32 v93, v90, v91
	ds_read_b128 v[56:59], v199 offset:45744
	s_waitcnt lgkmcnt(5)
	v_pk_mul_f32 v[88:89], v[44:45], v[94:95]
	ds_read_b128 v[2:5], v199 offset:47040
	v_pk_fma_f32 v[88:89], v[46:47], v[96:97], v[88:89]
	ds_read_b128 v[6:9], v199 offset:47056
	v_pk_fma_f32 v[88:89], v[48:49], v[98:99], v[88:89]
	ds_read_b128 v[34:37], v199 offset:48064
	v_pk_fma_f32 v[88:89], v[50:51], v[100:101], v[88:89]
	ds_read_b128 v[38:41], v199 offset:48080
	v_add_f32_e32 v86, v88, v89
	ds_read_b32 v42, v200 offset:47040
	v_pk_fma_f32 v[162:163], v[76:77], v[84:85], v[94:95] op_sel_hi:[1,0,1]
	v_add_f32_dpp v86, v86, v86 quad_perm:[1,0,3,2] row_mask:0xf bank_mask:0xf bound_ctrl:1
	v_add_f32_dpp v93, v93, v93 quad_perm:[1,0,3,2] row_mask:0xf bank_mask:0xf bound_ctrl:1
	ds_read_b128 v[26:29], v199 offset:47808
	v_add_f32_dpp v86, v86, v86 quad_perm:[2,3,0,1] row_mask:0xf bank_mask:0xf bound_ctrl:1
	v_add_f32_dpp v93, v93, v93 quad_perm:[2,3,0,1] row_mask:0xf bank_mask:0xf bound_ctrl:1
	ds_read_b128 v[30:33], v199 offset:47824
	v_add_f32_dpp v86, v86, v86 row_half_mirror row_mask:0xf bank_mask:0xf bound_ctrl:1
	v_add_f32_dpp v93, v93, v93 row_half_mirror row_mask:0xf bank_mask:0xf bound_ctrl:1
	v_pk_fma_f32 v[164:165], v[78:79], v[84:85], v[96:97] op_sel_hi:[1,0,1]
	v_pk_fma_f32 v[166:167], v[80:81], v[84:85], v[98:99] op_sel_hi:[1,0,1]
	v_pk_fma_f32 v[168:169], v[82:83], v[84:85], v[100:101] op_sel_hi:[1,0,1]
	s_waitcnt lgkmcnt(10)
; template <int CPL>
; DI void scan_block2(CP p, int layer, int s, int d, int hd, int rowhalf, char* smem) {
;     ...
; #pragma unroll 8
;       for (int jj = 0; jj < nst; ++jj) {
;         float4 na[CPL / 4], ny[CPL / 4], nw[CPL / 4], nb[CPL / 4], nk[CPL / 4];
;         float nvv;
;         {
;           const int jn = jj + 1;
;           const float* o = ob + jn * 392 + cg * CPL;
; #pragma unroll
;           for (int i = 0; i < CPL / 4; ++i) {
;             na[i] = *(const float4*)(o + 4 * i); ny[i] = *(const float4*)(o + 64 + 4 * i); nw[i] = *(const float4*)(o + 128 + 4 * i);
;             nb[i] = *(const float4*)(o + 192 + 4 * i); nk[i] = *(const float4*)(o + 256 + 4 * i);
;           }
;           nvv = ob[jn * 392 + 320 + row];
;         }
;         f2 A[NV], Y[NV], W[NV], B[NV], K[NV];
; #pragma unroll
;         for (int i = 0; i < CPL / 4; ++i) {
;           A[2 * i] = mk2(ca[i].x, ca[i].y); A[2 * i + 1] = mk2(ca[i].z, ca[i].w);
;           Y[2 * i] = mk2(cy[i].x, cy[i].y); Y[2 * i + 1] = mk2(cy[i].z, cy[i].w);
;           W[2 * i] = mk2(cw[i].x, cw[i].y); W[2 * i + 1] = mk2(cw[i].z, cw[i].w);
;           B[2 * i] = mk2(cb[i].x, cb[i].y); B[2 * i + 1] = mk2(cb[i].z, cb[i].w);
;           K[2 * i] = mk2(ck[i].x, ck[i].y); K[2 * i + 1] = mk2(ck[i].z, ck[i].w);
;         }
;         const float vv = cvv;
;         f2 pa0 = S[0] * A[0], pa1 = S[1] * A[1];
; #pragma unroll
;         for (int i = 2; i < NV; i += 2) { pa0 = S[i] * A[i] + pa0; pa1 = S[i + 1] * A[i + 1] + pa1; }
;         pa0 = pa0 + pa1;
;         float da = pa0.x + pa0.y;
;         const f2 vvv = mk2(vv, vv);
;         f2 SW[NV];
; #pragma unroll
;         for (int i = 0; i < NV; ++i) SW[i] = S[i] * W[i] + vvv * K[i];
;         da += __int_as_float(__builtin_amdgcn_update_dpp(0, __float_as_int(da), 0xB1, 0xf, 0xf, false));
;         da += __int_as_float(__builtin_amdgcn_update_dpp(0, __float_as_int(da), 0x4E, 0xf, 0xf, false));
;         if (CPL == 8) da += __int_as_float(__builtin_amdgcn_update_dpp(0, __float_as_int(da), 0x141, 0xf, 0xf, false));
;         const f2 dav = mk2(da, da);
; #pragma unroll
;         for (int i = 0; i < NV; ++i) S[i] = dav * B[i] + SW[i];
;         f2 py0 = S[0] * Y[0], py1 = S[1] * Y[1];
; #pragma unroll
;         for (int i = 2; i < NV; i += 2) { py0 = S[i] * Y[i] + py0; py1 = S[i + 1] * Y[i + 1] + py1; }
;         py0 = py0 + py1;
;         float yv = py0.x + py0.y;
	v_pk_fma_f32 v[170:171], v[68:69], v[86:87], v[162:163] op_sel_hi:[1,0,1]
	v_pk_fma_f32 v[172:173], v[70:71], v[86:87], v[164:165] op_sel_hi:[1,0,1]
	v_pk_fma_f32 v[174:175], v[72:73], v[86:87], v[166:167] op_sel_hi:[1,0,1]
	v_pk_fma_f32 v[176:177], v[74:75], v[86:87], v[168:169] op_sel_hi:[1,0,1]
	ds_write_b32 v201, v93 offset:6912
	v_pk_mul_f32 v[90:91], v[10:11], v[94:95]
	v_pk_fma_f32 v[90:91], v[12:13], v[96:97], v[90:91]
	v_pk_fma_f32 v[90:91], v[14:15], v[98:99], v[90:91]
	v_pk_fma_f32 v[90:91], v[16:17], v[100:101], v[90:91]
	ds_read_b128 v[10:13], v199 offset:47296
	v_add_f32_e32 v92, v90, v91
	ds_read_b128 v[14:17], v199 offset:47312
	s_waitcnt lgkmcnt(5)
	v_pk_mul_f32 v[88:89], v[2:3], v[170:171]
	ds_read_b128 v[44:47], v199 offset:48608
	v_pk_fma_f32 v[88:89], v[4:5], v[172:173], v[88:89]
	ds_read_b128 v[48:51], v199 offset:48624
	v_pk_fma_f32 v[88:89], v[6:7], v[174:175], v[88:89]
	ds_read_b128 v[76:79], v199 offset:49632
	v_pk_fma_f32 v[88:89], v[8:9], v[176:177], v[88:89]
	ds_read_b128 v[80:83], v199 offset:49648
	v_add_f32_e32 v86, v88, v89
	ds_read_b32 v84, v200 offset:48608
	v_pk_fma_f32 v[162:163], v[34:35], v[42:43], v[170:171] op_sel_hi:[1,0,1]
	v_add_f32_dpp v86, v86, v86 quad_perm:[1,0,3,2] row_mask:0xf bank_mask:0xf bound_ctrl:1
	v_add_f32_dpp v92, v92, v92 quad_perm:[1,0,3,2] row_mask:0xf bank_mask:0xf bound_ctrl:1
	ds_read_b128 v[68:71], v199 offset:49376
	v_add_f32_dpp v86, v86, v86 quad_perm:[2,3,0,1] row_mask:0xf bank_mask:0xf bound_ctrl:1
	v_add_f32_dpp v92, v92, v92 quad_perm:[2,3,0,1] row_mask:0xf bank_mask:0xf bound_ctrl:1
	ds_read_b128 v[72:75], v199 offset:49392
	v_add_f32_dpp v86, v86, v86 row_half_mirror row_mask:0xf bank_mask:0xf bound_ctrl:1
	v_add_f32_dpp v92, v92, v92 row_half_mirror row_mask:0xf bank_mask:0xf bound_ctrl:1
	v_pk_fma_f32 v[164:165], v[36:37], v[42:43], v[172:173] op_sel_hi:[1,0,1]
	v_pk_fma_f32 v[166:167], v[38:39], v[42:43], v[174:175] op_sel_hi:[1,0,1]
	v_pk_fma_f32 v[168:169], v[40:41], v[42:43], v[176:177] op_sel_hi:[1,0,1]
	s_waitcnt lgkmcnt(10)
	v_pk_fma_f32 v[94:95], v[26:27], v[86:87], v[162:163] op_sel_hi:[1,0,1]
	v_pk_fma_f32 v[96:97], v[28:29], v[86:87], v[164:165] op_sel_hi:[1,0,1]
	v_pk_fma_f32 v[98:99], v[30:31], v[86:87], v[166:167] op_sel_hi:[1,0,1]
	v_pk_fma_f32 v[100:101], v[32:33], v[86:87], v[168:169] op_sel_hi:[1,0,1]
	ds_write_b32 v201, v92 offset:7168
	v_pk_mul_f32 v[90:91], v[52:53], v[170:171]
	v_pk_fma_f32 v[90:91], v[54:55], v[172:173], v[90:91]
	v_pk_fma_f32 v[90:91], v[56:57], v[174:175], v[90:91]
	v_pk_fma_f32 v[90:91], v[58:59], v[176:177], v[90:91]
	ds_read_b128 v[52:55], v199 offset:48864
	v_add_f32_e32 v93, v90, v91
	ds_read_b128 v[56:59], v199 offset:48880
	s_waitcnt lgkmcnt(5)
	v_pk_mul_f32 v[88:89], v[44:45], v[94:95]
	ds_read_b128 v[2:5], v199 offset:50176
	v_pk_fma_f32 v[88:89], v[46:47], v[96:97], v[88:89]
	ds_read_b128 v[6:9], v199 offset:50192
	v_pk_fma_f32 v[88:89], v[48:49], v[98:99], v[88:89]
	ds_read_b128 v[34:37], v199 offset:51200
	v_pk_fma_f32 v[88:89], v[50:51], v[100:101], v[88:89]
	ds_read_b128 v[38:41], v199 offset:51216
	v_add_f32_e32 v86, v88, v89
	ds_read_b32 v42, v200 offset:50176
	ds_read_b128 v[18:21], v199 offset:49120
	ds_read_b128 v[22:25], v199 offset:49136
	v_add_f32_dpp v86, v86, v86 quad_perm:[1,0,3,2] row_mask:0xf bank_mask:0xf bound_ctrl:1
	v_add_f32_dpp v93, v93, v93 quad_perm:[1,0,3,2] row_mask:0xf bank_mask:0xf bound_ctrl:1
	ds_read_b128 v[26:29], v199 offset:50944
	v_add_f32_dpp v86, v86, v86 quad_perm:[2,3,0,1] row_mask:0xf bank_mask:0xf bound_ctrl:1
	v_add_f32_dpp v93, v93, v93 quad_perm:[2,3,0,1] row_mask:0xf bank_mask:0xf bound_ctrl:1
	ds_read_b128 v[30:33], v199 offset:50960
	v_add_f32_dpp v86, v86, v86 row_half_mirror row_mask:0xf bank_mask:0xf bound_ctrl:1
	v_add_f32_dpp v93, v93, v93 row_half_mirror row_mask:0xf bank_mask:0xf bound_ctrl:1
	v_pk_fma_f32 v[162:163], v[76:77], v[84:85], v[94:95] op_sel_hi:[1,0,1]
	v_pk_fma_f32 v[164:165], v[78:79], v[84:85], v[96:97] op_sel_hi:[1,0,1]
	v_pk_fma_f32 v[166:167], v[80:81], v[84:85], v[98:99] op_sel_hi:[1,0,1]
	v_pk_fma_f32 v[168:169], v[82:83], v[84:85], v[100:101] op_sel_hi:[1,0,1]
	s_waitcnt lgkmcnt(12)
	v_pk_fma_f32 v[170:171], v[68:69], v[86:87], v[162:163] op_sel_hi:[1,0,1]
	v_pk_fma_f32 v[172:173], v[70:71], v[86:87], v[164:165] op_sel_hi:[1,0,1]
	v_pk_fma_f32 v[174:175], v[72:73], v[86:87], v[166:167] op_sel_hi:[1,0,1]
	v_pk_fma_f32 v[176:177], v[74:75], v[86:87], v[168:169] op_sel_hi:[1,0,1]
	s_waitcnt lgkmcnt(2)
	v_pk_mul_f32 v[170:171], v[170:171], v[18:19]
	v_pk_mul_f32 v[172:173], v[172:173], v[20:21]
	v_pk_mul_f32 v[174:175], v[174:175], v[22:23]
	v_pk_mul_f32 v[176:177], v[176:177], v[24:25]
	ds_write_b32 v201, v93 offset:7424
	v_pk_mul_f32 v[90:91], v[10:11], v[94:95]
	v_pk_fma_f32 v[90:91], v[12:13], v[96:97], v[90:91]
	v_pk_fma_f32 v[90:91], v[14:15], v[98:99], v[90:91]
	v_pk_fma_f32 v[90:91], v[16:17], v[100:101], v[90:91]
	ds_read_b128 v[10:13], v199 offset:50432
	v_add_f32_e32 v92, v90, v91
	ds_read_b128 v[14:17], v199 offset:50448
	v_pk_mul_f32 v[90:91], v[52:53], v[170:171]
	v_add_f32_dpp v92, v92, v92 quad_perm:[1,0,3,2] row_mask:0xf bank_mask:0xf bound_ctrl:1
	v_pk_fma_f32 v[90:91], v[54:55], v[172:173], v[90:91]
	v_pk_fma_f32 v[90:91], v[56:57], v[174:175], v[90:91]
	v_add_f32_dpp v92, v92, v92 quad_perm:[2,3,0,1] row_mask:0xf bank_mask:0xf bound_ctrl:1
	v_pk_fma_f32 v[90:91], v[58:59], v[176:177], v[90:91]
	v_add_f32_e32 v93, v90, v91
	v_add_f32_dpp v92, v92, v92 row_half_mirror row_mask:0xf bank_mask:0xf bound_ctrl:1
	s_nop 0
	v_add_f32_dpp v93, v93, v93 quad_perm:[1,0,3,2] row_mask:0xf bank_mask:0xf bound_ctrl:1
	ds_write_b32 v201, v92 offset:7680
	s_nop 0
	v_add_f32_dpp v93, v93, v93 quad_perm:[2,3,0,1] row_mask:0xf bank_mask:0xf bound_ctrl:1
	s_nop 1
	v_add_f32_dpp v93, v93, v93 row_half_mirror row_mask:0xf bank_mask:0xf bound_ctrl:1
	s_nop 0
	ds_write_b32 v201, v93 offset:7936

; template <int CPL>
; DI void scan_block2(CP p, int layer, int s, int d, int hd, int rowhalf, char* smem) {
;     ...
;     auto load_raw = [&](int c) {
; #pragma unroll
;       for (int u = 0; u < 2; ++u) {
;         const int sj = 8 * sw + 4 * u + (lane >> 4);
;         const int sidc = min(c * 32 + sj, L - 1);
;         const int tok = d == 0 ? sidc : L - 1 - sidc;
;         const u16* base = p.regB + (size_t)(r0 + tok) * 1952 + 4 * q;
;         raw[u][0] = *(const uint2*)(base + aoff0); raw[u][1] = *(const uint2*)(base + aoff1); raw[u][2] = *(const uint2*)(base + aoff2);
;         raw[u][3] = *(const uint2*)(base + aoff3); raw[u][4] = *(const uint2*)(base + aoff4);
;       }
;     };
;     ...
;       for (int u = 0; u < 2; ++u) {
;         const int sj = 8 * sw + 4 * u + (lane >> 4);
;         const float4 w4 = *(const float4*)(OPn + sj * 392 + 128 + 4 * q);
;         const float4 a4 = *(const float4*)(OPn + sj * 392 + 4 * q);
;         const float4 ka = *(const float4*)(CS + 64 + 4 * q);
;         const float4 brk = *(const float4*)(CS + 128 + 4 * q);
;         const float wv4[4] = {w4.x, w4.y, w4.z, w4.w}, av4[4] = {a4.x, a4.y, a4.z, a4.w};
;         const float kav[4] = {ka.x, ka.y, ka.z, ka.w}, bkv[4] = {brk.x, brk.y, brk.z, brk.w};
;         float bb[4], kd[4];
;         float bs = 0.f;
; #pragma unroll
;         for (int e = 0; e < 4; ++e) {
;           bb[e] = -kk4[u][e] * av4[e];
;           kd[e] = k4[u][e] * (1.f + (av4[e] - 1.f) * kav[e]);
;           bs += r4[u][e] * kd[e] * bkv[e];
;         }
;         bs = sum16(bs);
;         float* o = OPn + sj * 392 + 4 * q;
;         *(float4*)(o) = make_float4(kk4[u][0], kk4[u][1], kk4[u][2], kk4[u][3]);
;         *(float4*)(o + 64) = make_float4(r4[u][0], r4[u][1], r4[u][2], r4[u][3]);
;         *(float4*)(o + 128) = w4;
;         *(float4*)(o + 192) = make_float4(bb[0], bb[1], bb[2], bb[3]);
;         *(float4*)(o + 256) = make_float4(kd[0], kd[1], kd[2], kd[3]);
;         *(float4*)(o + 320) = make_float4(v4[u][0], v4[u][1], v4[u][2], v4[u][3]);
;         if (q == 0) {
;           const int sidx = c * 32 + sj;
;           if (sidx < L && rowhalf == 0) { const int tok = d == 0 ? sidx : L - 1 - sidx; p.bsc[((size_t)d * TP + r0 + tok) * 8 + hd] = bs; }
;         }
;       }
.LBB0_194:
	s_or_b64 exec, exec, s[2:3]
	v_min_u32_e32 v0, 0x200f, v47
	v_sub_u32_e32 v3, 0x200f, v0
	v_cndmask_b32_e32 v0, v3, v0, vcc
	v_add_u32_e32 v0, s15, v0
	v_mov_b64_e32 v[4:5], s[66:67]
	v_mad_i64_i32 v[6:7], s[2:3], v0, s88, v[4:5]
	v_lshlrev_b32_e32 v0, 1, v76
	v_lshl_add_u64 v[6:7], v[6:7], 0, v[0:1]
	s_mov_b32 s73, s77
	v_lshl_add_u64 v[8:9], v[6:7], 0, s[76:77]
	v_lshl_add_u64 v[6:7], v[6:7], 0, s[72:73]
	global_load_dwordx2 v[10:11], v[8:9], off
	global_load_dwordx2 v[12:13], v[8:9], off offset:1024
	s_nop 0
	global_load_dwordx2 v[8:9], v[8:9], off offset:2048
	s_nop 0
	global_load_dwordx2 v[14:15], v[6:7], off offset:3072
	s_nop 0
	global_load_dwordx2 v[6:7], v[6:7], off offset:3328
	v_or_b32_e32 v3, 4, v47
	v_min_u32_e32 v3, 0x200f, v3
	v_sub_u32_e32 v16, 0x200f, v3
	v_cndmask_b32_e32 v3, v16, v3, vcc
	v_add_u32_e32 v3, s15, v3
	v_mad_i64_i32 v[4:5], s[2:3], v3, s88, v[4:5]
	v_lshl_add_u64 v[4:5], v[4:5], 0, v[0:1]
	v_lshl_add_u64 v[16:17], v[4:5], 0, s[76:77]
	v_lshl_add_u64 v[4:5], v[4:5], 0, s[72:73]
	global_load_dwordx2 v[32:33], v[16:17], off
	global_load_dwordx2 v[26:27], v[16:17], off offset:1024
	global_load_dwordx2 v[30:31], v[16:17], off offset:2048
	s_nop 0
	global_load_dwordx2 v[16:17], v[4:5], off offset:3072
	global_load_dwordx2 v[42:43], v[4:5], off offset:3328
	s_mov_b64 s[98:99], exec
	s_mov_b64 exec, -1
	v_and_b32_e32 v105, 63, v179
	v_lshlrev_b32_e32 v105, 2, v105
	v_lshrrev_b32_e32 v106, 6, v179
	v_add_u32_e32 v106, -4, v106
	v_mul_u32_u24_e32 v106, 0x3100, v106
	v_mov_b32_e32 v107, 0x0
	v_add3_u32 v105, v105, v106, v107
	s_waitcnt lgkmcnt(0)
	ds_read_b32 v109, v105 offset:256
	ds_read_b32 v110, v105 offset:512
	ds_read_b32 v111, v105 offset:768
	ds_read_b32 v112, v105 offset:1024
	s_waitcnt lgkmcnt(0)
	v_mov_b32_e32 v113, v110
	v_rcp_f32_e32 v114, v113
	v_mul_f32_e32 v109, v109, v113
	v_mul_f32_e32 v111, v111, v114
	v_mul_f32_e32 v112, v112, v114
	ds_write_b32 v105, v109 offset:256
	ds_write_b32 v105, v111 offset:768
	ds_write_b32 v105, v112 offset:1024
	ds_read_b32 v108, v105 offset:1568
	ds_read_b32 v109, v105 offset:1824
	ds_read_b32 v110, v105 offset:2080
	ds_read_b32 v111, v105 offset:2336
	ds_read_b32 v112, v105 offset:2592
	s_waitcnt lgkmcnt(0)
	v_mul_f32_e32 v108, v108, v113
	v_mul_f32_e32 v113, v113, v110
	v_rcp_f32_e32 v114, v113
	v_mul_f32_e32 v109, v109, v113
	v_mul_f32_e32 v111, v111, v114
	v_mul_f32_e32 v112, v112, v114
	ds_write_b32 v105, v108 offset:1568
	ds_write_b32 v105, v109 offset:1824
	ds_write_b32 v105, v113 offset:2080
	ds_write_b32 v105, v111 offset:2336
	ds_write_b32 v105, v112 offset:2592
	ds_read_b32 v108, v105 offset:3136
	ds_read_b32 v109, v105 offset:3392
	ds_read_b32 v110, v105 offset:3648
	ds_read_b32 v111, v105 offset:3904
	ds_read_b32 v112, v105 offset:4160
	s_waitcnt lgkmcnt(0)
	v_mul_f32_e32 v108, v108, v113
	v_mul_f32_e32 v113, v113, v110
	v_rcp_f32_e32 v114, v113
	v_mul_f32_e32 v109, v109, v113
	v_mul_f32_e32 v111, v111, v114
	v_mul_f32_e32 v112, v112, v114
	ds_write_b32 v105, v108 offset:3136
	ds_write_b32 v105, v109 offset:3392
	ds_write_b32 v105, v113 offset:3648
	ds_write_b32 v105, v111 offset:3904
	ds_write_b32 v105, v112 offset:4160
	ds_read_b32 v108, v105 offset:4704
	ds_read_b32 v109, v105 offset:4960
	ds_read_b32 v110, v105 offset:5216
	ds_read_b32 v111, v105 offset:5472
	ds_read_b32 v112, v105 offset:5728
	s_waitcnt lgkmcnt(0)
	v_mul_f32_e32 v108, v108, v113
	v_mul_f32_e32 v113, v113, v110
	v_rcp_f32_e32 v114, v113
	v_mul_f32_e32 v109, v109, v113
	v_mul_f32_e32 v111, v111, v114
	v_mul_f32_e32 v112, v112, v114
	ds_write_b32 v105, v108 offset:4704
	ds_write_b32 v105, v109 offset:4960
	ds_write_b32 v105, v113 offset:5216
	ds_write_b32 v105, v111 offset:5472
	ds_write_b32 v105, v112 offset:5728
	ds_read_b32 v108, v105 offset:6272
	ds_read_b32 v109, v105 offset:6528
	ds_read_b32 v110, v105 offset:6784
	ds_read_b32 v111, v105 offset:7040
	ds_read_b32 v112, v105 offset:7296
	s_waitcnt lgkmcnt(0)
	v_mul_f32_e32 v108, v108, v113
	v_mul_f32_e32 v113, v113, v110
	v_rcp_f32_e32 v114, v113
	v_mul_f32_e32 v109, v109, v113
	v_mul_f32_e32 v111, v111, v114
	v_mul_f32_e32 v112, v112, v114
	ds_write_b32 v105, v108 offset:6272
	ds_write_b32 v105, v109 offset:6528
	ds_write_b32 v105, v113 offset:6784
	ds_write_b32 v105, v111 offset:7040
	ds_write_b32 v105, v112 offset:7296
	ds_read_b32 v108, v105 offset:7840
	ds_read_b32 v109, v105 offset:8096
	ds_read_b32 v110, v105 offset:8352
	ds_read_b32 v111, v105 offset:8608
	ds_read_b32 v112, v105 offset:8864
	s_waitcnt lgkmcnt(0)
	v_mul_f32_e32 v108, v108, v113
	v_mul_f32_e32 v113, v113, v110
	v_rcp_f32_e32 v114, v113
	v_mul_f32_e32 v109, v109, v113
	v_mul_f32_e32 v111, v111, v114
	v_mul_f32_e32 v112, v112, v114
	ds_write_b32 v105, v108 offset:7840
	ds_write_b32 v105, v109 offset:8096
	ds_write_b32 v105, v113 offset:8352
	ds_write_b32 v105, v111 offset:8608
	ds_write_b32 v105, v112 offset:8864
	ds_read_b32 v108, v105 offset:9408
	ds_read_b32 v109, v105 offset:9664
	ds_read_b32 v110, v105 offset:9920
	ds_read_b32 v111, v105 offset:10176
	ds_read_b32 v112, v105 offset:10432
	s_waitcnt lgkmcnt(0)
	v_mul_f32_e32 v108, v108, v113
	v_mul_f32_e32 v113, v113, v110
	v_rcp_f32_e32 v114, v113
	v_mul_f32_e32 v109, v109, v113
	v_mul_f32_e32 v111, v111, v114
	v_mul_f32_e32 v112, v112, v114
	ds_write_b32 v105, v108 offset:9408
	ds_write_b32 v105, v109 offset:9664
	ds_write_b32 v105, v113 offset:9920
	ds_write_b32 v105, v111 offset:10176
	ds_write_b32 v105, v112 offset:10432
	ds_read_b32 v108, v105 offset:10976
	ds_read_b32 v110, v105 offset:11488
	ds_read_b32 v111, v105 offset:11744
	ds_read_b32 v112, v105 offset:12000
	s_waitcnt lgkmcnt(0)
	v_mul_f32_e32 v108, v108, v113
	v_mul_f32_e32 v113, v113, v110
	v_rcp_f32_e32 v114, v113
	s_nop 0
	v_mul_f32_e32 v111, v111, v114
	v_mul_f32_e32 v112, v112, v114
	ds_write_b32 v105, v108 offset:10976
	ds_write_b32 v105, v113 offset:11488
	ds_write_b32 v105, v111 offset:11744
	ds_write_b32 v105, v112 offset:12000
	s_mov_b64 exec, s[98:99]
	s_waitcnt lgkmcnt(0)
	s_barrier
; #define MFMA(a, b, c) __builtin_amdgcn_mfma_f32_32x32x16_bf16((a), (b), (c), 0, 0, 0)
; DI float bflo(unsigned u) { return __uint_as_float(u << 16); }
; DI float bfhi(unsigned u) { return __uint_as_float(u & 0xffff0000u); }
; template <int CPL>
; DI void scan_block2(CP p, int layer, int s, int d, int hd, int rowhalf, char* smem) {
;     ...
;     auto stage = [&](int c) {
;       float r4[2][4], k4[2][4], kk4[2][4], v4[2][4];
; #pragma unroll
;       for (int u = 0; u < 2; ++u) {
;         const int sj = 8 * sw + 4 * u + (lane >> 4);
;         r4[u][0] = bflo(raw[u][0].x); r4[u][1] = bfhi(raw[u][0].x); r4[u][2] = bflo(raw[u][0].y); r4[u][3] = bfhi(raw[u][0].y);
;         k4[u][0] = bflo(raw[u][1].x); k4[u][1] = bfhi(raw[u][1].x); k4[u][2] = bflo(raw[u][1].y); k4[u][3] = bfhi(raw[u][1].y);
;         v4[u][0] = bflo(raw[u][2].x); v4[u][1] = bfhi(raw[u][2].x); v4[u][2] = bflo(raw[u][2].y); v4[u][3] = bfhi(raw[u][2].y);
;         *(uint2*)(XL + sj * 72 + 4 * q) = raw[u][3];
;         *(uint2*)(XL + 32 * 72 + sj * 72 + 4 * q) = raw[u][4];
;         const float4 kkw = *(const float4*)(CS + 4 * q);
;         float x0 = k4[u][0] * kkw.x, x1 = k4[u][1] * kkw.y, x2 = k4[u][2] * kkw.z, x3 = k4[u][3] * kkw.w;
;         float ss = sum16(x0 * x0 + x1 * x1 + x2 * x2 + x3 * x3);
;         float inv = __builtin_amdgcn_rsqf(fmaxf(ss, 1e-24f));
;         kk4[u][0] = x0 * inv; kk4[u][1] = x1 * inv; kk4[u][2] = x2 * inv; kk4[u][3] = x3 * inv;
;       }
;       LDS_FENCE();
;       float* OPn = OP + (c & 1) * 32 * 392;
; #pragma unroll
;       for (int mat = 0; mat < 2; ++mat)
; #pragma unroll
;         for (int nt2 = 0; nt2 < 2; ++nt2) {
;           f32x16 acc;
; #pragma unroll
;           for (int r = 0; r < 16; ++r) acc[r] = 0.f;
;           const u16* xb = XL + mat * 32 * 72 + (8 * sw + (l32 & 7)) * 72 + hh * 8;
; #pragma unroll
;           for (int ks = 0; ks < 4; ++ks) acc = MFMA(*(const bf16x8*)(xb + ks * 16), *(const bf16x8*)(WL + (mat * 64 + nt2 * 32 + l32) * 72 + ks * 16 + hh * 8), acc);
; #pragma unroll
;           for (int r = 0; r < 4; ++r) {
;             float x = acc[r] + bias[mat][nt2];
;             float sg = sigmoidf_(x);
;             float val = mat ? sg : __expf(-0.6065306597126334f * sg);
;             OPn[(8 * sw + 4 * hh + r) * 392 + (mat ? 0 : 128) + nt2 * 32 + l32] = val;
;           }
;         }
	v_lshlrev_b32_e32 v2, 2, v2
	v_mov_b32_e32 v3, v1
	v_lshl_add_u64 v[36:37], s[64:65], 0, v[2:3]
	v_mul_u32_u24_e32 v78, 0x90, v46
	v_add_u32_e32 v79, 0x240, v67
	v_add_u32_e32 v80, 0x240, v68
	v_add_u32_e32 v78, v51, v78
	s_cmp_eq_u32 s16, 0
	s_movk_i32 s2, 0x1ff0
	s_cselect_b64 s[74:75], -1, 0
	v_cmp_gt_u32_e64 s[44:45], s2, v50
	v_cmp_eq_u32_e64 s[40:41], 0, v75
	v_mov_b32_e32 v83, v1
	s_and_b64 s[2:3], s[74:75], s[44:45]
	v_cmp_ne_u32_e64 s[42:43], 0, v75
	s_and_b64 s[10:11], s[40:41], s[2:3]
	s_waitcnt vmcnt(6)
	ds_write_b64 v67, v[14:15]
	s_waitcnt vmcnt(5)
	ds_write_b64 v68, v[6:7]
	ds_read_b128 v[2:5], v69
	v_lshlrev_b32_e32 v48, 16, v12
	v_and_b32_e32 v49, 0xffff0000, v12
	v_lshlrev_b32_e32 v46, 16, v13
	v_and_b32_e32 v47, 0xffff0000, v13
	s_waitcnt lgkmcnt(0)
	v_pk_mul_f32 v[2:3], v[2:3], v[48:49]
	v_pk_mul_f32 v[4:5], v[4:5], v[46:47]
	v_pk_mul_f32 v[6:7], v[2:3], v[2:3]
	v_lshlrev_b32_e32 v18, 16, v8
	v_and_b32_e32 v19, 0xffff0000, v8
	v_lshlrev_b32_e32 v20, 16, v9
	v_and_b32_e32 v21, 0xffff0000, v9
	v_pk_mul_f32 v[8:9], v[4:5], v[4:5]
	v_add_f32_e32 v6, v6, v7
	v_add_f32_e32 v6, v6, v8
	v_add_f32_e32 v6, v6, v9
	s_waitcnt vmcnt(1)
	ds_write_b64 v79, v[16:17]
	s_waitcnt vmcnt(0)
	ds_write_b64 v80, v[42:43]
	v_add_f32_dpp v6, v6, v6 row_ror:8 row_mask:0xf bank_mask:0xf bound_ctrl:1
	v_lshlrev_b32_e32 v40, 16, v26
	v_and_b32_e32 v41, 0xffff0000, v26
	v_add_f32_dpp v6, v6, v6 row_ror:4 row_mask:0xf bank_mask:0xf bound_ctrl:1
	v_lshlrev_b32_e32 v38, 16, v27
	v_and_b32_e32 v39, 0xffff0000, v27
	v_add_f32_dpp v6, v6, v6 row_ror:2 row_mask:0xf bank_mask:0xf bound_ctrl:1
	v_lshlrev_b32_e32 v22, 16, v10
	v_and_b32_e32 v23, 0xffff0000, v10
	v_add_f32_dpp v6, v6, v6 row_ror:1 row_mask:0xf bank_mask:0xf bound_ctrl:1
	v_max_f32_e32 v6, 0x179abe15, v6
	v_rsq_f32_e32 v6, v6
	v_lshlrev_b32_e32 v24, 16, v11
	v_and_b32_e32 v25, 0xffff0000, v11
	v_pk_mul_f32 v[26:27], v[2:3], v[6:7] op_sel_hi:[1,0]
	v_pk_mul_f32 v[28:29], v[4:5], v[6:7] op_sel_hi:[1,0]
	ds_read_b128 v[2:5], v69
	s_waitcnt lgkmcnt(0)
	s_waitcnt lgkmcnt(0)
	v_pk_mul_f32 v[42:43], v[2:3], v[40:41]
	v_pk_mul_f32 v[44:45], v[4:5], v[38:39]
	v_pk_mul_f32 v[2:3], v[42:43], v[42:43]
	v_pk_mul_f32 v[4:5], v[44:45], v[44:45]
	v_add_f32_e32 v2, v2, v3
	v_add_f32_e32 v2, v2, v4
	v_add_f32_e32 v2, v2, v5
	s_nop 1
	v_add_f32_dpp v2, v2, v2 row_ror:8 row_mask:0xf bank_mask:0xf bound_ctrl:1
	s_nop 1
	v_add_f32_dpp v2, v2, v2 row_ror:4 row_mask:0xf bank_mask:0xf bound_ctrl:1
	s_nop 1
	v_add_f32_dpp v82, v2, v2 row_ror:2 row_mask:0xf bank_mask:0xf bound_ctrl:1
	ds_read_b128 v[2:5], v62
	ds_read_b128 v[84:87], v62 offset:32
	ds_read_b128 v[6:9], v78
	ds_read_b128 v[88:91], v78 offset:32
	s_waitcnt lgkmcnt(1)
	v_mfma_f32_32x32x16_bf16 v[2:17], v[2:5], v[6:9], 0
	v_mov_b32_dpp v83, v82 row_ror:1 row_mask:0xf bank_mask:0xf
	s_waitcnt lgkmcnt(0)
	v_mfma_f32_32x32x16_bf16 v[2:17], v[84:87], v[88:91], v[2:17]
	ds_read_b128 v[84:87], v62 offset:64
	ds_read_b128 v[88:91], v78 offset:64
	s_waitcnt lgkmcnt(0)
	v_mfma_f32_32x32x16_bf16 v[2:17], v[84:87], v[88:91], v[2:17]
	ds_read_b128 v[84:87], v62 offset:96
	ds_read_b128 v[88:91], v78 offset:96
	s_waitcnt lgkmcnt(0)
	v_mfma_f32_32x32x16_bf16 v[2:17], v[84:87], v[88:91], v[2:17]
	s_nop 11
	v_add_f32_e32 v2, v64, v2
	v_mul_f32_e32 v2, 0xbfb8aa3b, v2
	v_exp_f32_e32 v2, v2
	s_nop 0
	v_add_f32_e32 v2, 1.0, v2
	v_rcp_f32_e32 v2, v2
	s_nop 0
	v_mul_f32_e32 v2, 0xbf1b4598, v2
	v_mul_f32_e32 v2, 0x3fb8aa3b, v2
	v_exp_f32_e32 v2, v2
	ds_write_b32 v59, v2 offset:50688
	v_add_f32_e32 v2, v64, v3
	v_mul_f32_e32 v2, 0xbfb8aa3b, v2
	v_exp_f32_e32 v2, v2
	s_nop 0
	v_add_f32_e32 v2, 1.0, v2
	v_rcp_f32_e32 v2, v2
	s_nop 0
	v_mul_f32_e32 v2, 0xbf1b4598, v2
	v_mul_f32_e32 v2, 0x3fb8aa3b, v2
	v_exp_f32_e32 v2, v2
	ds_write_b32 v66, v2 offset:51744
	v_add_f32_e32 v2, v64, v4
	v_mul_f32_e32 v2, 0xbfb8aa3b, v2
	v_exp_f32_e32 v2, v2
	s_nop 0
	v_add_f32_e32 v2, 1.0, v2
	v_rcp_f32_e32 v2, v2
	s_nop 0
	v_mul_f32_e32 v2, 0xbf1b4598, v2
	v_mul_f32_e32 v2, 0x3fb8aa3b, v2
	v_exp_f32_e32 v2, v2
	ds_write_b32 v66, v2 offset:53312
	v_add_f32_e32 v2, v64, v5
	v_mul_f32_e32 v2, 0xbfb8aa3b, v2
	v_exp_f32_e32 v2, v2
	s_nop 0
	v_add_f32_e32 v2, 1.0, v2
	v_rcp_f32_e32 v2, v2
	s_nop 0
	v_mul_f32_e32 v2, 0xbf1b4598, v2
	v_mul_f32_e32 v2, 0x3fb8aa3b, v2
	v_exp_f32_e32 v2, v2
	ds_write_b32 v66, v2 offset:54880
	ds_read_b128 v[2:5], v62
	ds_read_b128 v[84:87], v62 offset:32
	ds_read_b128 v[6:9], v78 offset:4608
	ds_read_b128 v[88:91], v78 offset:4640
	s_waitcnt lgkmcnt(1)
	v_mfma_f32_32x32x16_bf16 v[2:17], v[2:5], v[6:9], 0
	s_waitcnt lgkmcnt(0)
	v_mfma_f32_32x32x16_bf16 v[2:17], v[84:87], v[88:91], v[2:17]
	ds_read_b128 v[84:87], v62 offset:64
	ds_read_b128 v[88:91], v78 offset:4672
	s_waitcnt lgkmcnt(0)
	v_mfma_f32_32x32x16_bf16 v[2:17], v[84:87], v[88:91], v[2:17]
	ds_read_b128 v[84:87], v62 offset:96
	ds_read_b128 v[88:91], v78 offset:4704
	s_waitcnt lgkmcnt(0)
; template <int CPL>
; DI void scan_block2(CP p, int layer, int s, int d, int hd, int rowhalf, char* smem) {
;     ...
; #pragma unroll
;       for (int mat = 0; mat < 2; ++mat)
; #pragma unroll
;         for (int nt2 = 0; nt2 < 2; ++nt2) {
;           f32x16 acc;
; #pragma unroll
;           for (int r = 0; r < 16; ++r) acc[r] = 0.f;
;           const u16* xb = XL + mat * 32 * 72 + (8 * sw + (l32 & 7)) * 72 + hh * 8;
; #pragma unroll
;           for (int ks = 0; ks < 4; ++ks) acc = MFMA(*(const bf16x8*)(xb + ks * 16), *(const bf16x8*)(WL + (mat * 64 + nt2 * 32 + l32) * 72 + ks * 16 + hh * 8), acc);
; #pragma unroll
;           for (int r = 0; r < 4; ++r) {
;             float x = acc[r] + bias[mat][nt2];
;             float sg = sigmoidf_(x);
;             float val = mat ? sg : __expf(-0.6065306597126334f * sg);
;             OPn[(8 * sw + 4 * hh + r) * 392 + (mat ? 0 : 128) + nt2 * 32 + l32] = val;
;           }
;         }
;       LDS_FENCE();
; #pragma unroll
;       for (int u = 0; u < 2; ++u) {
;         const int sj = 8 * sw + 4 * u + (lane >> 4);
;         const float4 w4 = *(const float4*)(OPn + sj * 392 + 128 + 4 * q);
;         const float4 a4 = *(const float4*)(OPn + sj * 392 + 4 * q);
;         const float4 ka = *(const float4*)(CS + 64 + 4 * q);
;         const float4 brk = *(const float4*)(CS + 128 + 4 * q);
;         const float wv4[4] = {w4.x, w4.y, w4.z, w4.w}, av4[4] = {a4.x, a4.y, a4.z, a4.w};
;         const float kav[4] = {ka.x, ka.y, ka.z, ka.w}, bkv[4] = {brk.x, brk.y, brk.z, brk.w};
;         float bb[4], kd[4];
;         float bs = 0.f;
; #pragma unroll
;         for (int e = 0; e < 4; ++e) {
;           bb[e] = -kk4[u][e] * av4[e];
;           kd[e] = k4[u][e] * (1.f + (av4[e] - 1.f) * kav[e]);
;           bs += r4[u][e] * kd[e] * bkv[e];
;         }
;         bs = sum16(bs);
;         float* o = OPn + sj * 392 + 4 * q;
;         *(float4*)(o) = make_float4(kk4[u][0], kk4[u][1], kk4[u][2], kk4[u][3]);
;         *(float4*)(o + 64) = make_float4(r4[u][0], r4[u][1], r4[u][2], r4[u][3]);
;         *(float4*)(o + 128) = w4;
;         *(float4*)(o + 192) = make_float4(bb[0], bb[1], bb[2], bb[3]);
;         *(float4*)(o + 256) = make_float4(kd[0], kd[1], kd[2], kd[3]);
;         *(float4*)(o + 320) = make_float4(v4[u][0], v4[u][1], v4[u][2], v4[u][3]);
;         if (q == 0) {
;           const int sidx = c * 32 + sj;
	v_mfma_f32_32x32x16_bf16 v[2:17], v[84:87], v[88:91], v[2:17]
	s_nop 11
	v_add_f32_e32 v2, v63, v2
	v_mul_f32_e32 v2, 0xbfb8aa3b, v2
	v_exp_f32_e32 v2, v2
	s_nop 0
	v_add_f32_e32 v2, 1.0, v2
	v_rcp_f32_e32 v2, v2
	s_nop 0
	v_mul_f32_e32 v2, 0xbf1b4598, v2
	v_mul_f32_e32 v2, 0x3fb8aa3b, v2
	v_exp_f32_e32 v2, v2
	ds_write_b32 v59, v2 offset:50816
	v_add_f32_e32 v2, v63, v3
	v_mul_f32_e32 v2, 0xbfb8aa3b, v2
	v_exp_f32_e32 v2, v2
	s_nop 0
	v_add_f32_e32 v2, 1.0, v2
	v_rcp_f32_e32 v2, v2
	s_nop 0
	v_mul_f32_e32 v2, 0xbf1b4598, v2
	v_mul_f32_e32 v2, 0x3fb8aa3b, v2
	v_exp_f32_e32 v2, v2
	ds_write_b32 v65, v2 offset:51744
	v_add_f32_e32 v2, v63, v4
	v_mul_f32_e32 v2, 0xbfb8aa3b, v2
	v_exp_f32_e32 v2, v2
	s_nop 0
	v_add_f32_e32 v2, 1.0, v2
	v_rcp_f32_e32 v2, v2
	s_nop 0
	v_mul_f32_e32 v2, 0xbf1b4598, v2
	v_mul_f32_e32 v2, 0x3fb8aa3b, v2
	v_exp_f32_e32 v2, v2
	ds_write_b32 v65, v2 offset:53312
	v_add_f32_e32 v2, v63, v5
	v_mul_f32_e32 v2, 0xbfb8aa3b, v2
	v_exp_f32_e32 v2, v2
	s_nop 0
	v_add_f32_e32 v2, 1.0, v2
	v_rcp_f32_e32 v2, v2
	s_nop 0
	v_mul_f32_e32 v2, 0xbf1b4598, v2
	v_mul_f32_e32 v2, 0x3fb8aa3b, v2
	v_exp_f32_e32 v2, v2
	ds_write_b32 v65, v2 offset:54880
	ds_read_b128 v[2:5], v62 offset:4608
	ds_read_b128 v[84:87], v62 offset:4640
	ds_read_b128 v[6:9], v78 offset:9216
	ds_read_b128 v[88:91], v78 offset:9248
	s_waitcnt lgkmcnt(1)
	v_mfma_f32_32x32x16_bf16 v[2:17], v[2:5], v[6:9], 0
	s_waitcnt lgkmcnt(0)
	v_mfma_f32_32x32x16_bf16 v[2:17], v[84:87], v[88:91], v[2:17]
	ds_read_b128 v[84:87], v62 offset:4672
	ds_read_b128 v[88:91], v78 offset:9280
	s_waitcnt lgkmcnt(0)
	v_mfma_f32_32x32x16_bf16 v[2:17], v[84:87], v[88:91], v[2:17]
	ds_read_b128 v[84:87], v62 offset:4704
	ds_read_b128 v[88:91], v78 offset:9312
	s_waitcnt lgkmcnt(0)
	v_mfma_f32_32x32x16_bf16 v[2:17], v[84:87], v[88:91], v[2:17]
	s_nop 11
	v_add_f32_e32 v2, v56, v2
	v_mul_f32_e32 v2, 0xbfb8aa3b, v2
	v_exp_f32_e32 v2, v2
	s_nop 0
	v_add_f32_e32 v2, 1.0, v2
	v_rcp_f32_e32 v2, v2
	ds_write_b32 v59, v2 offset:50176
	v_add_f32_e32 v2, v56, v3
	v_mul_f32_e32 v2, 0xbfb8aa3b, v2
	v_exp_f32_e32 v2, v2
	s_nop 0
	v_add_f32_e32 v2, 1.0, v2
	v_rcp_f32_e32 v2, v2
	ds_write_b32 v59, v2 offset:51744
	v_add_f32_e32 v2, v56, v4
	v_mul_f32_e32 v2, 0xbfb8aa3b, v2
	v_exp_f32_e32 v2, v2
	s_nop 0
	v_add_f32_e32 v2, 1.0, v2
	v_rcp_f32_e32 v2, v2
	ds_write_b32 v59, v2 offset:53312
	v_add_f32_e32 v2, v56, v5
	v_mul_f32_e32 v2, 0xbfb8aa3b, v2
	v_exp_f32_e32 v2, v2
	s_nop 0
	v_add_f32_e32 v2, 1.0, v2
	v_rcp_f32_e32 v2, v2
	ds_write_b32 v59, v2 offset:54880
	ds_read_b128 v[2:5], v62 offset:4608
	ds_read_b128 v[84:87], v62 offset:4640
	ds_read_b128 v[6:9], v78 offset:13824
	ds_read_b128 v[88:91], v78 offset:13856
	s_waitcnt lgkmcnt(1)
	v_mfma_f32_32x32x16_bf16 v[2:17], v[2:5], v[6:9], 0
	s_waitcnt lgkmcnt(0)
	v_mfma_f32_32x32x16_bf16 v[2:17], v[84:87], v[88:91], v[2:17]
	ds_read_b128 v[84:87], v62 offset:4672
	ds_read_b128 v[88:91], v78 offset:13888
	s_waitcnt lgkmcnt(0)
	v_mfma_f32_32x32x16_bf16 v[2:17], v[84:87], v[88:91], v[2:17]
	ds_read_b128 v[84:87], v62 offset:4704
	ds_read_b128 v[88:91], v78 offset:13920
	s_waitcnt lgkmcnt(0)
	v_mfma_f32_32x32x16_bf16 v[2:17], v[84:87], v[88:91], v[2:17]
	s_nop 11
	v_add_f32_e32 v2, v55, v2
	v_mul_f32_e32 v2, 0xbfb8aa3b, v2
	v_exp_f32_e32 v2, v2
	s_nop 0
	v_add_f32_e32 v2, 1.0, v2
	v_rcp_f32_e32 v2, v2
	ds_write_b32 v59, v2 offset:50304
	v_add_f32_e32 v2, v55, v3
	v_mul_f32_e32 v2, 0xbfb8aa3b, v2
	v_exp_f32_e32 v2, v2
	s_nop 0
	v_add_f32_e32 v2, 1.0, v2
	v_rcp_f32_e32 v2, v2
	ds_write_b32 v60, v2 offset:51744
	v_add_f32_e32 v2, v55, v4
	v_mul_f32_e32 v2, 0xbfb8aa3b, v2
	v_exp_f32_e32 v2, v2
	s_nop 0
	v_add_f32_e32 v2, 1.0, v2
	v_rcp_f32_e32 v2, v2
	ds_write_b32 v60, v2 offset:53312
	v_add_f32_e32 v2, v55, v5
	v_mul_f32_e32 v2, 0xbfb8aa3b, v2
	v_exp_f32_e32 v2, v2
	s_nop 0
	v_add_f32_e32 v2, 1.0, v2
	v_rcp_f32_e32 v2, v2
	ds_write_b32 v60, v2 offset:54880
	s_waitcnt lgkmcnt(0)
	ds_read_b128 v[2:5], v61
	ds_read_b128 v[10:13], v57 offset:50176
	ds_write_b128 v57, v[22:25] offset:50432
	s_waitcnt lgkmcnt(1)
	v_pk_mul_f32 v[6:7], v[10:11], v[26:27] neg_lo:[0,1] neg_hi:[0,1]
	v_pk_mul_f32 v[8:9], v[12:13], v[28:29] neg_lo:[0,1] neg_hi:[0,1]
	ds_write_b128 v57, v[26:29] offset:50176
	ds_write_b128 v57, v[6:9] offset:50944
	ds_read_b128 v[6:9], v58
	v_pk_add_f32 v[10:11], v[10:11], -1.0 op_sel_hi:[1,0]
	v_pk_add_f32 v[12:13], v[12:13], -1.0 op_sel_hi:[1,0]
	s_waitcnt lgkmcnt(0)
	v_pk_fma_f32 v[10:11], v[10:11], v[6:7], 1.0 op_sel_hi:[1,1,0]
	s_nop 0
	v_pk_mul_f32 v[10:11], v[10:11], v[48:49]
	v_pk_fma_f32 v[12:13], v[12:13], v[8:9], 1.0 op_sel_hi:[1,1,0]
	v_mul_f32_e32 v14, v10, v22
	v_fma_f32 v14, v2, v14, 0
	v_mul_f32_e32 v15, v11, v23
	v_pk_mul_f32 v[12:13], v[12:13], v[46:47]
	v_fmac_f32_e32 v14, v3, v15
	v_mul_f32_e32 v15, v12, v24
	v_mul_f32_e32 v16, v13, v25
	v_fmac_f32_e32 v14, v4, v15
	v_fmac_f32_e32 v14, v5, v16
	v_mov_b32_e32 v15, v1
	ds_write_b128 v57, v[10:13] offset:51200
	ds_write_b128 v57, v[18:21] offset:51456
	v_add_f32_dpp v14, v14, v14 row_ror:8 row_mask:0xf bank_mask:0xf bound_ctrl:1
	s_nop 1
	v_add_f32_dpp v14, v14, v14 row_ror:4 row_mask:0xf bank_mask:0xf bound_ctrl:1
	s_nop 1
	v_add_f32_dpp v14, v14, v14 row_ror:2 row_mask:0xf bank_mask:0xf bound_ctrl:1
	s_nop 1
	v_mov_b32_dpp v15, v14 row_ror:1 row_mask:0xf bank_mask:0xf
	s_and_saveexec_b64 s[2:3], s[10:11]
	s_cbranch_execz .LBB0_196
	v_add_u32_e32 v10, 32, v54
	v_sub_u32_e32 v11, 0x1fef, v54
	v_cndmask_b32_e32 v10, v11, v10, vcc
	v_mov_b32_e32 v11, v1
	v_lshl_add_u64 v[10:11], v[34:35], 0, v[10:11]
	v_lshlrev_b64 v[10:11], 5, v[10:11]
	v_add_f32_e32 v12, v14, v15
	v_lshl_add_u64 v[10:11], v[36:37], 0, v[10:11]
	global_store_dword v[10:11], v12, off

; template <int CPL>
; DI void scan_block2(CP p, int layer, int s, int d, int hd, int rowhalf, char* smem) {
;     ...
;     auto load_raw = [&](int c) {
; #pragma unroll
;       for (int u = 0; u < 2; ++u) {
;         const int sj = 8 * sw + 4 * u + (lane >> 4);
;         const int sidc = min(c * 32 + sj, L - 1);
;         const int tok = d == 0 ? sidc : L - 1 - sidc;
;         const u16* base = p.regB + (size_t)(r0 + tok) * 1952 + 4 * q;
;         raw[u][0] = *(const uint2*)(base + aoff0); raw[u][1] = *(const uint2*)(base + aoff1); raw[u][2] = *(const uint2*)(base + aoff2);
;         raw[u][3] = *(const uint2*)(base + aoff3); raw[u][4] = *(const uint2*)(base + aoff4);
;       }
;     };
;     ...
;     load_raw(0);
;     stage(0);
;     if (nch > 1) load_raw(1);
;     __syncthreads();
.LBB0_198:
	s_or_b64 exec, exec, s[2:3]
	v_min_u32_e32 v2, 0x1fcf, v54
	v_add_u32_e32 v3, 64, v2
	v_sub_u32_e32 v2, 0x1fcf, v2
	v_cndmask_b32_e32 v2, v2, v3, vcc
	v_lshl_add_u64 v[44:45], s[66:67], 0, v[0:1]
	v_add_u32_e32 v2, s15, v2
	v_mad_i64_i32 v[2:3], s[2:3], v2, s88, v[44:45]
	v_lshl_add_u64 v[4:5], v[2:3], 0, s[76:77]
	s_mov_b32 s73, s77
	v_lshl_add_u64 v[2:3], v[2:3], 0, s[72:73]
	global_load_dwordx2 v[28:29], v[4:5], off
	global_load_dwordx2 v[50:51], v[4:5], off offset:1024
	global_load_dwordx2 v[48:49], v[4:5], off offset:2048
	global_load_dwordx2 v[6:7], v[2:3], off offset:3072
	v_min_u32_e32 v4, 0x1fcb, v54
	v_add_u32_e32 v5, 0x44, v4
	v_sub_u32_e32 v4, 0x1fcb, v4
	v_cndmask_b32_e32 v4, v4, v5, vcc
	v_add_u32_e32 v4, s15, v4
	v_mad_i64_i32 v[4:5], s[2:3], v4, s88, v[44:45]
	v_lshl_add_u64 v[10:11], v[4:5], 0, s[76:77]
	global_load_dwordx2 v[8:9], v[2:3], off offset:3328
	global_load_dwordx2 v[42:43], v[10:11], off
	global_load_dwordx2 v[46:47], v[10:11], off offset:1024
	global_load_dwordx2 v[40:41], v[10:11], off offset:2048
	v_lshl_add_u64 v[2:3], v[4:5], 0, s[72:73]
	global_load_dwordx2 v[4:5], v[2:3], off offset:3072
	s_nop 0
	global_load_dwordx2 v[2:3], v[2:3], off offset:3328
	s_lshl_b32 s2, s14, 1
	s_add_u32 s2, s78, s2
	s_addc_u32 s3, s79, 0
	s_add_u32 s2, s2, s76
	v_lshrrev_b32_e32 v10, 3, v75
	s_addc_u32 s3, s3, 0
	v_add_u32_e32 v83, v53, v52
	v_cmp_eq_u32_e64 s[44:45], s16, v10
	v_lshlrev_b32_e32 v82, 6, v54
	v_lshl_add_u64 v[38:39], s[2:3], 0, v[0:1]
	v_lshlrev_b32_e32 v75, 6, v77
	v_sub_u32_e32 v84, 0x1feb, v83
	s_mov_b32 s17, 0
	s_mov_b32 s16, 0
	s_mov_b64 s[98:99], exec
	s_mov_b64 exec, -1
	v_and_b32_e32 v105, 63, v179
	v_lshlrev_b32_e32 v105, 2, v105
	v_lshrrev_b32_e32 v106, 6, v179
	v_add_u32_e32 v106, -4, v106
	v_mul_u32_u24_e32 v106, 0x3100, v106
	v_mov_b32_e32 v107, 0xc400
	v_add3_u32 v105, v105, v106, v107
	s_waitcnt lgkmcnt(0)
	ds_read_b32 v109, v105 offset:256
	ds_read_b32 v110, v105 offset:512
	ds_read_b32 v111, v105 offset:768
	ds_read_b32 v112, v105 offset:1024
	s_waitcnt lgkmcnt(0)
	v_mov_b32_e32 v113, v110
	v_rcp_f32_e32 v114, v113
	v_mul_f32_e32 v109, v109, v113
	v_mul_f32_e32 v111, v111, v114
	v_mul_f32_e32 v112, v112, v114
	ds_write_b32 v105, v109 offset:256
	ds_write_b32 v105, v111 offset:768
	ds_write_b32 v105, v112 offset:1024
	ds_read_b32 v108, v105 offset:1568
	ds_read_b32 v109, v105 offset:1824
	ds_read_b32 v110, v105 offset:2080
	ds_read_b32 v111, v105 offset:2336
	ds_read_b32 v112, v105 offset:2592
	s_waitcnt lgkmcnt(0)
	v_mul_f32_e32 v108, v108, v113
	v_mul_f32_e32 v113, v113, v110
	v_rcp_f32_e32 v114, v113
	v_mul_f32_e32 v109, v109, v113
	v_mul_f32_e32 v111, v111, v114
	v_mul_f32_e32 v112, v112, v114
	ds_write_b32 v105, v108 offset:1568
	ds_write_b32 v105, v109 offset:1824
	ds_write_b32 v105, v113 offset:2080
	ds_write_b32 v105, v111 offset:2336
	ds_write_b32 v105, v112 offset:2592
	ds_read_b32 v108, v105 offset:3136
	ds_read_b32 v109, v105 offset:3392
	ds_read_b32 v110, v105 offset:3648
	ds_read_b32 v111, v105 offset:3904
	ds_read_b32 v112, v105 offset:4160
	s_waitcnt lgkmcnt(0)
	v_mul_f32_e32 v108, v108, v113
	v_mul_f32_e32 v113, v113, v110
	v_rcp_f32_e32 v114, v113
	v_mul_f32_e32 v109, v109, v113
	v_mul_f32_e32 v111, v111, v114
	v_mul_f32_e32 v112, v112, v114
	ds_write_b32 v105, v108 offset:3136
	ds_write_b32 v105, v109 offset:3392
	ds_write_b32 v105, v113 offset:3648
	ds_write_b32 v105, v111 offset:3904
	ds_write_b32 v105, v112 offset:4160
	ds_read_b32 v108, v105 offset:4704
	ds_read_b32 v109, v105 offset:4960
	ds_read_b32 v110, v105 offset:5216
	ds_read_b32 v111, v105 offset:5472
	ds_read_b32 v112, v105 offset:5728
	s_waitcnt lgkmcnt(0)
	v_mul_f32_e32 v108, v108, v113
	v_mul_f32_e32 v113, v113, v110
	v_rcp_f32_e32 v114, v113
	v_mul_f32_e32 v109, v109, v113
	v_mul_f32_e32 v111, v111, v114
	v_mul_f32_e32 v112, v112, v114
	ds_write_b32 v105, v108 offset:4704
	ds_write_b32 v105, v109 offset:4960
	ds_write_b32 v105, v113 offset:5216
	ds_write_b32 v105, v111 offset:5472
	ds_write_b32 v105, v112 offset:5728
	ds_read_b32 v108, v105 offset:6272
	ds_read_b32 v109, v105 offset:6528
	ds_read_b32 v110, v105 offset:6784
	ds_read_b32 v111, v105 offset:7040
	ds_read_b32 v112, v105 offset:7296
	s_waitcnt lgkmcnt(0)
	v_mul_f32_e32 v108, v108, v113
	v_mul_f32_e32 v113, v113, v110
	v_rcp_f32_e32 v114, v113
	v_mul_f32_e32 v109, v109, v113
	v_mul_f32_e32 v111, v111, v114
	v_mul_f32_e32 v112, v112, v114
	ds_write_b32 v105, v108 offset:6272
	ds_write_b32 v105, v109 offset:6528
	ds_write_b32 v105, v113 offset:6784
	ds_write_b32 v105, v111 offset:7040
	ds_write_b32 v105, v112 offset:7296
	ds_read_b32 v108, v105 offset:7840
	ds_read_b32 v109, v105 offset:8096
	ds_read_b32 v110, v105 offset:8352
	ds_read_b32 v111, v105 offset:8608
	ds_read_b32 v112, v105 offset:8864
	s_waitcnt lgkmcnt(0)
	v_mul_f32_e32 v108, v108, v113
	v_mul_f32_e32 v113, v113, v110
	v_rcp_f32_e32 v114, v113
	v_mul_f32_e32 v109, v109, v113
	v_mul_f32_e32 v111, v111, v114
	v_mul_f32_e32 v112, v112, v114
	ds_write_b32 v105, v108 offset:7840
	ds_write_b32 v105, v109 offset:8096
	ds_write_b32 v105, v113 offset:8352
	ds_write_b32 v105, v111 offset:8608
	ds_write_b32 v105, v112 offset:8864
	ds_read_b32 v108, v105 offset:9408
	ds_read_b32 v109, v105 offset:9664
	ds_read_b32 v110, v105 offset:9920
	ds_read_b32 v111, v105 offset:10176
	ds_read_b32 v112, v105 offset:10432
	s_waitcnt lgkmcnt(0)
	v_mul_f32_e32 v108, v108, v113
	v_mul_f32_e32 v113, v113, v110
	v_rcp_f32_e32 v114, v113
	v_mul_f32_e32 v109, v109, v113
	v_mul_f32_e32 v111, v111, v114
	v_mul_f32_e32 v112, v112, v114
	ds_write_b32 v105, v108 offset:9408
	ds_write_b32 v105, v109 offset:9664
	ds_write_b32 v105, v113 offset:9920
	ds_write_b32 v105, v111 offset:10176
	ds_write_b32 v105, v112 offset:10432
	ds_read_b32 v108, v105 offset:10976
	ds_read_b32 v110, v105 offset:11488
	ds_read_b32 v111, v105 offset:11744
	ds_read_b32 v112, v105 offset:12000
	s_waitcnt lgkmcnt(0)
	v_mul_f32_e32 v108, v108, v113
	v_mul_f32_e32 v113, v113, v110
	v_rcp_f32_e32 v114, v113
	s_nop 0
	v_mul_f32_e32 v111, v111, v114
	v_mul_f32_e32 v112, v112, v114
	ds_write_b32 v105, v108 offset:10976
	ds_write_b32 v105, v113 offset:11488
	ds_write_b32 v105, v111 offset:11744
	ds_write_b32 v105, v112 offset:12000
	s_mov_b64 exec, s[98:99]
	s_waitcnt lgkmcnt(0)
	s_barrier
	s_branch .LBB0_200
; template <int CPL>
; DI void scan_block2(CP p, int layer, int s, int d, int hd, int rowhalf, char* smem) {
;     ...
;     for (int c = 0; c < nch; ++c) {
;       if (c + 1 < nch) { stage(c + 1); if (c + 2 < nch) load_raw(c + 2); }
;       if (c >= 1) writeout(c - 1);
;       __syncthreads();
;     }
.LBB0_199:
	s_or_b64 exec, exec, s[2:3]
	s_mov_b64 s[98:99], exec
	s_mov_b64 exec, -1
	v_and_b32_e32 v105, 63, v179
	v_lshlrev_b32_e32 v105, 2, v105
	v_lshrrev_b32_e32 v106, 6, v179
	v_add_u32_e32 v106, -4, v106
	v_mul_u32_u24_e32 v106, 0x3100, v106
	v_mov_b32_e32 v107, 32
	v_and_b32_e32 v107, s16, v107
	v_mul_u32_u24_e32 v107, 0x620, v107
	v_add3_u32 v105, v105, v106, v107
	s_waitcnt lgkmcnt(0)
	ds_read_b32 v109, v105 offset:256
	ds_read_b32 v110, v105 offset:512
	ds_read_b32 v111, v105 offset:768
	ds_read_b32 v112, v105 offset:1024
	s_waitcnt lgkmcnt(0)
	v_mov_b32_e32 v113, v110
	v_rcp_f32_e32 v114, v113
	v_mul_f32_e32 v109, v109, v113
	v_mul_f32_e32 v111, v111, v114
	v_mul_f32_e32 v112, v112, v114
	ds_write_b32 v105, v109 offset:256
	ds_write_b32 v105, v111 offset:768
	ds_write_b32 v105, v112 offset:1024
	ds_read_b32 v108, v105 offset:1568
	ds_read_b32 v109, v105 offset:1824
	ds_read_b32 v110, v105 offset:2080
	ds_read_b32 v111, v105 offset:2336
	ds_read_b32 v112, v105 offset:2592
	s_waitcnt lgkmcnt(0)
	v_mul_f32_e32 v108, v108, v113
	v_mul_f32_e32 v113, v113, v110
	v_rcp_f32_e32 v114, v113
	v_mul_f32_e32 v109, v109, v113
	v_mul_f32_e32 v111, v111, v114
	v_mul_f32_e32 v112, v112, v114
	ds_write_b32 v105, v108 offset:1568
	ds_write_b32 v105, v109 offset:1824
	ds_write_b32 v105, v113 offset:2080
	ds_write_b32 v105, v111 offset:2336
	ds_write_b32 v105, v112 offset:2592
	ds_read_b32 v108, v105 offset:3136
	ds_read_b32 v109, v105 offset:3392
	ds_read_b32 v110, v105 offset:3648
	ds_read_b32 v111, v105 offset:3904
	ds_read_b32 v112, v105 offset:4160
	s_waitcnt lgkmcnt(0)
	v_mul_f32_e32 v108, v108, v113
	v_mul_f32_e32 v113, v113, v110
	v_rcp_f32_e32 v114, v113
	v_mul_f32_e32 v109, v109, v113
	v_mul_f32_e32 v111, v111, v114
	v_mul_f32_e32 v112, v112, v114
	ds_write_b32 v105, v108 offset:3136
	ds_write_b32 v105, v109 offset:3392
	ds_write_b32 v105, v113 offset:3648
	ds_write_b32 v105, v111 offset:3904
	ds_write_b32 v105, v112 offset:4160
	ds_read_b32 v108, v105 offset:4704
	ds_read_b32 v109, v105 offset:4960
	ds_read_b32 v110, v105 offset:5216
	ds_read_b32 v111, v105 offset:5472
	ds_read_b32 v112, v105 offset:5728
	s_waitcnt lgkmcnt(0)
	v_mul_f32_e32 v108, v108, v113
	v_mul_f32_e32 v113, v113, v110
	v_rcp_f32_e32 v114, v113
	v_mul_f32_e32 v109, v109, v113
	v_mul_f32_e32 v111, v111, v114
	v_mul_f32_e32 v112, v112, v114
	ds_write_b32 v105, v108 offset:4704
	ds_write_b32 v105, v109 offset:4960
	ds_write_b32 v105, v113 offset:5216
	ds_write_b32 v105, v111 offset:5472
	ds_write_b32 v105, v112 offset:5728
	ds_read_b32 v108, v105 offset:6272
	ds_read_b32 v109, v105 offset:6528
	ds_read_b32 v110, v105 offset:6784
	ds_read_b32 v111, v105 offset:7040
	ds_read_b32 v112, v105 offset:7296
	s_waitcnt lgkmcnt(0)
	v_mul_f32_e32 v108, v108, v113
	v_mul_f32_e32 v113, v113, v110
	v_rcp_f32_e32 v114, v113
	v_mul_f32_e32 v109, v109, v113
	v_mul_f32_e32 v111, v111, v114
	v_mul_f32_e32 v112, v112, v114
	ds_write_b32 v105, v108 offset:6272
	ds_write_b32 v105, v109 offset:6528
	ds_write_b32 v105, v113 offset:6784
	ds_write_b32 v105, v111 offset:7040
	ds_write_b32 v105, v112 offset:7296
	ds_read_b32 v108, v105 offset:7840
	ds_read_b32 v109, v105 offset:8096
	ds_read_b32 v110, v105 offset:8352
	ds_read_b32 v111, v105 offset:8608
	ds_read_b32 v112, v105 offset:8864
	s_waitcnt lgkmcnt(0)
	v_mul_f32_e32 v108, v108, v113
	v_mul_f32_e32 v113, v113, v110
	v_rcp_f32_e32 v114, v113
	v_mul_f32_e32 v109, v109, v113
	v_mul_f32_e32 v111, v111, v114
	v_mul_f32_e32 v112, v112, v114
	ds_write_b32 v105, v108 offset:7840
	ds_write_b32 v105, v109 offset:8096
	ds_write_b32 v105, v113 offset:8352
	ds_write_b32 v105, v111 offset:8608
	ds_write_b32 v105, v112 offset:8864
	ds_read_b32 v108, v105 offset:9408
	ds_read_b32 v109, v105 offset:9664
	ds_read_b32 v110, v105 offset:9920
	ds_read_b32 v111, v105 offset:10176
	ds_read_b32 v112, v105 offset:10432
	s_waitcnt lgkmcnt(0)
	v_mul_f32_e32 v108, v108, v113
	v_mul_f32_e32 v113, v113, v110
	v_rcp_f32_e32 v114, v113
	v_mul_f32_e32 v109, v109, v113
	v_mul_f32_e32 v111, v111, v114
	v_mul_f32_e32 v112, v112, v114
	ds_write_b32 v105, v108 offset:9408
	ds_write_b32 v105, v109 offset:9664
	ds_write_b32 v105, v113 offset:9920
	ds_write_b32 v105, v111 offset:10176
	ds_write_b32 v105, v112 offset:10432
	ds_read_b32 v108, v105 offset:10976
	ds_read_b32 v110, v105 offset:11488
	ds_read_b32 v111, v105 offset:11744
	ds_read_b32 v112, v105 offset:12000
	s_waitcnt lgkmcnt(0)
	v_mul_f32_e32 v108, v108, v113
	v_mul_f32_e32 v113, v113, v110
	v_rcp_f32_e32 v114, v113
	s_nop 0
	v_mul_f32_e32 v111, v111, v114
	v_mul_f32_e32 v112, v112, v114
	ds_write_b32 v105, v108 offset:10976
	ds_write_b32 v105, v113 offset:11488
	ds_write_b32 v105, v111 offset:11744
	ds_write_b32 v105, v112 offset:12000
	s_mov_b64 exec, s[98:99]
	s_add_i32 s16, s16, 32
	s_addk_i32 s17, 0x800
	s_cmpk_eq_i32 s16, 0x1fc0
	v_subrev_u32_e32 v84, 32, v84
	s_waitcnt lgkmcnt(0)
	s_barrier
	s_cbranch_scc1 .LBB0_213

; DI void store4(u16* dst, float a, float b, float c, float d) { *(uint2*)dst = make_uint2(pack2(a, b), pack2(c, d)); }
; template <int CPL>
; DI void scan_block2(CP p, int layer, int s, int d, int hd, int rowhalf, char* smem) {
;     ...
;     auto writeout = [&](int c) {
;       const float* yb = YB + (c & 1) * 2048;
; #pragma unroll
;       for (int u = 0; u < 2; ++u) {
;         const int sj = 8 * sw + 4 * u + (lane >> 4);
;         const int sidx = c * 32 + sj;
;         const bool mine = CPL == 16 ? true : ((q >> 3) == rowhalf);
;         if (sidx < L && mine) {
;           const int tok = d == 0 ? sidx : L - 1 - sidx;
;           const float4 yv = *(const float4*)(yb + sj * 64 + 4 * q);
;           store4((u16*)p.out + (size_t)(r0 + tok) * 1024 + d * 512 + hd * 64 + 4 * q, yv.x, yv.y, yv.z, yv.w);
;         }
;       }
;     ...
;     for (int c = 0; c < nch; ++c) {
;       if (c + 1 < nch) { stage(c + 1); if (c + 2 < nch) load_raw(c + 2); }
;       if (c >= 1) writeout(c - 1);
;       __syncthreads();
;     }
;     writeout(nch - 1);
.LBB0_223:
	s_or_b64 exec, exec, s[2:3]
	v_cmp_gt_i32_e64 s[40:41], 48, v54
	s_and_b64 s[10:11], s[44:45], s[40:41]
	s_mov_b64 s[98:99], exec
	s_mov_b64 exec, -1
	v_and_b32_e32 v105, 63, v179
	v_lshlrev_b32_e32 v105, 2, v105
	v_lshrrev_b32_e32 v106, 6, v179
	v_add_u32_e32 v106, -4, v106
	v_mul_u32_u24_e32 v106, 0x3100, v106
	v_mov_b32_e32 v107, 0x0
	v_add3_u32 v105, v105, v106, v107
	s_waitcnt lgkmcnt(0)
	ds_read_b32 v109, v105 offset:256
	ds_read_b32 v110, v105 offset:512
	ds_read_b32 v111, v105 offset:768
	ds_read_b32 v112, v105 offset:1024
	s_waitcnt lgkmcnt(0)
	v_mov_b32_e32 v113, v110
	v_rcp_f32_e32 v114, v113
	v_mul_f32_e32 v109, v109, v113
	v_mul_f32_e32 v111, v111, v114
	v_mul_f32_e32 v112, v112, v114
	ds_write_b32 v105, v109 offset:256
	ds_write_b32 v105, v111 offset:768
	ds_write_b32 v105, v112 offset:1024
	ds_read_b32 v108, v105 offset:1568
	ds_read_b32 v109, v105 offset:1824
	ds_read_b32 v110, v105 offset:2080
	ds_read_b32 v111, v105 offset:2336
	ds_read_b32 v112, v105 offset:2592
	s_waitcnt lgkmcnt(0)
	v_mul_f32_e32 v108, v108, v113
	v_mul_f32_e32 v113, v113, v110
	v_rcp_f32_e32 v114, v113
	v_mul_f32_e32 v109, v109, v113
	v_mul_f32_e32 v111, v111, v114
	v_mul_f32_e32 v112, v112, v114
	ds_write_b32 v105, v108 offset:1568
	ds_write_b32 v105, v109 offset:1824
	ds_write_b32 v105, v113 offset:2080
	ds_write_b32 v105, v111 offset:2336
	ds_write_b32 v105, v112 offset:2592
	ds_read_b32 v108, v105 offset:3136
	ds_read_b32 v109, v105 offset:3392
	ds_read_b32 v110, v105 offset:3648
	ds_read_b32 v111, v105 offset:3904
	ds_read_b32 v112, v105 offset:4160
	s_waitcnt lgkmcnt(0)
	v_mul_f32_e32 v108, v108, v113
	v_mul_f32_e32 v113, v113, v110
	v_rcp_f32_e32 v114, v113
	v_mul_f32_e32 v109, v109, v113
	v_mul_f32_e32 v111, v111, v114
	v_mul_f32_e32 v112, v112, v114
	ds_write_b32 v105, v108 offset:3136
	ds_write_b32 v105, v109 offset:3392
	ds_write_b32 v105, v113 offset:3648
	ds_write_b32 v105, v111 offset:3904
	ds_write_b32 v105, v112 offset:4160
	ds_read_b32 v108, v105 offset:4704
	ds_read_b32 v109, v105 offset:4960
	ds_read_b32 v110, v105 offset:5216
	ds_read_b32 v111, v105 offset:5472
	ds_read_b32 v112, v105 offset:5728
	s_waitcnt lgkmcnt(0)
	v_mul_f32_e32 v108, v108, v113
	v_mul_f32_e32 v113, v113, v110
	v_rcp_f32_e32 v114, v113
	v_mul_f32_e32 v109, v109, v113
	v_mul_f32_e32 v111, v111, v114
	v_mul_f32_e32 v112, v112, v114
	ds_write_b32 v105, v108 offset:4704
	ds_write_b32 v105, v109 offset:4960
	ds_write_b32 v105, v113 offset:5216
	ds_write_b32 v105, v111 offset:5472
	ds_write_b32 v105, v112 offset:5728
	ds_read_b32 v108, v105 offset:6272
	ds_read_b32 v109, v105 offset:6528
	ds_read_b32 v110, v105 offset:6784
	ds_read_b32 v111, v105 offset:7040
	ds_read_b32 v112, v105 offset:7296
	s_waitcnt lgkmcnt(0)
	v_mul_f32_e32 v108, v108, v113
	v_mul_f32_e32 v113, v113, v110
	v_rcp_f32_e32 v114, v113
	v_mul_f32_e32 v109, v109, v113
	v_mul_f32_e32 v111, v111, v114
	v_mul_f32_e32 v112, v112, v114
	ds_write_b32 v105, v108 offset:6272
	ds_write_b32 v105, v109 offset:6528
	ds_write_b32 v105, v113 offset:6784
	ds_write_b32 v105, v111 offset:7040
	ds_write_b32 v105, v112 offset:7296
	ds_read_b32 v108, v105 offset:7840
	ds_read_b32 v109, v105 offset:8096
	ds_read_b32 v110, v105 offset:8352
	ds_read_b32 v111, v105 offset:8608
	ds_read_b32 v112, v105 offset:8864
	s_waitcnt lgkmcnt(0)
	v_mul_f32_e32 v108, v108, v113
	v_mul_f32_e32 v113, v113, v110
	v_rcp_f32_e32 v114, v113
	v_mul_f32_e32 v109, v109, v113
	v_mul_f32_e32 v111, v111, v114
	v_mul_f32_e32 v112, v112, v114
	ds_write_b32 v105, v108 offset:7840
	ds_write_b32 v105, v109 offset:8096
	ds_write_b32 v105, v113 offset:8352
	ds_write_b32 v105, v111 offset:8608
	ds_write_b32 v105, v112 offset:8864
	ds_read_b32 v108, v105 offset:9408
	ds_read_b32 v109, v105 offset:9664
	ds_read_b32 v110, v105 offset:9920
	ds_read_b32 v111, v105 offset:10176
	ds_read_b32 v112, v105 offset:10432
	s_waitcnt lgkmcnt(0)
	v_mul_f32_e32 v108, v108, v113
	v_mul_f32_e32 v113, v113, v110
	v_rcp_f32_e32 v114, v113
	v_mul_f32_e32 v109, v109, v113
	v_mul_f32_e32 v111, v111, v114
	v_mul_f32_e32 v112, v112, v114
	ds_write_b32 v105, v108 offset:9408
	ds_write_b32 v105, v109 offset:9664
	ds_write_b32 v105, v113 offset:9920
	ds_write_b32 v105, v111 offset:10176
	ds_write_b32 v105, v112 offset:10432
	ds_read_b32 v108, v105 offset:10976
	ds_read_b32 v110, v105 offset:11488
	ds_read_b32 v111, v105 offset:11744
	ds_read_b32 v112, v105 offset:12000
	s_waitcnt lgkmcnt(0)
	v_mul_f32_e32 v108, v108, v113
	v_mul_f32_e32 v113, v113, v110
	v_rcp_f32_e32 v114, v113
	s_nop 0
	v_mul_f32_e32 v111, v111, v114
	v_mul_f32_e32 v112, v112, v114
	ds_write_b32 v105, v108 offset:10976
	ds_write_b32 v105, v113 offset:11488
	ds_write_b32 v105, v111 offset:11744
	ds_write_b32 v105, v112 offset:12000
	s_mov_b64 exec, s[98:99]
	s_waitcnt lgkmcnt(0)
	s_barrier
	s_and_saveexec_b64 s[2:3], s[10:11]
	s_cbranch_execz .LBB0_225
	v_add_u32_e32 v5, 0x1fe0, v54
	v_sub_u32_e32 v6, 47, v54
	v_readlane_b32 s10, v252, 31
	v_cndmask_b32_e32 v5, v6, v5, vcc
	v_add_u32_e32 v10, s15, v5
	v_add3_u32 v6, s10, v4, v2
	ds_read_b128 v[6:9], v6
	v_ashrrev_i32_e32 v11, 31, v10
	v_lshlrev_b64 v[10:11], 11, v[10:11]
	v_lshl_add_u64 v[10:11], v[38:39], 0, v[10:11]
	s_waitcnt lgkmcnt(0)
	v_cvt_pk_bf16_f32 v6, v6, v7
	v_cvt_pk_bf16_f32 v7, v8, v9
	global_store_dwordx2 v[10:11], v[6:7], off
